# K-loop counted waits relaxed to exactly the staged loads each super-phase reads (vmcnt 10/14/10/14 instead of 8/8/8/8, loop bodies and peeled first iterations of all 9 GEMM loops): one more staging gr
# speedup vs baseline: 1.0123x; 1.0065x over previous
.Lnostb0:
	s_add_u32 s48, s46, 0xfffc0080
	s_addc_u32 s49, s47, -1
	s_add_i32 s83, 0, 0x10000
	s_cmp_eq_u32 s82, 12
	s_cselect_b32 s49, s39, s49
	s_cselect_b32 s48, s78, s48
	v_add_u32_e32 v140, s83, v146
	s_cselect_b32 s85, s37, s81
	s_cselect_b32 s84, s79, s80
	s_add_i32 s86, 0, 0x14000
	ds_read_b128 v[136:139], v140
	ds_read_b128 v[152:155], v140 offset:1024
	ds_read_b128 v[156:159], v140 offset:2048
	ds_read_b128 v[160:163], v140 offset:3072
	v_add_u32_e32 v140, s86, v146
	ds_read_b128 v[164:167], v140
	ds_read_b128 v[168:171], v140 offset:1024
	ds_read_b128 v[172:175], v140 offset:2048
	ds_read_b128 v[176:179], v140 offset:3072
	v_lshl_add_u64 v[140:141], s[46:47], 0, v[132:133]
	s_add_i32 m0, s45, 0xc000
	ds_read_b128 v[180:183], v150
	ds_read_b128 v[184:187], v150 offset:1024
	ds_read_b128 v[188:191], v150 offset:2048
	ds_read_b128 v[192:195], v150 offset:3072
	ds_read_b128 v[196:199], v150 offset:4096
	ds_read_b128 v[200:203], v150 offset:5120
	ds_read_b128 v[204:207], v150 offset:6144
	ds_read_b128 v[208:211], v150 offset:7168
	global_load_lds_dwordx4 v[140:141], off
	v_lshl_add_u64 v[140:141], v[140:141], 0, s[12:13]
	s_add_i32 m0, s45, 0xe000
	s_nop 0
	global_load_lds_dwordx4 v[140:141], off
	s_waitcnt vmcnt(10)
	s_waitcnt lgkmcnt(0)
	s_barrier
	s_setprio 1
	s_waitcnt lgkmcnt(0)
	v_mfma_f32_16x16x32_bf16 v[124:127], v[136:139], v[180:183], 0
	v_mfma_f32_16x16x32_bf16 v[120:123], v[156:159], v[180:183], 0
	v_mfma_f32_16x16x32_bf16 v[112:115], v[136:139], v[188:191], 0
	v_mfma_f32_16x16x32_bf16 v[104:107], v[156:159], v[188:191], 0
	v_mfma_f32_16x16x32_bf16 v[96:99], v[136:139], v[196:199], 0
	v_mfma_f32_16x16x32_bf16 v[88:91], v[156:159], v[196:199], 0
	v_mfma_f32_16x16x32_bf16 v[80:83], v[136:139], v[204:207], 0
	v_mfma_f32_16x16x32_bf16 v[72:75], v[156:159], v[204:207], 0
	v_mfma_f32_16x16x32_bf16 v[124:127], v[152:155], v[184:187], v[124:127]
	v_mfma_f32_16x16x32_bf16 v[120:123], v[160:163], v[184:187], v[120:123]
	v_mfma_f32_16x16x32_bf16 v[112:115], v[152:155], v[192:195], v[112:115]
	v_mfma_f32_16x16x32_bf16 v[104:107], v[160:163], v[192:195], v[104:107]
	v_mfma_f32_16x16x32_bf16 v[96:99], v[152:155], v[200:203], v[96:99]
	v_mfma_f32_16x16x32_bf16 v[88:91], v[160:163], v[200:203], v[88:91]
	v_mfma_f32_16x16x32_bf16 v[80:83], v[152:155], v[208:211], v[80:83]
	v_mfma_f32_16x16x32_bf16 v[72:75], v[160:163], v[208:211], v[72:75]
	s_setprio 0
	s_setprio 1
	v_mfma_f32_16x16x32_bf16 v[116:119], v[164:167], v[180:183], 0
	v_mfma_f32_16x16x32_bf16 v[108:111], v[172:175], v[180:183], 0
	v_mfma_f32_16x16x32_bf16 v[100:103], v[164:167], v[188:191], 0
	v_mfma_f32_16x16x32_bf16 v[92:95], v[172:175], v[188:191], 0
	v_mfma_f32_16x16x32_bf16 v[84:87], v[164:167], v[196:199], 0
	v_mfma_f32_16x16x32_bf16 v[76:79], v[172:175], v[196:199], 0
	v_mfma_f32_16x16x32_bf16 v[68:71], v[164:167], v[204:207], 0
	v_mfma_f32_16x16x32_bf16 v[64:67], v[172:175], v[204:207], 0
	v_mfma_f32_16x16x32_bf16 v[116:119], v[168:171], v[184:187], v[116:119]
	v_mfma_f32_16x16x32_bf16 v[108:111], v[176:179], v[184:187], v[108:111]
	v_mfma_f32_16x16x32_bf16 v[100:103], v[168:171], v[192:195], v[100:103]
	v_mfma_f32_16x16x32_bf16 v[92:95], v[176:179], v[192:195], v[92:95]
	v_mfma_f32_16x16x32_bf16 v[84:87], v[168:171], v[200:203], v[84:87]
	v_mfma_f32_16x16x32_bf16 v[76:79], v[176:179], v[200:203], v[76:79]
	v_mfma_f32_16x16x32_bf16 v[68:71], v[168:171], v[208:211], v[68:71]
	v_mfma_f32_16x16x32_bf16 v[64:67], v[176:179], v[208:211], v[64:67]
	s_setprio 0
	s_barrier
	s_add_i32 s83, s83, s69
	v_lshl_add_u64 v[140:141], s[84:85], 0, v[128:129]
	s_mov_b32 m0, s83
	ds_read_b128 v[180:183], v150 offset:16384
	ds_read_b128 v[184:187], v150 offset:17408
	ds_read_b128 v[188:191], v150 offset:18432
	ds_read_b128 v[192:195], v150 offset:19456
	ds_read_b128 v[196:199], v150 offset:20480
	ds_read_b128 v[200:203], v150 offset:21504
	ds_read_b128 v[204:207], v150 offset:22528
	ds_read_b128 v[208:211], v150 offset:23552
	global_load_lds_dwordx4 v[140:141], off
	v_lshl_add_u64 v[212:213], v[140:141], 0, s[12:13]
	s_add_i32 m0, s83, 0x2000
	s_add_i32 s83, s86, s69
	global_load_lds_dwordx4 v[212:213], off
	v_lshl_add_u64 v[212:213], v[140:141], 0, s[14:15]
	s_mov_b32 m0, s83
	s_nop 0
	global_load_lds_dwordx4 v[212:213], off
	v_lshl_add_u64 v[212:213], v[140:141], 0, s[16:17]
	s_add_i32 m0, s83, 0x2000
	s_nop 0
	global_load_lds_dwordx4 v[212:213], off
	v_lshl_add_u64 v[212:213], s[48:49], 0, v[130:131]
	s_mov_b32 m0, s45
	v_lshl_add_u64 v[214:215], v[212:213], 0, s[12:13]
	global_load_lds_dwordx4 v[212:213], off
	s_mov_b32 m0, s71
	s_nop 0
	global_load_lds_dwordx4 v[214:215], off
	s_waitcnt vmcnt(14)
	s_waitcnt lgkmcnt(0)
	s_barrier
	s_setprio 1
	s_waitcnt lgkmcnt(0)
	v_mfma_f32_16x16x32_bf16 v[60:63], v[136:139], v[180:183], 0
	v_mfma_f32_16x16x32_bf16 v[56:59], v[156:159], v[180:183], 0
	v_mfma_f32_16x16x32_bf16 v[48:51], v[136:139], v[188:191], 0
	v_mfma_f32_16x16x32_bf16 v[40:43], v[156:159], v[188:191], 0
	v_mfma_f32_16x16x32_bf16 v[32:35], v[136:139], v[196:199], 0
	v_mfma_f32_16x16x32_bf16 v[24:27], v[156:159], v[196:199], 0
	v_mfma_f32_16x16x32_bf16 v[16:19], v[136:139], v[204:207], 0
	v_mfma_f32_16x16x32_bf16 v[8:11], v[156:159], v[204:207], 0
	v_mfma_f32_16x16x32_bf16 v[60:63], v[152:155], v[184:187], v[60:63]
	v_mfma_f32_16x16x32_bf16 v[56:59], v[160:163], v[184:187], v[56:59]
	v_mfma_f32_16x16x32_bf16 v[48:51], v[152:155], v[192:195], v[48:51]
	v_mfma_f32_16x16x32_bf16 v[40:43], v[160:163], v[192:195], v[40:43]
	v_mfma_f32_16x16x32_bf16 v[32:35], v[152:155], v[200:203], v[32:35]
	v_mfma_f32_16x16x32_bf16 v[24:27], v[160:163], v[200:203], v[24:27]
	v_mfma_f32_16x16x32_bf16 v[16:19], v[152:155], v[208:211], v[16:19]
	v_mfma_f32_16x16x32_bf16 v[8:11], v[160:163], v[208:211], v[8:11]
	s_setprio 0
	s_setprio 1
	v_mfma_f32_16x16x32_bf16 v[52:55], v[164:167], v[180:183], 0
	v_mfma_f32_16x16x32_bf16 v[44:47], v[172:175], v[180:183], 0
	v_mfma_f32_16x16x32_bf16 v[36:39], v[164:167], v[188:191], 0
	v_mfma_f32_16x16x32_bf16 v[28:31], v[172:175], v[188:191], 0
	v_mfma_f32_16x16x32_bf16 v[20:23], v[164:167], v[196:199], 0
	v_mfma_f32_16x16x32_bf16 v[12:15], v[172:175], v[196:199], 0
	v_mfma_f32_16x16x32_bf16 v[4:7], v[164:167], v[204:207], 0
	v_mfma_f32_16x16x32_bf16 v[0:3], v[172:175], v[204:207], 0
	v_mfma_f32_16x16x32_bf16 v[52:55], v[168:171], v[184:187], v[52:55]
	v_mfma_f32_16x16x32_bf16 v[44:47], v[176:179], v[184:187], v[44:47]
	v_mfma_f32_16x16x32_bf16 v[36:39], v[168:171], v[192:195], v[36:39]
	v_mfma_f32_16x16x32_bf16 v[28:31], v[176:179], v[192:195], v[28:31]
	v_mfma_f32_16x16x32_bf16 v[20:23], v[168:171], v[200:203], v[20:23]
	v_mfma_f32_16x16x32_bf16 v[12:15], v[176:179], v[200:203], v[12:15]
	v_mfma_f32_16x16x32_bf16 v[4:7], v[168:171], v[208:211], v[4:7]
	v_mfma_f32_16x16x32_bf16 v[0:3], v[176:179], v[208:211], v[0:3]
	s_setprio 0
	s_barrier
	s_add_i32 s48, 0, 0x18000
	v_add_u32_e32 v151, s48, v146
	s_add_i32 s49, 0, 0x1c000
	ds_read_b128 v[136:139], v151
	ds_read_b128 v[152:155], v151 offset:1024
	ds_read_b128 v[156:159], v151 offset:2048
	ds_read_b128 v[160:163], v151 offset:3072
	v_add_u32_e32 v151, s49, v146
	ds_read_b128 v[164:167], v151
	ds_read_b128 v[168:171], v151 offset:1024
	ds_read_b128 v[172:175], v151 offset:2048
	ds_read_b128 v[176:179], v151 offset:3072
	s_mov_b32 m0, s72
	v_lshl_add_u64 v[214:215], v[212:213], 0, s[14:15]
	ds_read_b128 v[180:183], v150 offset:32768
	ds_read_b128 v[184:187], v150 offset:33792
	ds_read_b128 v[188:191], v150 offset:34816
	ds_read_b128 v[192:195], v150 offset:35840
	ds_read_b128 v[196:199], v150 offset:36864
	ds_read_b128 v[200:203], v150 offset:37888
	ds_read_b128 v[204:207], v150 offset:38912
	ds_read_b128 v[208:211], v150 offset:39936
	global_load_lds_dwordx4 v[214:215], off
	v_lshl_add_u64 v[214:215], v[212:213], 0, s[16:17]
	s_mov_b32 m0, s73
	s_nop 0
	global_load_lds_dwordx4 v[214:215], off
	s_waitcnt vmcnt(10)
	s_waitcnt lgkmcnt(0)
	s_barrier
	s_setprio 1
	s_waitcnt lgkmcnt(0)
	v_mfma_f32_16x16x32_bf16 v[124:127], v[136:139], v[180:183], v[124:127]
	v_mfma_f32_16x16x32_bf16 v[120:123], v[156:159], v[180:183], v[120:123]
	v_mfma_f32_16x16x32_bf16 v[112:115], v[136:139], v[188:191], v[112:115]
	v_mfma_f32_16x16x32_bf16 v[104:107], v[156:159], v[188:191], v[104:107]
	v_mfma_f32_16x16x32_bf16 v[96:99], v[136:139], v[196:199], v[96:99]
	v_mfma_f32_16x16x32_bf16 v[88:91], v[156:159], v[196:199], v[88:91]
	v_mfma_f32_16x16x32_bf16 v[80:83], v[136:139], v[204:207], v[80:83]
	v_mfma_f32_16x16x32_bf16 v[72:75], v[156:159], v[204:207], v[72:75]
	v_mfma_f32_16x16x32_bf16 v[124:127], v[152:155], v[184:187], v[124:127]
	v_mfma_f32_16x16x32_bf16 v[120:123], v[160:163], v[184:187], v[120:123]
	v_mfma_f32_16x16x32_bf16 v[112:115], v[152:155], v[192:195], v[112:115]
	v_mfma_f32_16x16x32_bf16 v[104:107], v[160:163], v[192:195], v[104:107]
	v_mfma_f32_16x16x32_bf16 v[96:99], v[152:155], v[200:203], v[96:99]
	v_mfma_f32_16x16x32_bf16 v[88:91], v[160:163], v[200:203], v[88:91]
	v_mfma_f32_16x16x32_bf16 v[80:83], v[152:155], v[208:211], v[80:83]
	v_mfma_f32_16x16x32_bf16 v[72:75], v[160:163], v[208:211], v[72:75]
	s_setprio 0
	s_setprio 1
	v_mfma_f32_16x16x32_bf16 v[116:119], v[164:167], v[180:183], v[116:119]
	v_mfma_f32_16x16x32_bf16 v[108:111], v[172:175], v[180:183], v[108:111]
	v_mfma_f32_16x16x32_bf16 v[100:103], v[164:167], v[188:191], v[100:103]
	v_mfma_f32_16x16x32_bf16 v[92:95], v[172:175], v[188:191], v[92:95]
	v_mfma_f32_16x16x32_bf16 v[84:87], v[164:167], v[196:199], v[84:87]
	v_mfma_f32_16x16x32_bf16 v[76:79], v[172:175], v[196:199], v[76:79]
	v_mfma_f32_16x16x32_bf16 v[68:71], v[164:167], v[204:207], v[68:71]
	v_mfma_f32_16x16x32_bf16 v[64:67], v[172:175], v[204:207], v[64:67]
	v_mfma_f32_16x16x32_bf16 v[116:119], v[168:171], v[184:187], v[116:119]
	v_mfma_f32_16x16x32_bf16 v[108:111], v[176:179], v[184:187], v[108:111]
	v_mfma_f32_16x16x32_bf16 v[100:103], v[168:171], v[192:195], v[100:103]
	v_mfma_f32_16x16x32_bf16 v[92:95], v[176:179], v[192:195], v[92:95]
	v_mfma_f32_16x16x32_bf16 v[84:87], v[168:171], v[200:203], v[84:87]
	v_mfma_f32_16x16x32_bf16 v[76:79], v[176:179], v[200:203], v[76:79]
	v_mfma_f32_16x16x32_bf16 v[68:71], v[168:171], v[208:211], v[68:71]
	v_mfma_f32_16x16x32_bf16 v[64:67], v[176:179], v[208:211], v[64:67]
	s_setprio 0
	s_barrier
	s_add_i32 s48, s48, s69
	v_lshl_add_u64 v[214:215], v[140:141], 0, s[18:19]
	s_mov_b32 m0, s48
	ds_read_b128 v[180:183], v150 offset:49152
	ds_read_b128 v[184:187], v150 offset:50176
	ds_read_b128 v[188:191], v150 offset:51200
	ds_read_b128 v[192:195], v150 offset:52224
	ds_read_b128 v[196:199], v150 offset:53248
	ds_read_b128 v[200:203], v150 offset:54272
	ds_read_b128 v[204:207], v150 offset:55296
	ds_read_b128 v[208:211], v150 offset:56320
	global_load_lds_dwordx4 v[214:215], off
	v_lshl_add_u64 v[214:215], v[140:141], 0, s[20:21]
	s_add_i32 m0, s48, 0x2000
	s_add_i32 s48, s49, s69
	global_load_lds_dwordx4 v[214:215], off
	v_lshl_add_u64 v[214:215], v[140:141], 0, s[22:23]
	s_mov_b32 m0, s48
	v_lshl_add_u64 v[140:141], v[140:141], 0, s[24:25]
	global_load_lds_dwordx4 v[214:215], off
	s_add_i32 m0, s48, 0x2000
	s_nop 0
	global_load_lds_dwordx4 v[140:141], off
	v_lshl_add_u64 v[140:141], v[212:213], 0, s[18:19]
	s_mov_b32 m0, s10
	s_nop 0
	global_load_lds_dwordx4 v[140:141], off
	v_lshl_add_u64 v[140:141], v[212:213], 0, s[20:21]
	s_mov_b32 m0, s74
	s_nop 0
	global_load_lds_dwordx4 v[140:141], off
	s_waitcnt vmcnt(14)
	s_waitcnt lgkmcnt(0)
	s_barrier
	s_setprio 1
	s_waitcnt lgkmcnt(0)
	v_mfma_f32_16x16x32_bf16 v[60:63], v[136:139], v[180:183], v[60:63]
	v_mfma_f32_16x16x32_bf16 v[56:59], v[156:159], v[180:183], v[56:59]
	v_mfma_f32_16x16x32_bf16 v[48:51], v[136:139], v[188:191], v[48:51]
	v_mfma_f32_16x16x32_bf16 v[40:43], v[156:159], v[188:191], v[40:43]
	v_mfma_f32_16x16x32_bf16 v[32:35], v[136:139], v[196:199], v[32:35]
	v_mfma_f32_16x16x32_bf16 v[24:27], v[156:159], v[196:199], v[24:27]
	v_mfma_f32_16x16x32_bf16 v[16:19], v[136:139], v[204:207], v[16:19]
	v_mfma_f32_16x16x32_bf16 v[8:11], v[156:159], v[204:207], v[8:11]
	v_mfma_f32_16x16x32_bf16 v[60:63], v[152:155], v[184:187], v[60:63]
	v_mfma_f32_16x16x32_bf16 v[56:59], v[160:163], v[184:187], v[56:59]
	v_mfma_f32_16x16x32_bf16 v[48:51], v[152:155], v[192:195], v[48:51]
	v_mfma_f32_16x16x32_bf16 v[40:43], v[160:163], v[192:195], v[40:43]
	v_mfma_f32_16x16x32_bf16 v[32:35], v[152:155], v[200:203], v[32:35]
	v_mfma_f32_16x16x32_bf16 v[24:27], v[160:163], v[200:203], v[24:27]
	v_mfma_f32_16x16x32_bf16 v[16:19], v[152:155], v[208:211], v[16:19]
	v_mfma_f32_16x16x32_bf16 v[8:11], v[160:163], v[208:211], v[8:11]
	s_setprio 0
	s_setprio 1
	v_mfma_f32_16x16x32_bf16 v[52:55], v[164:167], v[180:183], v[52:55]
	v_mfma_f32_16x16x32_bf16 v[44:47], v[172:175], v[180:183], v[44:47]
	v_mfma_f32_16x16x32_bf16 v[36:39], v[164:167], v[188:191], v[36:39]
	v_mfma_f32_16x16x32_bf16 v[28:31], v[172:175], v[188:191], v[28:31]
	v_mfma_f32_16x16x32_bf16 v[20:23], v[164:167], v[196:199], v[20:23]
	v_mfma_f32_16x16x32_bf16 v[12:15], v[172:175], v[196:199], v[12:15]
	v_mfma_f32_16x16x32_bf16 v[4:7], v[164:167], v[204:207], v[4:7]
	v_mfma_f32_16x16x32_bf16 v[0:3], v[172:175], v[204:207], v[0:3]
	v_mfma_f32_16x16x32_bf16 v[52:55], v[168:171], v[184:187], v[52:55]
	v_mfma_f32_16x16x32_bf16 v[44:47], v[176:179], v[184:187], v[44:47]
	v_mfma_f32_16x16x32_bf16 v[36:39], v[168:171], v[192:195], v[36:39]
	v_mfma_f32_16x16x32_bf16 v[28:31], v[176:179], v[192:195], v[28:31]
	v_mfma_f32_16x16x32_bf16 v[20:23], v[168:171], v[200:203], v[20:23]
	v_mfma_f32_16x16x32_bf16 v[12:15], v[176:179], v[200:203], v[12:15]
	v_mfma_f32_16x16x32_bf16 v[4:7], v[168:171], v[208:211], v[4:7]
	v_mfma_f32_16x16x32_bf16 v[0:3], v[176:179], v[208:211], v[0:3]
	s_setprio 0
	s_barrier
	s_add_i32 s82, s82, 2
	s_add_u32 s46, s46, 0x100
	s_addc_u32 s47, s47, 0
	s_add_u32 s80, s80, 0x100
	s_addc_u32 s81, s81, 0
	s_cmp_gt_u32 s82, 13
.LBB0_192:
	s_add_u32 s48, s46, 0xfffc0080
	s_addc_u32 s49, s47, -1
	s_add_i32 s83, 0, 0x10000
	s_cmp_eq_u32 s82, 12
	s_cselect_b32 s49, s39, s49
	s_cselect_b32 s48, s78, s48
	v_add_u32_e32 v140, s83, v146
	s_cselect_b32 s85, s37, s81
	s_cselect_b32 s84, s79, s80
	s_add_i32 s86, 0, 0x14000
	ds_read_b128 v[136:139], v140
	ds_read_b128 v[152:155], v140 offset:1024
	ds_read_b128 v[156:159], v140 offset:2048
	ds_read_b128 v[160:163], v140 offset:3072
	v_add_u32_e32 v140, s86, v146
	ds_read_b128 v[164:167], v140
	ds_read_b128 v[168:171], v140 offset:1024
	ds_read_b128 v[172:175], v140 offset:2048
	ds_read_b128 v[176:179], v140 offset:3072
	v_lshl_add_u64 v[140:141], s[46:47], 0, v[132:133]
	s_add_i32 m0, s45, 0xc000
	ds_read_b128 v[180:183], v150
	ds_read_b128 v[184:187], v150 offset:1024
	ds_read_b128 v[188:191], v150 offset:2048
	ds_read_b128 v[192:195], v150 offset:3072
	ds_read_b128 v[196:199], v150 offset:4096
	ds_read_b128 v[200:203], v150 offset:5120
	ds_read_b128 v[204:207], v150 offset:6144
	ds_read_b128 v[208:211], v150 offset:7168
	global_load_lds_dwordx4 v[140:141], off
	v_lshl_add_u64 v[140:141], v[140:141], 0, s[12:13]
	s_add_i32 m0, s45, 0xe000
	s_nop 0
	global_load_lds_dwordx4 v[140:141], off
	s_waitcnt vmcnt(10)
	s_waitcnt lgkmcnt(0)
	s_barrier
	s_setprio 1
	s_waitcnt lgkmcnt(0)
	v_mfma_f32_16x16x32_bf16 v[124:127], v[136:139], v[180:183], v[124:127]
	v_mfma_f32_16x16x32_bf16 v[120:123], v[156:159], v[180:183], v[120:123]
	v_mfma_f32_16x16x32_bf16 v[112:115], v[136:139], v[188:191], v[112:115]
	v_mfma_f32_16x16x32_bf16 v[104:107], v[156:159], v[188:191], v[104:107]
	v_mfma_f32_16x16x32_bf16 v[96:99], v[136:139], v[196:199], v[96:99]
	v_mfma_f32_16x16x32_bf16 v[88:91], v[156:159], v[196:199], v[88:91]
	v_mfma_f32_16x16x32_bf16 v[80:83], v[136:139], v[204:207], v[80:83]
	v_mfma_f32_16x16x32_bf16 v[72:75], v[156:159], v[204:207], v[72:75]
	v_mfma_f32_16x16x32_bf16 v[124:127], v[152:155], v[184:187], v[124:127]
	v_mfma_f32_16x16x32_bf16 v[120:123], v[160:163], v[184:187], v[120:123]
	v_mfma_f32_16x16x32_bf16 v[112:115], v[152:155], v[192:195], v[112:115]
	v_mfma_f32_16x16x32_bf16 v[104:107], v[160:163], v[192:195], v[104:107]
	v_mfma_f32_16x16x32_bf16 v[96:99], v[152:155], v[200:203], v[96:99]
	v_mfma_f32_16x16x32_bf16 v[88:91], v[160:163], v[200:203], v[88:91]
	v_mfma_f32_16x16x32_bf16 v[80:83], v[152:155], v[208:211], v[80:83]
	v_mfma_f32_16x16x32_bf16 v[72:75], v[160:163], v[208:211], v[72:75]
	s_setprio 0
	s_setprio 1
	v_mfma_f32_16x16x32_bf16 v[116:119], v[164:167], v[180:183], v[116:119]
	v_mfma_f32_16x16x32_bf16 v[108:111], v[172:175], v[180:183], v[108:111]
	v_mfma_f32_16x16x32_bf16 v[100:103], v[164:167], v[188:191], v[100:103]
	v_mfma_f32_16x16x32_bf16 v[92:95], v[172:175], v[188:191], v[92:95]
	v_mfma_f32_16x16x32_bf16 v[84:87], v[164:167], v[196:199], v[84:87]
	v_mfma_f32_16x16x32_bf16 v[76:79], v[172:175], v[196:199], v[76:79]
	v_mfma_f32_16x16x32_bf16 v[68:71], v[164:167], v[204:207], v[68:71]
	v_mfma_f32_16x16x32_bf16 v[64:67], v[172:175], v[204:207], v[64:67]
	v_mfma_f32_16x16x32_bf16 v[116:119], v[168:171], v[184:187], v[116:119]
	v_mfma_f32_16x16x32_bf16 v[108:111], v[176:179], v[184:187], v[108:111]
	v_mfma_f32_16x16x32_bf16 v[100:103], v[168:171], v[192:195], v[100:103]
	v_mfma_f32_16x16x32_bf16 v[92:95], v[176:179], v[192:195], v[92:95]
	v_mfma_f32_16x16x32_bf16 v[84:87], v[168:171], v[200:203], v[84:87]
	v_mfma_f32_16x16x32_bf16 v[76:79], v[176:179], v[200:203], v[76:79]
	v_mfma_f32_16x16x32_bf16 v[68:71], v[168:171], v[208:211], v[68:71]
	v_mfma_f32_16x16x32_bf16 v[64:67], v[176:179], v[208:211], v[64:67]
	s_setprio 0
	s_barrier
	s_add_i32 s83, s83, s69
	v_lshl_add_u64 v[140:141], s[84:85], 0, v[128:129]
	s_mov_b32 m0, s83
	ds_read_b128 v[180:183], v150 offset:16384
	ds_read_b128 v[184:187], v150 offset:17408
	ds_read_b128 v[188:191], v150 offset:18432
	ds_read_b128 v[192:195], v150 offset:19456
	ds_read_b128 v[196:199], v150 offset:20480
	ds_read_b128 v[200:203], v150 offset:21504
	ds_read_b128 v[204:207], v150 offset:22528
	ds_read_b128 v[208:211], v150 offset:23552
	global_load_lds_dwordx4 v[140:141], off
	v_lshl_add_u64 v[212:213], v[140:141], 0, s[12:13]
	s_add_i32 m0, s83, 0x2000
	s_add_i32 s83, s86, s69
	global_load_lds_dwordx4 v[212:213], off
	v_lshl_add_u64 v[212:213], v[140:141], 0, s[14:15]
	s_mov_b32 m0, s83
	s_nop 0
	global_load_lds_dwordx4 v[212:213], off
	v_lshl_add_u64 v[212:213], v[140:141], 0, s[16:17]
	s_add_i32 m0, s83, 0x2000
	s_nop 0
	global_load_lds_dwordx4 v[212:213], off
	v_lshl_add_u64 v[212:213], s[48:49], 0, v[130:131]
	s_mov_b32 m0, s45
	v_lshl_add_u64 v[214:215], v[212:213], 0, s[12:13]
	global_load_lds_dwordx4 v[212:213], off
	s_mov_b32 m0, s71
	s_nop 0
	global_load_lds_dwordx4 v[214:215], off
	s_waitcnt vmcnt(14)
	s_waitcnt lgkmcnt(0)
	s_barrier
	s_setprio 1
	s_waitcnt lgkmcnt(0)
	v_mfma_f32_16x16x32_bf16 v[60:63], v[136:139], v[180:183], v[60:63]
	v_mfma_f32_16x16x32_bf16 v[56:59], v[156:159], v[180:183], v[56:59]
	v_mfma_f32_16x16x32_bf16 v[48:51], v[136:139], v[188:191], v[48:51]
	v_mfma_f32_16x16x32_bf16 v[40:43], v[156:159], v[188:191], v[40:43]
	v_mfma_f32_16x16x32_bf16 v[32:35], v[136:139], v[196:199], v[32:35]
	v_mfma_f32_16x16x32_bf16 v[24:27], v[156:159], v[196:199], v[24:27]
	v_mfma_f32_16x16x32_bf16 v[16:19], v[136:139], v[204:207], v[16:19]
	v_mfma_f32_16x16x32_bf16 v[8:11], v[156:159], v[204:207], v[8:11]
	v_mfma_f32_16x16x32_bf16 v[60:63], v[152:155], v[184:187], v[60:63]
	v_mfma_f32_16x16x32_bf16 v[56:59], v[160:163], v[184:187], v[56:59]
	v_mfma_f32_16x16x32_bf16 v[48:51], v[152:155], v[192:195], v[48:51]
	v_mfma_f32_16x16x32_bf16 v[40:43], v[160:163], v[192:195], v[40:43]
	v_mfma_f32_16x16x32_bf16 v[32:35], v[152:155], v[200:203], v[32:35]
	v_mfma_f32_16x16x32_bf16 v[24:27], v[160:163], v[200:203], v[24:27]
	v_mfma_f32_16x16x32_bf16 v[16:19], v[152:155], v[208:211], v[16:19]
	v_mfma_f32_16x16x32_bf16 v[8:11], v[160:163], v[208:211], v[8:11]
	s_setprio 0
	s_setprio 1
	v_mfma_f32_16x16x32_bf16 v[52:55], v[164:167], v[180:183], v[52:55]
	v_mfma_f32_16x16x32_bf16 v[44:47], v[172:175], v[180:183], v[44:47]
	v_mfma_f32_16x16x32_bf16 v[36:39], v[164:167], v[188:191], v[36:39]
	v_mfma_f32_16x16x32_bf16 v[28:31], v[172:175], v[188:191], v[28:31]
	v_mfma_f32_16x16x32_bf16 v[20:23], v[164:167], v[196:199], v[20:23]
	v_mfma_f32_16x16x32_bf16 v[12:15], v[172:175], v[196:199], v[12:15]
	v_mfma_f32_16x16x32_bf16 v[4:7], v[164:167], v[204:207], v[4:7]
	v_mfma_f32_16x16x32_bf16 v[0:3], v[172:175], v[204:207], v[0:3]
	v_mfma_f32_16x16x32_bf16 v[52:55], v[168:171], v[184:187], v[52:55]
	v_mfma_f32_16x16x32_bf16 v[44:47], v[176:179], v[184:187], v[44:47]
	v_mfma_f32_16x16x32_bf16 v[36:39], v[168:171], v[192:195], v[36:39]
	v_mfma_f32_16x16x32_bf16 v[28:31], v[176:179], v[192:195], v[28:31]
	v_mfma_f32_16x16x32_bf16 v[20:23], v[168:171], v[200:203], v[20:23]
	v_mfma_f32_16x16x32_bf16 v[12:15], v[176:179], v[200:203], v[12:15]
	v_mfma_f32_16x16x32_bf16 v[4:7], v[168:171], v[208:211], v[4:7]
	v_mfma_f32_16x16x32_bf16 v[0:3], v[176:179], v[208:211], v[0:3]
	s_setprio 0
	s_barrier
	s_add_i32 s48, 0, 0x18000
	v_add_u32_e32 v151, s48, v146
	s_add_i32 s49, 0, 0x1c000
	ds_read_b128 v[136:139], v151
	ds_read_b128 v[152:155], v151 offset:1024
	ds_read_b128 v[156:159], v151 offset:2048
	ds_read_b128 v[160:163], v151 offset:3072
	v_add_u32_e32 v151, s49, v146
	ds_read_b128 v[164:167], v151
	ds_read_b128 v[168:171], v151 offset:1024
	ds_read_b128 v[172:175], v151 offset:2048
	ds_read_b128 v[176:179], v151 offset:3072
	s_mov_b32 m0, s72
	v_lshl_add_u64 v[214:215], v[212:213], 0, s[14:15]
	ds_read_b128 v[180:183], v150 offset:32768
	ds_read_b128 v[184:187], v150 offset:33792
	ds_read_b128 v[188:191], v150 offset:34816
	ds_read_b128 v[192:195], v150 offset:35840
	ds_read_b128 v[196:199], v150 offset:36864
	ds_read_b128 v[200:203], v150 offset:37888
	ds_read_b128 v[204:207], v150 offset:38912
	ds_read_b128 v[208:211], v150 offset:39936
	global_load_lds_dwordx4 v[214:215], off
	v_lshl_add_u64 v[214:215], v[212:213], 0, s[16:17]
	s_mov_b32 m0, s73
	s_nop 0
	global_load_lds_dwordx4 v[214:215], off
	s_waitcnt vmcnt(10)
	s_waitcnt lgkmcnt(0)
	s_barrier
	s_setprio 1
	s_waitcnt lgkmcnt(0)
	v_mfma_f32_16x16x32_bf16 v[124:127], v[136:139], v[180:183], v[124:127]
	v_mfma_f32_16x16x32_bf16 v[120:123], v[156:159], v[180:183], v[120:123]
	v_mfma_f32_16x16x32_bf16 v[112:115], v[136:139], v[188:191], v[112:115]
	v_mfma_f32_16x16x32_bf16 v[104:107], v[156:159], v[188:191], v[104:107]
	v_mfma_f32_16x16x32_bf16 v[96:99], v[136:139], v[196:199], v[96:99]
	v_mfma_f32_16x16x32_bf16 v[88:91], v[156:159], v[196:199], v[88:91]
	v_mfma_f32_16x16x32_bf16 v[80:83], v[136:139], v[204:207], v[80:83]
	v_mfma_f32_16x16x32_bf16 v[72:75], v[156:159], v[204:207], v[72:75]
	v_mfma_f32_16x16x32_bf16 v[124:127], v[152:155], v[184:187], v[124:127]
	v_mfma_f32_16x16x32_bf16 v[120:123], v[160:163], v[184:187], v[120:123]
	v_mfma_f32_16x16x32_bf16 v[112:115], v[152:155], v[192:195], v[112:115]
	v_mfma_f32_16x16x32_bf16 v[104:107], v[160:163], v[192:195], v[104:107]
	v_mfma_f32_16x16x32_bf16 v[96:99], v[152:155], v[200:203], v[96:99]
	v_mfma_f32_16x16x32_bf16 v[88:91], v[160:163], v[200:203], v[88:91]
	v_mfma_f32_16x16x32_bf16 v[80:83], v[152:155], v[208:211], v[80:83]
	v_mfma_f32_16x16x32_bf16 v[72:75], v[160:163], v[208:211], v[72:75]
	s_setprio 0
	s_setprio 1
	v_mfma_f32_16x16x32_bf16 v[116:119], v[164:167], v[180:183], v[116:119]
	v_mfma_f32_16x16x32_bf16 v[108:111], v[172:175], v[180:183], v[108:111]
	v_mfma_f32_16x16x32_bf16 v[100:103], v[164:167], v[188:191], v[100:103]
	v_mfma_f32_16x16x32_bf16 v[92:95], v[172:175], v[188:191], v[92:95]
	v_mfma_f32_16x16x32_bf16 v[84:87], v[164:167], v[196:199], v[84:87]
	v_mfma_f32_16x16x32_bf16 v[76:79], v[172:175], v[196:199], v[76:79]
	v_mfma_f32_16x16x32_bf16 v[68:71], v[164:167], v[204:207], v[68:71]
	v_mfma_f32_16x16x32_bf16 v[64:67], v[172:175], v[204:207], v[64:67]
	v_mfma_f32_16x16x32_bf16 v[116:119], v[168:171], v[184:187], v[116:119]
	v_mfma_f32_16x16x32_bf16 v[108:111], v[176:179], v[184:187], v[108:111]
	v_mfma_f32_16x16x32_bf16 v[100:103], v[168:171], v[192:195], v[100:103]
	v_mfma_f32_16x16x32_bf16 v[92:95], v[176:179], v[192:195], v[92:95]
	v_mfma_f32_16x16x32_bf16 v[84:87], v[168:171], v[200:203], v[84:87]
	v_mfma_f32_16x16x32_bf16 v[76:79], v[176:179], v[200:203], v[76:79]
	v_mfma_f32_16x16x32_bf16 v[68:71], v[168:171], v[208:211], v[68:71]
	v_mfma_f32_16x16x32_bf16 v[64:67], v[176:179], v[208:211], v[64:67]
	s_setprio 0
	s_barrier
	s_add_i32 s48, s48, s69
	v_lshl_add_u64 v[214:215], v[140:141], 0, s[18:19]
	s_mov_b32 m0, s48
	ds_read_b128 v[180:183], v150 offset:49152
	ds_read_b128 v[184:187], v150 offset:50176
	ds_read_b128 v[188:191], v150 offset:51200
	ds_read_b128 v[192:195], v150 offset:52224
	ds_read_b128 v[196:199], v150 offset:53248
	ds_read_b128 v[200:203], v150 offset:54272
	ds_read_b128 v[204:207], v150 offset:55296
	ds_read_b128 v[208:211], v150 offset:56320
	global_load_lds_dwordx4 v[214:215], off
	v_lshl_add_u64 v[214:215], v[140:141], 0, s[20:21]
	s_add_i32 m0, s48, 0x2000
	s_add_i32 s48, s49, s69
	global_load_lds_dwordx4 v[214:215], off
	v_lshl_add_u64 v[214:215], v[140:141], 0, s[22:23]
	s_mov_b32 m0, s48
	v_lshl_add_u64 v[140:141], v[140:141], 0, s[24:25]
	global_load_lds_dwordx4 v[214:215], off
	s_add_i32 m0, s48, 0x2000
	s_nop 0
	global_load_lds_dwordx4 v[140:141], off
	v_lshl_add_u64 v[140:141], v[212:213], 0, s[18:19]
	s_mov_b32 m0, s10
	s_nop 0
	global_load_lds_dwordx4 v[140:141], off
	v_lshl_add_u64 v[140:141], v[212:213], 0, s[20:21]
	s_mov_b32 m0, s74
	s_nop 0
	global_load_lds_dwordx4 v[140:141], off
	s_waitcnt vmcnt(14)
	s_waitcnt lgkmcnt(0)
	s_barrier
	s_setprio 1
	s_waitcnt lgkmcnt(0)
	v_mfma_f32_16x16x32_bf16 v[60:63], v[136:139], v[180:183], v[60:63]
	v_mfma_f32_16x16x32_bf16 v[56:59], v[156:159], v[180:183], v[56:59]
	v_mfma_f32_16x16x32_bf16 v[48:51], v[136:139], v[188:191], v[48:51]
	v_mfma_f32_16x16x32_bf16 v[40:43], v[156:159], v[188:191], v[40:43]
	v_mfma_f32_16x16x32_bf16 v[32:35], v[136:139], v[196:199], v[32:35]
	v_mfma_f32_16x16x32_bf16 v[24:27], v[156:159], v[196:199], v[24:27]
	v_mfma_f32_16x16x32_bf16 v[16:19], v[136:139], v[204:207], v[16:19]
	v_mfma_f32_16x16x32_bf16 v[8:11], v[156:159], v[204:207], v[8:11]
	v_mfma_f32_16x16x32_bf16 v[60:63], v[152:155], v[184:187], v[60:63]
	v_mfma_f32_16x16x32_bf16 v[56:59], v[160:163], v[184:187], v[56:59]
	v_mfma_f32_16x16x32_bf16 v[48:51], v[152:155], v[192:195], v[48:51]
	v_mfma_f32_16x16x32_bf16 v[40:43], v[160:163], v[192:195], v[40:43]
	v_mfma_f32_16x16x32_bf16 v[32:35], v[152:155], v[200:203], v[32:35]
	v_mfma_f32_16x16x32_bf16 v[24:27], v[160:163], v[200:203], v[24:27]
	v_mfma_f32_16x16x32_bf16 v[16:19], v[152:155], v[208:211], v[16:19]
	v_mfma_f32_16x16x32_bf16 v[8:11], v[160:163], v[208:211], v[8:11]
	s_setprio 0
	s_setprio 1
	v_mfma_f32_16x16x32_bf16 v[52:55], v[164:167], v[180:183], v[52:55]
	v_mfma_f32_16x16x32_bf16 v[44:47], v[172:175], v[180:183], v[44:47]
	v_mfma_f32_16x16x32_bf16 v[36:39], v[164:167], v[188:191], v[36:39]
	v_mfma_f32_16x16x32_bf16 v[28:31], v[172:175], v[188:191], v[28:31]
	v_mfma_f32_16x16x32_bf16 v[20:23], v[164:167], v[196:199], v[20:23]
	v_mfma_f32_16x16x32_bf16 v[12:15], v[172:175], v[196:199], v[12:15]
	v_mfma_f32_16x16x32_bf16 v[4:7], v[164:167], v[204:207], v[4:7]
	v_mfma_f32_16x16x32_bf16 v[0:3], v[172:175], v[204:207], v[0:3]
	v_mfma_f32_16x16x32_bf16 v[52:55], v[168:171], v[184:187], v[52:55]
	v_mfma_f32_16x16x32_bf16 v[44:47], v[176:179], v[184:187], v[44:47]
	v_mfma_f32_16x16x32_bf16 v[36:39], v[168:171], v[192:195], v[36:39]
	v_mfma_f32_16x16x32_bf16 v[28:31], v[176:179], v[192:195], v[28:31]
	v_mfma_f32_16x16x32_bf16 v[20:23], v[168:171], v[200:203], v[20:23]
	v_mfma_f32_16x16x32_bf16 v[12:15], v[176:179], v[200:203], v[12:15]
	v_mfma_f32_16x16x32_bf16 v[4:7], v[168:171], v[208:211], v[4:7]
	v_mfma_f32_16x16x32_bf16 v[0:3], v[176:179], v[208:211], v[0:3]
	s_setprio 0
	s_barrier
	s_add_i32 s82, s82, 2
	s_add_u32 s46, s46, 0x100
	s_addc_u32 s47, s47, 0
	s_add_u32 s80, s80, 0x100
	s_addc_u32 s81, s81, 0
	s_cmp_gt_u32 s82, 13
	s_cbranch_scc0 .LBB0_192
	s_and_b64 vcc, exec, s[30:31]
	s_cbranch_vccz .LBB0_195
	s_barrier

.Lnostb1:
	s_add_u32 s14, s60, 0xfffc0080
	s_addc_u32 s15, s61, -1
	s_add_i32 s18, 0, 0x10000
	s_cmp_eq_u32 s85, 12
	s_cselect_b32 s15, s22, s15
	s_cselect_b32 s14, s45, s14
	v_add_u32_e32 v137, s18, v141
	s_cselect_b32 vcc_hi, s43, s17
	s_cselect_b32 vcc_lo, s84, s16
	s_add_i32 s21, 0, 0x14000
	ds_read_b128 v[146:149], v137
	ds_read_b128 v[150:153], v137 offset:1024
	ds_read_b128 v[154:157], v137 offset:2048
	ds_read_b128 v[158:161], v137 offset:3072
	v_add_u32_e32 v137, s21, v141
	ds_read_b128 v[162:165], v137
	ds_read_b128 v[166:169], v137 offset:1024
	ds_read_b128 v[170:173], v137 offset:2048
	ds_read_b128 v[174:177], v137 offset:3072
	v_lshl_add_u64 v[138:139], s[60:61], 0, v[184:185]
	s_add_i32 m0, s25, 0xc000
	ds_read_b128 v[178:181], v145
	ds_read_b128 v[194:197], v145 offset:1024
	ds_read_b128 v[198:201], v145 offset:2048
	ds_read_b128 v[202:205], v145 offset:3072
	ds_read_b128 v[206:209], v145 offset:4096
	ds_read_b128 v[210:213], v145 offset:5120
	ds_read_b128 v[214:217], v145 offset:6144
	ds_read_b128 v[218:221], v145 offset:7168
	global_load_lds_dwordx4 v[138:139], off
	v_lshl_add_u64 v[138:139], v[138:139], 0, s[34:35]
	s_add_i32 m0, s25, 0xe000
	s_nop 0
	global_load_lds_dwordx4 v[138:139], off
	s_waitcnt vmcnt(10)
	s_waitcnt lgkmcnt(0)
	s_barrier
	s_setprio 1
	s_waitcnt lgkmcnt(0)
	v_mfma_f32_16x16x32_bf16 v[124:127], v[146:149], v[178:181], 0
	v_mfma_f32_16x16x32_bf16 v[120:123], v[154:157], v[178:181], 0
	v_mfma_f32_16x16x32_bf16 v[112:115], v[146:149], v[198:201], 0
	v_mfma_f32_16x16x32_bf16 v[104:107], v[154:157], v[198:201], 0
	v_mfma_f32_16x16x32_bf16 v[96:99], v[146:149], v[206:209], 0
	v_mfma_f32_16x16x32_bf16 v[88:91], v[154:157], v[206:209], 0
	v_mfma_f32_16x16x32_bf16 v[80:83], v[146:149], v[214:217], 0
	v_mfma_f32_16x16x32_bf16 v[72:75], v[154:157], v[214:217], 0
	v_mfma_f32_16x16x32_bf16 v[124:127], v[150:153], v[194:197], v[124:127]
	v_mfma_f32_16x16x32_bf16 v[120:123], v[158:161], v[194:197], v[120:123]
	v_mfma_f32_16x16x32_bf16 v[112:115], v[150:153], v[202:205], v[112:115]
	v_mfma_f32_16x16x32_bf16 v[104:107], v[158:161], v[202:205], v[104:107]
	v_mfma_f32_16x16x32_bf16 v[96:99], v[150:153], v[210:213], v[96:99]
	v_mfma_f32_16x16x32_bf16 v[88:91], v[158:161], v[210:213], v[88:91]
	v_mfma_f32_16x16x32_bf16 v[80:83], v[150:153], v[218:221], v[80:83]
	v_mfma_f32_16x16x32_bf16 v[72:75], v[158:161], v[218:221], v[72:75]
	s_setprio 0
	s_setprio 1
	v_mfma_f32_16x16x32_bf16 v[116:119], v[162:165], v[178:181], 0
	v_mfma_f32_16x16x32_bf16 v[108:111], v[170:173], v[178:181], 0
	v_mfma_f32_16x16x32_bf16 v[100:103], v[162:165], v[198:201], 0
	v_mfma_f32_16x16x32_bf16 v[92:95], v[170:173], v[198:201], 0
	v_mfma_f32_16x16x32_bf16 v[84:87], v[162:165], v[206:209], 0
	v_mfma_f32_16x16x32_bf16 v[76:79], v[170:173], v[206:209], 0
	v_mfma_f32_16x16x32_bf16 v[68:71], v[162:165], v[214:217], 0
	v_mfma_f32_16x16x32_bf16 v[64:67], v[170:173], v[214:217], 0
	v_mfma_f32_16x16x32_bf16 v[116:119], v[166:169], v[194:197], v[116:119]
	v_mfma_f32_16x16x32_bf16 v[108:111], v[174:177], v[194:197], v[108:111]
	v_mfma_f32_16x16x32_bf16 v[100:103], v[166:169], v[202:205], v[100:103]
	v_mfma_f32_16x16x32_bf16 v[92:95], v[174:177], v[202:205], v[92:95]
	v_mfma_f32_16x16x32_bf16 v[84:87], v[166:169], v[210:213], v[84:87]
	v_mfma_f32_16x16x32_bf16 v[76:79], v[174:177], v[210:213], v[76:79]
	v_mfma_f32_16x16x32_bf16 v[68:71], v[166:169], v[218:221], v[68:71]
	v_mfma_f32_16x16x32_bf16 v[64:67], v[174:177], v[218:221], v[64:67]
	s_setprio 0
	s_barrier
	s_add_i32 s18, s18, s23
	v_lshl_add_u64 v[138:139], vcc, 0, v[128:129]
	s_mov_b32 m0, s18
	ds_read_b128 v[178:181], v145 offset:16384
	ds_read_b128 v[194:197], v145 offset:17408
	ds_read_b128 v[198:201], v145 offset:18432
	ds_read_b128 v[202:205], v145 offset:19456
	ds_read_b128 v[206:209], v145 offset:20480
	ds_read_b128 v[210:213], v145 offset:21504
	ds_read_b128 v[214:217], v145 offset:22528
	ds_read_b128 v[218:221], v145 offset:23552
	global_load_lds_dwordx4 v[138:139], off
	v_lshl_add_u64 v[182:183], v[138:139], 0, s[34:35]
	s_add_i32 m0, s18, 0x2000
	s_add_i32 s18, s21, s23
	global_load_lds_dwordx4 v[182:183], off
	v_lshl_add_u64 v[182:183], v[138:139], 0, s[92:93]
	s_mov_b32 m0, s18
	s_nop 0
	global_load_lds_dwordx4 v[182:183], off
	v_lshl_add_u64 v[182:183], v[138:139], 0, s[52:53]
	s_add_i32 m0, s18, 0x2000
	s_nop 0
	global_load_lds_dwordx4 v[182:183], off
	v_lshl_add_u64 v[182:183], s[14:15], 0, v[130:131]
	s_mov_b32 m0, s25
	v_lshl_add_u64 v[186:187], v[182:183], 0, s[34:35]
	global_load_lds_dwordx4 v[182:183], off
	s_mov_b32 m0, s26
	s_nop 0
	global_load_lds_dwordx4 v[186:187], off
	s_waitcnt vmcnt(14)
	s_waitcnt lgkmcnt(0)
	s_barrier
	s_setprio 1
	s_waitcnt lgkmcnt(0)
	v_mfma_f32_16x16x32_bf16 v[60:63], v[146:149], v[178:181], 0
	v_mfma_f32_16x16x32_bf16 v[56:59], v[154:157], v[178:181], 0
	v_mfma_f32_16x16x32_bf16 v[48:51], v[146:149], v[198:201], 0
	v_mfma_f32_16x16x32_bf16 v[40:43], v[154:157], v[198:201], 0
	v_mfma_f32_16x16x32_bf16 v[32:35], v[146:149], v[206:209], 0
	v_mfma_f32_16x16x32_bf16 v[24:27], v[154:157], v[206:209], 0
	v_mfma_f32_16x16x32_bf16 v[16:19], v[146:149], v[214:217], 0
	v_mfma_f32_16x16x32_bf16 v[8:11], v[154:157], v[214:217], 0
	v_mfma_f32_16x16x32_bf16 v[60:63], v[150:153], v[194:197], v[60:63]
	v_mfma_f32_16x16x32_bf16 v[56:59], v[158:161], v[194:197], v[56:59]
	v_mfma_f32_16x16x32_bf16 v[48:51], v[150:153], v[202:205], v[48:51]
	v_mfma_f32_16x16x32_bf16 v[40:43], v[158:161], v[202:205], v[40:43]
	v_mfma_f32_16x16x32_bf16 v[32:35], v[150:153], v[210:213], v[32:35]
	v_mfma_f32_16x16x32_bf16 v[24:27], v[158:161], v[210:213], v[24:27]
	v_mfma_f32_16x16x32_bf16 v[16:19], v[150:153], v[218:221], v[16:19]
	v_mfma_f32_16x16x32_bf16 v[8:11], v[158:161], v[218:221], v[8:11]
	s_setprio 0
	s_setprio 1
	v_mfma_f32_16x16x32_bf16 v[52:55], v[162:165], v[178:181], 0
	v_mfma_f32_16x16x32_bf16 v[44:47], v[170:173], v[178:181], 0
	v_mfma_f32_16x16x32_bf16 v[36:39], v[162:165], v[198:201], 0
	v_mfma_f32_16x16x32_bf16 v[28:31], v[170:173], v[198:201], 0
	v_mfma_f32_16x16x32_bf16 v[20:23], v[162:165], v[206:209], 0
	v_mfma_f32_16x16x32_bf16 v[12:15], v[170:173], v[206:209], 0
	v_mfma_f32_16x16x32_bf16 v[4:7], v[162:165], v[214:217], 0
	v_mfma_f32_16x16x32_bf16 v[0:3], v[170:173], v[214:217], 0
	v_mfma_f32_16x16x32_bf16 v[52:55], v[166:169], v[194:197], v[52:55]
	v_mfma_f32_16x16x32_bf16 v[44:47], v[174:177], v[194:197], v[44:47]
	v_mfma_f32_16x16x32_bf16 v[36:39], v[166:169], v[202:205], v[36:39]
	v_mfma_f32_16x16x32_bf16 v[28:31], v[174:177], v[202:205], v[28:31]
	v_mfma_f32_16x16x32_bf16 v[20:23], v[166:169], v[210:213], v[20:23]
	v_mfma_f32_16x16x32_bf16 v[12:15], v[174:177], v[210:213], v[12:15]
	v_mfma_f32_16x16x32_bf16 v[4:7], v[166:169], v[218:221], v[4:7]
	v_mfma_f32_16x16x32_bf16 v[0:3], v[174:177], v[218:221], v[0:3]
	s_setprio 0
	s_barrier
	s_add_i32 s14, 0, 0x18000
	v_add_u32_e32 v137, s14, v141
	s_add_i32 s15, 0, 0x1c000
	ds_read_b128 v[146:149], v137
	ds_read_b128 v[150:153], v137 offset:1024
	ds_read_b128 v[154:157], v137 offset:2048
	ds_read_b128 v[158:161], v137 offset:3072
	v_add_u32_e32 v137, s15, v141
	ds_read_b128 v[162:165], v137
	ds_read_b128 v[166:169], v137 offset:1024
	ds_read_b128 v[170:173], v137 offset:2048
	ds_read_b128 v[174:177], v137 offset:3072
	s_mov_b32 m0, s27
	v_lshl_add_u64 v[186:187], v[182:183], 0, s[92:93]
	ds_read_b128 v[178:181], v145 offset:32768
	ds_read_b128 v[194:197], v145 offset:33792
	ds_read_b128 v[198:201], v145 offset:34816
	ds_read_b128 v[202:205], v145 offset:35840
	ds_read_b128 v[206:209], v145 offset:36864
	ds_read_b128 v[210:213], v145 offset:37888
	ds_read_b128 v[214:217], v145 offset:38912
	ds_read_b128 v[218:221], v145 offset:39936
	global_load_lds_dwordx4 v[186:187], off
	v_lshl_add_u64 v[186:187], v[182:183], 0, s[52:53]
	s_mov_b32 m0, s28
	s_nop 0
	global_load_lds_dwordx4 v[186:187], off
	s_waitcnt vmcnt(10)
	s_waitcnt lgkmcnt(0)
	s_barrier
	s_setprio 1
	s_waitcnt lgkmcnt(0)
	v_mfma_f32_16x16x32_bf16 v[124:127], v[146:149], v[178:181], v[124:127]
	v_mfma_f32_16x16x32_bf16 v[120:123], v[154:157], v[178:181], v[120:123]
	v_mfma_f32_16x16x32_bf16 v[112:115], v[146:149], v[198:201], v[112:115]
	v_mfma_f32_16x16x32_bf16 v[104:107], v[154:157], v[198:201], v[104:107]
	v_mfma_f32_16x16x32_bf16 v[96:99], v[146:149], v[206:209], v[96:99]
	v_mfma_f32_16x16x32_bf16 v[88:91], v[154:157], v[206:209], v[88:91]
	v_mfma_f32_16x16x32_bf16 v[80:83], v[146:149], v[214:217], v[80:83]
	v_mfma_f32_16x16x32_bf16 v[72:75], v[154:157], v[214:217], v[72:75]
	v_mfma_f32_16x16x32_bf16 v[124:127], v[150:153], v[194:197], v[124:127]
	v_mfma_f32_16x16x32_bf16 v[120:123], v[158:161], v[194:197], v[120:123]
	v_mfma_f32_16x16x32_bf16 v[112:115], v[150:153], v[202:205], v[112:115]
	v_mfma_f32_16x16x32_bf16 v[104:107], v[158:161], v[202:205], v[104:107]
	v_mfma_f32_16x16x32_bf16 v[96:99], v[150:153], v[210:213], v[96:99]
	v_mfma_f32_16x16x32_bf16 v[88:91], v[158:161], v[210:213], v[88:91]
	v_mfma_f32_16x16x32_bf16 v[80:83], v[150:153], v[218:221], v[80:83]
	v_mfma_f32_16x16x32_bf16 v[72:75], v[158:161], v[218:221], v[72:75]
	s_setprio 0
	s_setprio 1
	v_mfma_f32_16x16x32_bf16 v[116:119], v[162:165], v[178:181], v[116:119]
	v_mfma_f32_16x16x32_bf16 v[108:111], v[170:173], v[178:181], v[108:111]
	v_mfma_f32_16x16x32_bf16 v[100:103], v[162:165], v[198:201], v[100:103]
	v_mfma_f32_16x16x32_bf16 v[92:95], v[170:173], v[198:201], v[92:95]
	v_mfma_f32_16x16x32_bf16 v[84:87], v[162:165], v[206:209], v[84:87]
	v_mfma_f32_16x16x32_bf16 v[76:79], v[170:173], v[206:209], v[76:79]
	v_mfma_f32_16x16x32_bf16 v[68:71], v[162:165], v[214:217], v[68:71]
	v_mfma_f32_16x16x32_bf16 v[64:67], v[170:173], v[214:217], v[64:67]
	v_mfma_f32_16x16x32_bf16 v[116:119], v[166:169], v[194:197], v[116:119]
	v_mfma_f32_16x16x32_bf16 v[108:111], v[174:177], v[194:197], v[108:111]
	v_mfma_f32_16x16x32_bf16 v[100:103], v[166:169], v[202:205], v[100:103]
	v_mfma_f32_16x16x32_bf16 v[92:95], v[174:177], v[202:205], v[92:95]
	v_mfma_f32_16x16x32_bf16 v[84:87], v[166:169], v[210:213], v[84:87]
	v_mfma_f32_16x16x32_bf16 v[76:79], v[174:177], v[210:213], v[76:79]
	v_mfma_f32_16x16x32_bf16 v[68:71], v[166:169], v[218:221], v[68:71]
	v_mfma_f32_16x16x32_bf16 v[64:67], v[174:177], v[218:221], v[64:67]
	s_setprio 0
	s_barrier
	s_add_i32 s14, s14, s23
	v_lshl_add_u64 v[186:187], v[138:139], 0, s[56:57]
	s_mov_b32 m0, s14
	ds_read_b128 v[178:181], v145 offset:49152
	ds_read_b128 v[194:197], v145 offset:50176
	ds_read_b128 v[198:201], v145 offset:51200
	ds_read_b128 v[202:205], v145 offset:52224
	ds_read_b128 v[206:209], v145 offset:53248
	ds_read_b128 v[210:213], v145 offset:54272
	ds_read_b128 v[214:217], v145 offset:55296
	ds_read_b128 v[218:221], v145 offset:56320
	global_load_lds_dwordx4 v[186:187], off
	v_lshl_add_u64 v[186:187], v[138:139], 0, s[96:97]
	s_add_i32 m0, s14, 0x2000
	s_add_i32 s14, s15, s23
	global_load_lds_dwordx4 v[186:187], off
	v_lshl_add_u64 v[186:187], v[138:139], 0, s[88:89]
	s_mov_b32 m0, s14
	v_lshl_add_u64 v[138:139], v[138:139], 0, s[68:69]
	global_load_lds_dwordx4 v[186:187], off
	s_add_i32 m0, s14, 0x2000
	s_nop 0
	global_load_lds_dwordx4 v[138:139], off
	v_lshl_add_u64 v[138:139], v[182:183], 0, s[56:57]
	s_mov_b32 m0, s29
	s_nop 0
	global_load_lds_dwordx4 v[138:139], off
	v_lshl_add_u64 v[138:139], v[182:183], 0, s[96:97]
	s_mov_b32 m0, s30
	s_nop 0
	global_load_lds_dwordx4 v[138:139], off
	s_waitcnt vmcnt(14)
	s_waitcnt lgkmcnt(0)
	s_barrier
	s_setprio 1
	s_waitcnt lgkmcnt(0)
	v_mfma_f32_16x16x32_bf16 v[60:63], v[146:149], v[178:181], v[60:63]
	v_mfma_f32_16x16x32_bf16 v[56:59], v[154:157], v[178:181], v[56:59]
	v_mfma_f32_16x16x32_bf16 v[48:51], v[146:149], v[198:201], v[48:51]
	v_mfma_f32_16x16x32_bf16 v[40:43], v[154:157], v[198:201], v[40:43]
	v_mfma_f32_16x16x32_bf16 v[32:35], v[146:149], v[206:209], v[32:35]
	v_mfma_f32_16x16x32_bf16 v[24:27], v[154:157], v[206:209], v[24:27]
	v_mfma_f32_16x16x32_bf16 v[16:19], v[146:149], v[214:217], v[16:19]
	v_mfma_f32_16x16x32_bf16 v[8:11], v[154:157], v[214:217], v[8:11]
	v_mfma_f32_16x16x32_bf16 v[60:63], v[150:153], v[194:197], v[60:63]
	v_mfma_f32_16x16x32_bf16 v[56:59], v[158:161], v[194:197], v[56:59]
	v_mfma_f32_16x16x32_bf16 v[48:51], v[150:153], v[202:205], v[48:51]
	v_mfma_f32_16x16x32_bf16 v[40:43], v[158:161], v[202:205], v[40:43]
	v_mfma_f32_16x16x32_bf16 v[32:35], v[150:153], v[210:213], v[32:35]
	v_mfma_f32_16x16x32_bf16 v[24:27], v[158:161], v[210:213], v[24:27]
	v_mfma_f32_16x16x32_bf16 v[16:19], v[150:153], v[218:221], v[16:19]
	v_mfma_f32_16x16x32_bf16 v[8:11], v[158:161], v[218:221], v[8:11]
	s_setprio 0
	s_setprio 1
	v_mfma_f32_16x16x32_bf16 v[52:55], v[162:165], v[178:181], v[52:55]
	v_mfma_f32_16x16x32_bf16 v[44:47], v[170:173], v[178:181], v[44:47]
	v_mfma_f32_16x16x32_bf16 v[36:39], v[162:165], v[198:201], v[36:39]
	v_mfma_f32_16x16x32_bf16 v[28:31], v[170:173], v[198:201], v[28:31]
	v_mfma_f32_16x16x32_bf16 v[20:23], v[162:165], v[206:209], v[20:23]
	v_mfma_f32_16x16x32_bf16 v[12:15], v[170:173], v[206:209], v[12:15]
	v_mfma_f32_16x16x32_bf16 v[4:7], v[162:165], v[214:217], v[4:7]
	v_mfma_f32_16x16x32_bf16 v[0:3], v[170:173], v[214:217], v[0:3]
	v_mfma_f32_16x16x32_bf16 v[52:55], v[166:169], v[194:197], v[52:55]
	v_mfma_f32_16x16x32_bf16 v[44:47], v[174:177], v[194:197], v[44:47]
	v_mfma_f32_16x16x32_bf16 v[36:39], v[166:169], v[202:205], v[36:39]
	v_mfma_f32_16x16x32_bf16 v[28:31], v[174:177], v[202:205], v[28:31]
	v_mfma_f32_16x16x32_bf16 v[20:23], v[166:169], v[210:213], v[20:23]
	v_mfma_f32_16x16x32_bf16 v[12:15], v[174:177], v[210:213], v[12:15]
	v_mfma_f32_16x16x32_bf16 v[4:7], v[166:169], v[218:221], v[4:7]
	v_mfma_f32_16x16x32_bf16 v[0:3], v[174:177], v[218:221], v[0:3]
	s_setprio 0
	s_barrier
	s_add_i32 s85, s85, 2
	s_add_u32 s60, s60, 0x100
	s_addc_u32 s61, s61, 0
	s_add_u32 s16, s16, 0x100
	s_addc_u32 s17, s17, 0
	s_cmp_gt_u32 s85, 13
.LBB0_229:
	s_add_u32 s14, s60, 0xfffc0080
	s_addc_u32 s15, s61, -1
	s_add_i32 s18, 0, 0x10000
	s_cmp_eq_u32 s85, 12
	s_cselect_b32 s15, s22, s15
	s_cselect_b32 s14, s45, s14
	v_add_u32_e32 v137, s18, v141
	s_cselect_b32 vcc_hi, s43, s17
	s_cselect_b32 vcc_lo, s84, s16
	s_add_i32 s21, 0, 0x14000
	ds_read_b128 v[146:149], v137
	ds_read_b128 v[150:153], v137 offset:1024
	ds_read_b128 v[154:157], v137 offset:2048
	ds_read_b128 v[158:161], v137 offset:3072
	v_add_u32_e32 v137, s21, v141
	ds_read_b128 v[162:165], v137
	ds_read_b128 v[166:169], v137 offset:1024
	ds_read_b128 v[170:173], v137 offset:2048
	ds_read_b128 v[174:177], v137 offset:3072
	v_lshl_add_u64 v[138:139], s[60:61], 0, v[184:185]
	s_add_i32 m0, s25, 0xc000
	ds_read_b128 v[178:181], v145
	ds_read_b128 v[194:197], v145 offset:1024
	ds_read_b128 v[198:201], v145 offset:2048
	ds_read_b128 v[202:205], v145 offset:3072
	ds_read_b128 v[206:209], v145 offset:4096
	ds_read_b128 v[210:213], v145 offset:5120
	ds_read_b128 v[214:217], v145 offset:6144
	ds_read_b128 v[218:221], v145 offset:7168
	global_load_lds_dwordx4 v[138:139], off
	v_lshl_add_u64 v[138:139], v[138:139], 0, s[34:35]
	s_add_i32 m0, s25, 0xe000
	s_nop 0
	global_load_lds_dwordx4 v[138:139], off
	s_waitcnt vmcnt(10)
	s_waitcnt lgkmcnt(0)
	s_barrier
	s_setprio 1
	s_waitcnt lgkmcnt(0)
	v_mfma_f32_16x16x32_bf16 v[124:127], v[146:149], v[178:181], v[124:127]
	v_mfma_f32_16x16x32_bf16 v[120:123], v[154:157], v[178:181], v[120:123]
	v_mfma_f32_16x16x32_bf16 v[112:115], v[146:149], v[198:201], v[112:115]
	v_mfma_f32_16x16x32_bf16 v[104:107], v[154:157], v[198:201], v[104:107]
	v_mfma_f32_16x16x32_bf16 v[96:99], v[146:149], v[206:209], v[96:99]
	v_mfma_f32_16x16x32_bf16 v[88:91], v[154:157], v[206:209], v[88:91]
	v_mfma_f32_16x16x32_bf16 v[80:83], v[146:149], v[214:217], v[80:83]
	v_mfma_f32_16x16x32_bf16 v[72:75], v[154:157], v[214:217], v[72:75]
	v_mfma_f32_16x16x32_bf16 v[124:127], v[150:153], v[194:197], v[124:127]
	v_mfma_f32_16x16x32_bf16 v[120:123], v[158:161], v[194:197], v[120:123]
	v_mfma_f32_16x16x32_bf16 v[112:115], v[150:153], v[202:205], v[112:115]
	v_mfma_f32_16x16x32_bf16 v[104:107], v[158:161], v[202:205], v[104:107]
	v_mfma_f32_16x16x32_bf16 v[96:99], v[150:153], v[210:213], v[96:99]
	v_mfma_f32_16x16x32_bf16 v[88:91], v[158:161], v[210:213], v[88:91]
	v_mfma_f32_16x16x32_bf16 v[80:83], v[150:153], v[218:221], v[80:83]
	v_mfma_f32_16x16x32_bf16 v[72:75], v[158:161], v[218:221], v[72:75]
	s_setprio 0
	s_setprio 1
	v_mfma_f32_16x16x32_bf16 v[116:119], v[162:165], v[178:181], v[116:119]
	v_mfma_f32_16x16x32_bf16 v[108:111], v[170:173], v[178:181], v[108:111]
	v_mfma_f32_16x16x32_bf16 v[100:103], v[162:165], v[198:201], v[100:103]
	v_mfma_f32_16x16x32_bf16 v[92:95], v[170:173], v[198:201], v[92:95]
	v_mfma_f32_16x16x32_bf16 v[84:87], v[162:165], v[206:209], v[84:87]
	v_mfma_f32_16x16x32_bf16 v[76:79], v[170:173], v[206:209], v[76:79]
	v_mfma_f32_16x16x32_bf16 v[68:71], v[162:165], v[214:217], v[68:71]
	v_mfma_f32_16x16x32_bf16 v[64:67], v[170:173], v[214:217], v[64:67]
	v_mfma_f32_16x16x32_bf16 v[116:119], v[166:169], v[194:197], v[116:119]
	v_mfma_f32_16x16x32_bf16 v[108:111], v[174:177], v[194:197], v[108:111]
	v_mfma_f32_16x16x32_bf16 v[100:103], v[166:169], v[202:205], v[100:103]
	v_mfma_f32_16x16x32_bf16 v[92:95], v[174:177], v[202:205], v[92:95]
	v_mfma_f32_16x16x32_bf16 v[84:87], v[166:169], v[210:213], v[84:87]
	v_mfma_f32_16x16x32_bf16 v[76:79], v[174:177], v[210:213], v[76:79]
	v_mfma_f32_16x16x32_bf16 v[68:71], v[166:169], v[218:221], v[68:71]
	v_mfma_f32_16x16x32_bf16 v[64:67], v[174:177], v[218:221], v[64:67]
	s_setprio 0
	s_barrier
	s_add_i32 s18, s18, s23
	v_lshl_add_u64 v[138:139], vcc, 0, v[128:129]
	s_mov_b32 m0, s18
	ds_read_b128 v[178:181], v145 offset:16384
	ds_read_b128 v[194:197], v145 offset:17408
	ds_read_b128 v[198:201], v145 offset:18432
	ds_read_b128 v[202:205], v145 offset:19456
	ds_read_b128 v[206:209], v145 offset:20480
	ds_read_b128 v[210:213], v145 offset:21504
	ds_read_b128 v[214:217], v145 offset:22528
	ds_read_b128 v[218:221], v145 offset:23552
	global_load_lds_dwordx4 v[138:139], off
	v_lshl_add_u64 v[182:183], v[138:139], 0, s[34:35]
	s_add_i32 m0, s18, 0x2000
	s_add_i32 s18, s21, s23
	global_load_lds_dwordx4 v[182:183], off
	v_lshl_add_u64 v[182:183], v[138:139], 0, s[92:93]
	s_mov_b32 m0, s18
	s_nop 0
	global_load_lds_dwordx4 v[182:183], off
	v_lshl_add_u64 v[182:183], v[138:139], 0, s[52:53]
	s_add_i32 m0, s18, 0x2000
	s_nop 0
	global_load_lds_dwordx4 v[182:183], off
	v_lshl_add_u64 v[182:183], s[14:15], 0, v[130:131]
	s_mov_b32 m0, s25
	v_lshl_add_u64 v[186:187], v[182:183], 0, s[34:35]
	global_load_lds_dwordx4 v[182:183], off
	s_mov_b32 m0, s26
	s_nop 0
	global_load_lds_dwordx4 v[186:187], off
	s_waitcnt vmcnt(14)
	s_waitcnt lgkmcnt(0)
	s_barrier
	s_setprio 1
	s_waitcnt lgkmcnt(0)
	v_mfma_f32_16x16x32_bf16 v[60:63], v[146:149], v[178:181], v[60:63]
	v_mfma_f32_16x16x32_bf16 v[56:59], v[154:157], v[178:181], v[56:59]
	v_mfma_f32_16x16x32_bf16 v[48:51], v[146:149], v[198:201], v[48:51]
	v_mfma_f32_16x16x32_bf16 v[40:43], v[154:157], v[198:201], v[40:43]
	v_mfma_f32_16x16x32_bf16 v[32:35], v[146:149], v[206:209], v[32:35]
	v_mfma_f32_16x16x32_bf16 v[24:27], v[154:157], v[206:209], v[24:27]
	v_mfma_f32_16x16x32_bf16 v[16:19], v[146:149], v[214:217], v[16:19]
	v_mfma_f32_16x16x32_bf16 v[8:11], v[154:157], v[214:217], v[8:11]
	v_mfma_f32_16x16x32_bf16 v[60:63], v[150:153], v[194:197], v[60:63]
	v_mfma_f32_16x16x32_bf16 v[56:59], v[158:161], v[194:197], v[56:59]
	v_mfma_f32_16x16x32_bf16 v[48:51], v[150:153], v[202:205], v[48:51]
	v_mfma_f32_16x16x32_bf16 v[40:43], v[158:161], v[202:205], v[40:43]
	v_mfma_f32_16x16x32_bf16 v[32:35], v[150:153], v[210:213], v[32:35]
	v_mfma_f32_16x16x32_bf16 v[24:27], v[158:161], v[210:213], v[24:27]
	v_mfma_f32_16x16x32_bf16 v[16:19], v[150:153], v[218:221], v[16:19]
	v_mfma_f32_16x16x32_bf16 v[8:11], v[158:161], v[218:221], v[8:11]
	s_setprio 0
	s_setprio 1
	v_mfma_f32_16x16x32_bf16 v[52:55], v[162:165], v[178:181], v[52:55]
	v_mfma_f32_16x16x32_bf16 v[44:47], v[170:173], v[178:181], v[44:47]
	v_mfma_f32_16x16x32_bf16 v[36:39], v[162:165], v[198:201], v[36:39]
	v_mfma_f32_16x16x32_bf16 v[28:31], v[170:173], v[198:201], v[28:31]
	v_mfma_f32_16x16x32_bf16 v[20:23], v[162:165], v[206:209], v[20:23]
	v_mfma_f32_16x16x32_bf16 v[12:15], v[170:173], v[206:209], v[12:15]
	v_mfma_f32_16x16x32_bf16 v[4:7], v[162:165], v[214:217], v[4:7]
	v_mfma_f32_16x16x32_bf16 v[0:3], v[170:173], v[214:217], v[0:3]
	v_mfma_f32_16x16x32_bf16 v[52:55], v[166:169], v[194:197], v[52:55]
	v_mfma_f32_16x16x32_bf16 v[44:47], v[174:177], v[194:197], v[44:47]
	v_mfma_f32_16x16x32_bf16 v[36:39], v[166:169], v[202:205], v[36:39]
	v_mfma_f32_16x16x32_bf16 v[28:31], v[174:177], v[202:205], v[28:31]
	v_mfma_f32_16x16x32_bf16 v[20:23], v[166:169], v[210:213], v[20:23]
	v_mfma_f32_16x16x32_bf16 v[12:15], v[174:177], v[210:213], v[12:15]
	v_mfma_f32_16x16x32_bf16 v[4:7], v[166:169], v[218:221], v[4:7]
	v_mfma_f32_16x16x32_bf16 v[0:3], v[174:177], v[218:221], v[0:3]
	s_setprio 0
	s_barrier
	s_add_i32 s14, 0, 0x18000
	v_add_u32_e32 v137, s14, v141
	s_add_i32 s15, 0, 0x1c000
	ds_read_b128 v[146:149], v137
	ds_read_b128 v[150:153], v137 offset:1024
	ds_read_b128 v[154:157], v137 offset:2048
	ds_read_b128 v[158:161], v137 offset:3072
	v_add_u32_e32 v137, s15, v141
	ds_read_b128 v[162:165], v137
	ds_read_b128 v[166:169], v137 offset:1024
	ds_read_b128 v[170:173], v137 offset:2048
	ds_read_b128 v[174:177], v137 offset:3072
	s_mov_b32 m0, s27
	v_lshl_add_u64 v[186:187], v[182:183], 0, s[92:93]
	ds_read_b128 v[178:181], v145 offset:32768
	ds_read_b128 v[194:197], v145 offset:33792
	ds_read_b128 v[198:201], v145 offset:34816
	ds_read_b128 v[202:205], v145 offset:35840
	ds_read_b128 v[206:209], v145 offset:36864
	ds_read_b128 v[210:213], v145 offset:37888
	ds_read_b128 v[214:217], v145 offset:38912
	ds_read_b128 v[218:221], v145 offset:39936
	global_load_lds_dwordx4 v[186:187], off
	v_lshl_add_u64 v[186:187], v[182:183], 0, s[52:53]
	s_mov_b32 m0, s28
	s_nop 0
	global_load_lds_dwordx4 v[186:187], off
	s_waitcnt vmcnt(10)
	s_waitcnt lgkmcnt(0)
	s_barrier
	s_setprio 1
	s_waitcnt lgkmcnt(0)
	v_mfma_f32_16x16x32_bf16 v[124:127], v[146:149], v[178:181], v[124:127]
	v_mfma_f32_16x16x32_bf16 v[120:123], v[154:157], v[178:181], v[120:123]
	v_mfma_f32_16x16x32_bf16 v[112:115], v[146:149], v[198:201], v[112:115]
	v_mfma_f32_16x16x32_bf16 v[104:107], v[154:157], v[198:201], v[104:107]
	v_mfma_f32_16x16x32_bf16 v[96:99], v[146:149], v[206:209], v[96:99]
	v_mfma_f32_16x16x32_bf16 v[88:91], v[154:157], v[206:209], v[88:91]
	v_mfma_f32_16x16x32_bf16 v[80:83], v[146:149], v[214:217], v[80:83]
	v_mfma_f32_16x16x32_bf16 v[72:75], v[154:157], v[214:217], v[72:75]
	v_mfma_f32_16x16x32_bf16 v[124:127], v[150:153], v[194:197], v[124:127]
	v_mfma_f32_16x16x32_bf16 v[120:123], v[158:161], v[194:197], v[120:123]
	v_mfma_f32_16x16x32_bf16 v[112:115], v[150:153], v[202:205], v[112:115]
	v_mfma_f32_16x16x32_bf16 v[104:107], v[158:161], v[202:205], v[104:107]
	v_mfma_f32_16x16x32_bf16 v[96:99], v[150:153], v[210:213], v[96:99]
	v_mfma_f32_16x16x32_bf16 v[88:91], v[158:161], v[210:213], v[88:91]
	v_mfma_f32_16x16x32_bf16 v[80:83], v[150:153], v[218:221], v[80:83]
	v_mfma_f32_16x16x32_bf16 v[72:75], v[158:161], v[218:221], v[72:75]
	s_setprio 0
	s_setprio 1
	v_mfma_f32_16x16x32_bf16 v[116:119], v[162:165], v[178:181], v[116:119]
	v_mfma_f32_16x16x32_bf16 v[108:111], v[170:173], v[178:181], v[108:111]
	v_mfma_f32_16x16x32_bf16 v[100:103], v[162:165], v[198:201], v[100:103]
	v_mfma_f32_16x16x32_bf16 v[92:95], v[170:173], v[198:201], v[92:95]
	v_mfma_f32_16x16x32_bf16 v[84:87], v[162:165], v[206:209], v[84:87]
	v_mfma_f32_16x16x32_bf16 v[76:79], v[170:173], v[206:209], v[76:79]
	v_mfma_f32_16x16x32_bf16 v[68:71], v[162:165], v[214:217], v[68:71]
	v_mfma_f32_16x16x32_bf16 v[64:67], v[170:173], v[214:217], v[64:67]
	v_mfma_f32_16x16x32_bf16 v[116:119], v[166:169], v[194:197], v[116:119]
	v_mfma_f32_16x16x32_bf16 v[108:111], v[174:177], v[194:197], v[108:111]
	v_mfma_f32_16x16x32_bf16 v[100:103], v[166:169], v[202:205], v[100:103]
	v_mfma_f32_16x16x32_bf16 v[92:95], v[174:177], v[202:205], v[92:95]
	v_mfma_f32_16x16x32_bf16 v[84:87], v[166:169], v[210:213], v[84:87]
	v_mfma_f32_16x16x32_bf16 v[76:79], v[174:177], v[210:213], v[76:79]
	v_mfma_f32_16x16x32_bf16 v[68:71], v[166:169], v[218:221], v[68:71]
	v_mfma_f32_16x16x32_bf16 v[64:67], v[174:177], v[218:221], v[64:67]
	s_setprio 0
	s_barrier
	s_add_i32 s14, s14, s23
	v_lshl_add_u64 v[186:187], v[138:139], 0, s[56:57]
	s_mov_b32 m0, s14
	ds_read_b128 v[178:181], v145 offset:49152
	ds_read_b128 v[194:197], v145 offset:50176
	ds_read_b128 v[198:201], v145 offset:51200
	ds_read_b128 v[202:205], v145 offset:52224
	ds_read_b128 v[206:209], v145 offset:53248
	ds_read_b128 v[210:213], v145 offset:54272
	ds_read_b128 v[214:217], v145 offset:55296
	ds_read_b128 v[218:221], v145 offset:56320
	global_load_lds_dwordx4 v[186:187], off
	v_lshl_add_u64 v[186:187], v[138:139], 0, s[96:97]
	s_add_i32 m0, s14, 0x2000
	s_add_i32 s14, s15, s23
	global_load_lds_dwordx4 v[186:187], off
	v_lshl_add_u64 v[186:187], v[138:139], 0, s[88:89]
	s_mov_b32 m0, s14
	v_lshl_add_u64 v[138:139], v[138:139], 0, s[68:69]
	global_load_lds_dwordx4 v[186:187], off
	s_add_i32 m0, s14, 0x2000
	s_nop 0
	global_load_lds_dwordx4 v[138:139], off
	v_lshl_add_u64 v[138:139], v[182:183], 0, s[56:57]
	s_mov_b32 m0, s29
	s_nop 0
	global_load_lds_dwordx4 v[138:139], off
	v_lshl_add_u64 v[138:139], v[182:183], 0, s[96:97]
	s_mov_b32 m0, s30
	s_nop 0
	global_load_lds_dwordx4 v[138:139], off
	s_waitcnt vmcnt(14)
	s_waitcnt lgkmcnt(0)
	s_barrier
	s_setprio 1
	s_waitcnt lgkmcnt(0)
	v_mfma_f32_16x16x32_bf16 v[60:63], v[146:149], v[178:181], v[60:63]
	v_mfma_f32_16x16x32_bf16 v[56:59], v[154:157], v[178:181], v[56:59]
	v_mfma_f32_16x16x32_bf16 v[48:51], v[146:149], v[198:201], v[48:51]
	v_mfma_f32_16x16x32_bf16 v[40:43], v[154:157], v[198:201], v[40:43]
	v_mfma_f32_16x16x32_bf16 v[32:35], v[146:149], v[206:209], v[32:35]
	v_mfma_f32_16x16x32_bf16 v[24:27], v[154:157], v[206:209], v[24:27]
	v_mfma_f32_16x16x32_bf16 v[16:19], v[146:149], v[214:217], v[16:19]
	v_mfma_f32_16x16x32_bf16 v[8:11], v[154:157], v[214:217], v[8:11]
	v_mfma_f32_16x16x32_bf16 v[60:63], v[150:153], v[194:197], v[60:63]
	v_mfma_f32_16x16x32_bf16 v[56:59], v[158:161], v[194:197], v[56:59]
	v_mfma_f32_16x16x32_bf16 v[48:51], v[150:153], v[202:205], v[48:51]
	v_mfma_f32_16x16x32_bf16 v[40:43], v[158:161], v[202:205], v[40:43]
	v_mfma_f32_16x16x32_bf16 v[32:35], v[150:153], v[210:213], v[32:35]
	v_mfma_f32_16x16x32_bf16 v[24:27], v[158:161], v[210:213], v[24:27]
	v_mfma_f32_16x16x32_bf16 v[16:19], v[150:153], v[218:221], v[16:19]
	v_mfma_f32_16x16x32_bf16 v[8:11], v[158:161], v[218:221], v[8:11]
	s_setprio 0
	s_setprio 1
	v_mfma_f32_16x16x32_bf16 v[52:55], v[162:165], v[178:181], v[52:55]
	v_mfma_f32_16x16x32_bf16 v[44:47], v[170:173], v[178:181], v[44:47]
	v_mfma_f32_16x16x32_bf16 v[36:39], v[162:165], v[198:201], v[36:39]
	v_mfma_f32_16x16x32_bf16 v[28:31], v[170:173], v[198:201], v[28:31]
	v_mfma_f32_16x16x32_bf16 v[20:23], v[162:165], v[206:209], v[20:23]
	v_mfma_f32_16x16x32_bf16 v[12:15], v[170:173], v[206:209], v[12:15]
	v_mfma_f32_16x16x32_bf16 v[4:7], v[162:165], v[214:217], v[4:7]
	v_mfma_f32_16x16x32_bf16 v[0:3], v[170:173], v[214:217], v[0:3]
	v_mfma_f32_16x16x32_bf16 v[52:55], v[166:169], v[194:197], v[52:55]
	v_mfma_f32_16x16x32_bf16 v[44:47], v[174:177], v[194:197], v[44:47]
	v_mfma_f32_16x16x32_bf16 v[36:39], v[166:169], v[202:205], v[36:39]
	v_mfma_f32_16x16x32_bf16 v[28:31], v[174:177], v[202:205], v[28:31]
	v_mfma_f32_16x16x32_bf16 v[20:23], v[166:169], v[210:213], v[20:23]
	v_mfma_f32_16x16x32_bf16 v[12:15], v[174:177], v[210:213], v[12:15]
	v_mfma_f32_16x16x32_bf16 v[4:7], v[166:169], v[218:221], v[4:7]
	v_mfma_f32_16x16x32_bf16 v[0:3], v[174:177], v[218:221], v[0:3]
	s_setprio 0
	s_barrier
	s_add_i32 s85, s85, 2
	s_add_u32 s60, s60, 0x100
	s_addc_u32 s61, s61, 0
	s_add_u32 s16, s16, 0x100
	s_addc_u32 s17, s17, 0
	s_cmp_gt_u32 s85, 13
	s_cbranch_scc0 .LBB0_229
	s_and_b64 vcc, exec, s[40:41]
	s_cbranch_vccz .LBB0_232
	s_barrier

.Lnostb2:
	s_add_u32 s14, s60, 0xfffc0080
	s_addc_u32 s15, s61, -1
	s_add_i32 s18, 0, 0x10000
	s_cmp_eq_u32 s85, 12
	s_cselect_b32 s15, s22, s15
	s_cselect_b32 s14, s45, s14
	s_waitcnt lgkmcnt(0)
	v_add_u32_e32 v137, s18, v149
	s_cselect_b32 vcc_hi, s43, s17
	s_cselect_b32 vcc_lo, s84, s16
	s_add_i32 s21, 0, 0x14000
	ds_read_b128 v[138:141], v137
	ds_read_b128 v[142:145], v137 offset:1024
	ds_read_b128 v[154:157], v137 offset:2048
	ds_read_b128 v[158:161], v137 offset:3072
	v_add_u32_e32 v137, s21, v149
	ds_read_b128 v[162:165], v137
	ds_read_b128 v[166:169], v137 offset:1024
	ds_read_b128 v[170:173], v137 offset:2048
	ds_read_b128 v[174:177], v137 offset:3072
	v_lshl_add_u64 v[146:147], s[60:61], 0, v[134:135]
	s_add_i32 m0, s25, 0xc000
	ds_read_b128 v[178:181], v153
	ds_read_b128 v[194:197], v153 offset:1024
	ds_read_b128 v[198:201], v153 offset:2048
	ds_read_b128 v[202:205], v153 offset:3072
	ds_read_b128 v[206:209], v153 offset:4096
	ds_read_b128 v[210:213], v153 offset:5120
	ds_read_b128 v[214:217], v153 offset:6144
	ds_read_b128 v[218:221], v153 offset:7168
	global_load_lds_dwordx4 v[146:147], off
	v_lshl_add_u64 v[146:147], v[146:147], 0, s[34:35]
	s_add_i32 m0, s25, 0xe000
	s_nop 0
	global_load_lds_dwordx4 v[146:147], off
	s_waitcnt vmcnt(10)
	s_waitcnt lgkmcnt(0)
	s_barrier
	s_setprio 1
	s_waitcnt lgkmcnt(0)
	v_mfma_f32_16x16x32_bf16 v[124:127], v[138:141], v[178:181], 0
	v_mfma_f32_16x16x32_bf16 v[120:123], v[154:157], v[178:181], 0
	v_mfma_f32_16x16x32_bf16 v[108:111], v[138:141], v[198:201], 0
	v_mfma_f32_16x16x32_bf16 v[104:107], v[154:157], v[198:201], 0
	v_mfma_f32_16x16x32_bf16 v[96:99], v[138:141], v[206:209], 0
	v_mfma_f32_16x16x32_bf16 v[88:91], v[154:157], v[206:209], 0
	v_mfma_f32_16x16x32_bf16 v[80:83], v[138:141], v[214:217], 0
	v_mfma_f32_16x16x32_bf16 v[72:75], v[154:157], v[214:217], 0
	v_mfma_f32_16x16x32_bf16 v[124:127], v[142:145], v[194:197], v[124:127]
	v_mfma_f32_16x16x32_bf16 v[120:123], v[158:161], v[194:197], v[120:123]
	v_mfma_f32_16x16x32_bf16 v[108:111], v[142:145], v[202:205], v[108:111]
	v_mfma_f32_16x16x32_bf16 v[104:107], v[158:161], v[202:205], v[104:107]
	v_mfma_f32_16x16x32_bf16 v[96:99], v[142:145], v[210:213], v[96:99]
	v_mfma_f32_16x16x32_bf16 v[88:91], v[158:161], v[210:213], v[88:91]
	v_mfma_f32_16x16x32_bf16 v[80:83], v[142:145], v[218:221], v[80:83]
	v_mfma_f32_16x16x32_bf16 v[72:75], v[158:161], v[218:221], v[72:75]
	s_setprio 0
	s_setprio 1
	v_mfma_f32_16x16x32_bf16 v[116:119], v[162:165], v[178:181], 0
	v_mfma_f32_16x16x32_bf16 v[112:115], v[170:173], v[178:181], 0
	v_mfma_f32_16x16x32_bf16 v[100:103], v[162:165], v[198:201], 0
	v_mfma_f32_16x16x32_bf16 v[92:95], v[170:173], v[198:201], 0
	v_mfma_f32_16x16x32_bf16 v[84:87], v[162:165], v[206:209], 0
	v_mfma_f32_16x16x32_bf16 v[76:79], v[170:173], v[206:209], 0
	v_mfma_f32_16x16x32_bf16 v[68:71], v[162:165], v[214:217], 0
	v_mfma_f32_16x16x32_bf16 v[64:67], v[170:173], v[214:217], 0
	v_mfma_f32_16x16x32_bf16 v[116:119], v[166:169], v[194:197], v[116:119]
	v_mfma_f32_16x16x32_bf16 v[112:115], v[174:177], v[194:197], v[112:115]
	v_mfma_f32_16x16x32_bf16 v[100:103], v[166:169], v[202:205], v[100:103]
	v_mfma_f32_16x16x32_bf16 v[92:95], v[174:177], v[202:205], v[92:95]
	v_mfma_f32_16x16x32_bf16 v[84:87], v[166:169], v[210:213], v[84:87]
	v_mfma_f32_16x16x32_bf16 v[76:79], v[174:177], v[210:213], v[76:79]
	v_mfma_f32_16x16x32_bf16 v[68:71], v[166:169], v[218:221], v[68:71]
	v_mfma_f32_16x16x32_bf16 v[64:67], v[174:177], v[218:221], v[64:67]
	s_setprio 0
	s_barrier
	s_add_i32 s18, s18, s23
	v_lshl_add_u64 v[146:147], vcc, 0, v[128:129]
	s_mov_b32 m0, s18
	ds_read_b128 v[178:181], v153 offset:16384
	ds_read_b128 v[194:197], v153 offset:17408
	ds_read_b128 v[198:201], v153 offset:18432
	ds_read_b128 v[202:205], v153 offset:19456
	ds_read_b128 v[206:209], v153 offset:20480
	ds_read_b128 v[210:213], v153 offset:21504
	ds_read_b128 v[214:217], v153 offset:22528
	ds_read_b128 v[218:221], v153 offset:23552
	global_load_lds_dwordx4 v[146:147], off
	v_lshl_add_u64 v[182:183], v[146:147], 0, s[34:35]
	s_add_i32 m0, s18, 0x2000
	s_add_i32 s18, s21, s23
	global_load_lds_dwordx4 v[182:183], off
	v_lshl_add_u64 v[182:183], v[146:147], 0, s[92:93]
	s_mov_b32 m0, s18
	s_nop 0
	global_load_lds_dwordx4 v[182:183], off
	v_lshl_add_u64 v[182:183], v[146:147], 0, s[52:53]
	s_add_i32 m0, s18, 0x2000
	s_nop 0
	global_load_lds_dwordx4 v[182:183], off
	v_lshl_add_u64 v[182:183], s[14:15], 0, v[130:131]
	s_mov_b32 m0, s25
	v_lshl_add_u64 v[186:187], v[182:183], 0, s[34:35]
	global_load_lds_dwordx4 v[182:183], off
	s_mov_b32 m0, s26
	s_nop 0
	global_load_lds_dwordx4 v[186:187], off
	s_waitcnt vmcnt(14)
	s_waitcnt lgkmcnt(0)
	s_barrier
	s_setprio 1
	s_waitcnt lgkmcnt(0)
	v_mfma_f32_16x16x32_bf16 v[60:63], v[138:141], v[178:181], 0
	v_mfma_f32_16x16x32_bf16 v[56:59], v[154:157], v[178:181], 0
	v_mfma_f32_16x16x32_bf16 v[48:51], v[138:141], v[198:201], 0
	v_mfma_f32_16x16x32_bf16 v[40:43], v[154:157], v[198:201], 0
	v_mfma_f32_16x16x32_bf16 v[32:35], v[138:141], v[206:209], 0
	v_mfma_f32_16x16x32_bf16 v[24:27], v[154:157], v[206:209], 0
	v_mfma_f32_16x16x32_bf16 v[16:19], v[138:141], v[214:217], 0
	v_mfma_f32_16x16x32_bf16 v[8:11], v[154:157], v[214:217], 0
	v_mfma_f32_16x16x32_bf16 v[60:63], v[142:145], v[194:197], v[60:63]
	v_mfma_f32_16x16x32_bf16 v[56:59], v[158:161], v[194:197], v[56:59]
	v_mfma_f32_16x16x32_bf16 v[48:51], v[142:145], v[202:205], v[48:51]
	v_mfma_f32_16x16x32_bf16 v[40:43], v[158:161], v[202:205], v[40:43]
	v_mfma_f32_16x16x32_bf16 v[32:35], v[142:145], v[210:213], v[32:35]
	v_mfma_f32_16x16x32_bf16 v[24:27], v[158:161], v[210:213], v[24:27]
	v_mfma_f32_16x16x32_bf16 v[16:19], v[142:145], v[218:221], v[16:19]
	v_mfma_f32_16x16x32_bf16 v[8:11], v[158:161], v[218:221], v[8:11]
	s_setprio 0
	s_setprio 1
	v_mfma_f32_16x16x32_bf16 v[52:55], v[162:165], v[178:181], 0
	v_mfma_f32_16x16x32_bf16 v[44:47], v[170:173], v[178:181], 0
	v_mfma_f32_16x16x32_bf16 v[36:39], v[162:165], v[198:201], 0
	v_mfma_f32_16x16x32_bf16 v[28:31], v[170:173], v[198:201], 0
	v_mfma_f32_16x16x32_bf16 v[20:23], v[162:165], v[206:209], 0
	v_mfma_f32_16x16x32_bf16 v[12:15], v[170:173], v[206:209], 0
	v_mfma_f32_16x16x32_bf16 v[4:7], v[162:165], v[214:217], 0
	v_mfma_f32_16x16x32_bf16 v[0:3], v[170:173], v[214:217], 0
	v_mfma_f32_16x16x32_bf16 v[52:55], v[166:169], v[194:197], v[52:55]
	v_mfma_f32_16x16x32_bf16 v[44:47], v[174:177], v[194:197], v[44:47]
	v_mfma_f32_16x16x32_bf16 v[36:39], v[166:169], v[202:205], v[36:39]
	v_mfma_f32_16x16x32_bf16 v[28:31], v[174:177], v[202:205], v[28:31]
	v_mfma_f32_16x16x32_bf16 v[20:23], v[166:169], v[210:213], v[20:23]
	v_mfma_f32_16x16x32_bf16 v[12:15], v[174:177], v[210:213], v[12:15]
	v_mfma_f32_16x16x32_bf16 v[4:7], v[166:169], v[218:221], v[4:7]
	v_mfma_f32_16x16x32_bf16 v[0:3], v[174:177], v[218:221], v[0:3]
	s_setprio 0
	s_barrier
	s_add_i32 s14, 0, 0x18000
	v_add_u32_e32 v137, s14, v149
	s_add_i32 s15, 0, 0x1c000
	ds_read_b128 v[138:141], v137
	ds_read_b128 v[142:145], v137 offset:1024
	ds_read_b128 v[154:157], v137 offset:2048
	ds_read_b128 v[158:161], v137 offset:3072
	v_add_u32_e32 v137, s15, v149
	ds_read_b128 v[162:165], v137
	ds_read_b128 v[166:169], v137 offset:1024
	ds_read_b128 v[170:173], v137 offset:2048
	ds_read_b128 v[174:177], v137 offset:3072
	s_mov_b32 m0, s27
	v_lshl_add_u64 v[186:187], v[182:183], 0, s[92:93]
	ds_read_b128 v[178:181], v153 offset:32768
	ds_read_b128 v[194:197], v153 offset:33792
	ds_read_b128 v[198:201], v153 offset:34816
	ds_read_b128 v[202:205], v153 offset:35840
	ds_read_b128 v[206:209], v153 offset:36864
	ds_read_b128 v[210:213], v153 offset:37888
	ds_read_b128 v[214:217], v153 offset:38912
	ds_read_b128 v[218:221], v153 offset:39936
	global_load_lds_dwordx4 v[186:187], off
	v_lshl_add_u64 v[186:187], v[182:183], 0, s[52:53]
	s_mov_b32 m0, s28
	s_nop 0
	global_load_lds_dwordx4 v[186:187], off
	s_waitcnt vmcnt(10)
	s_waitcnt lgkmcnt(0)
	s_barrier
	s_setprio 1
	s_waitcnt lgkmcnt(0)
	v_mfma_f32_16x16x32_bf16 v[124:127], v[138:141], v[178:181], v[124:127]
	v_mfma_f32_16x16x32_bf16 v[120:123], v[154:157], v[178:181], v[120:123]
	v_mfma_f32_16x16x32_bf16 v[108:111], v[138:141], v[198:201], v[108:111]
	v_mfma_f32_16x16x32_bf16 v[104:107], v[154:157], v[198:201], v[104:107]
	v_mfma_f32_16x16x32_bf16 v[96:99], v[138:141], v[206:209], v[96:99]
	v_mfma_f32_16x16x32_bf16 v[88:91], v[154:157], v[206:209], v[88:91]
	v_mfma_f32_16x16x32_bf16 v[80:83], v[138:141], v[214:217], v[80:83]
	v_mfma_f32_16x16x32_bf16 v[72:75], v[154:157], v[214:217], v[72:75]
	v_mfma_f32_16x16x32_bf16 v[124:127], v[142:145], v[194:197], v[124:127]
	v_mfma_f32_16x16x32_bf16 v[120:123], v[158:161], v[194:197], v[120:123]
	v_mfma_f32_16x16x32_bf16 v[108:111], v[142:145], v[202:205], v[108:111]
	v_mfma_f32_16x16x32_bf16 v[104:107], v[158:161], v[202:205], v[104:107]
	v_mfma_f32_16x16x32_bf16 v[96:99], v[142:145], v[210:213], v[96:99]
	v_mfma_f32_16x16x32_bf16 v[88:91], v[158:161], v[210:213], v[88:91]
	v_mfma_f32_16x16x32_bf16 v[80:83], v[142:145], v[218:221], v[80:83]
	v_mfma_f32_16x16x32_bf16 v[72:75], v[158:161], v[218:221], v[72:75]
	s_setprio 0
	s_setprio 1
	v_mfma_f32_16x16x32_bf16 v[116:119], v[162:165], v[178:181], v[116:119]
	v_mfma_f32_16x16x32_bf16 v[112:115], v[170:173], v[178:181], v[112:115]
	v_mfma_f32_16x16x32_bf16 v[100:103], v[162:165], v[198:201], v[100:103]
	v_mfma_f32_16x16x32_bf16 v[92:95], v[170:173], v[198:201], v[92:95]
	v_mfma_f32_16x16x32_bf16 v[84:87], v[162:165], v[206:209], v[84:87]
	v_mfma_f32_16x16x32_bf16 v[76:79], v[170:173], v[206:209], v[76:79]
	v_mfma_f32_16x16x32_bf16 v[68:71], v[162:165], v[214:217], v[68:71]
	v_mfma_f32_16x16x32_bf16 v[64:67], v[170:173], v[214:217], v[64:67]
	v_mfma_f32_16x16x32_bf16 v[116:119], v[166:169], v[194:197], v[116:119]
	v_mfma_f32_16x16x32_bf16 v[112:115], v[174:177], v[194:197], v[112:115]
	v_mfma_f32_16x16x32_bf16 v[100:103], v[166:169], v[202:205], v[100:103]
	v_mfma_f32_16x16x32_bf16 v[92:95], v[174:177], v[202:205], v[92:95]
	v_mfma_f32_16x16x32_bf16 v[84:87], v[166:169], v[210:213], v[84:87]
	v_mfma_f32_16x16x32_bf16 v[76:79], v[174:177], v[210:213], v[76:79]
	v_mfma_f32_16x16x32_bf16 v[68:71], v[166:169], v[218:221], v[68:71]
	v_mfma_f32_16x16x32_bf16 v[64:67], v[174:177], v[218:221], v[64:67]
	s_setprio 0
	s_barrier
	s_add_i32 s14, s14, s23
	v_lshl_add_u64 v[186:187], v[146:147], 0, s[56:57]
	s_mov_b32 m0, s14
	ds_read_b128 v[178:181], v153 offset:49152
	ds_read_b128 v[194:197], v153 offset:50176
	ds_read_b128 v[198:201], v153 offset:51200
	ds_read_b128 v[202:205], v153 offset:52224
	ds_read_b128 v[206:209], v153 offset:53248
	ds_read_b128 v[210:213], v153 offset:54272
	ds_read_b128 v[214:217], v153 offset:55296
	ds_read_b128 v[218:221], v153 offset:56320
	global_load_lds_dwordx4 v[186:187], off
	v_lshl_add_u64 v[186:187], v[146:147], 0, s[96:97]
	s_add_i32 m0, s14, 0x2000
	s_add_i32 s14, s15, s23
	global_load_lds_dwordx4 v[186:187], off
	v_lshl_add_u64 v[186:187], v[146:147], 0, s[88:89]
	s_mov_b32 m0, s14
	v_lshl_add_u64 v[146:147], v[146:147], 0, s[68:69]
	global_load_lds_dwordx4 v[186:187], off
	s_add_i32 m0, s14, 0x2000
	s_nop 0
	global_load_lds_dwordx4 v[146:147], off
	v_lshl_add_u64 v[146:147], v[182:183], 0, s[56:57]
	s_mov_b32 m0, s29
	s_nop 0
	global_load_lds_dwordx4 v[146:147], off
	v_lshl_add_u64 v[146:147], v[182:183], 0, s[96:97]
	s_mov_b32 m0, s30
	s_nop 0
	global_load_lds_dwordx4 v[146:147], off
	s_waitcnt vmcnt(14)
	s_waitcnt lgkmcnt(0)
	s_barrier
	s_setprio 1
	s_waitcnt lgkmcnt(0)
	v_mfma_f32_16x16x32_bf16 v[60:63], v[138:141], v[178:181], v[60:63]
	v_mfma_f32_16x16x32_bf16 v[56:59], v[154:157], v[178:181], v[56:59]
	v_mfma_f32_16x16x32_bf16 v[48:51], v[138:141], v[198:201], v[48:51]
	v_mfma_f32_16x16x32_bf16 v[40:43], v[154:157], v[198:201], v[40:43]
	v_mfma_f32_16x16x32_bf16 v[32:35], v[138:141], v[206:209], v[32:35]
	v_mfma_f32_16x16x32_bf16 v[24:27], v[154:157], v[206:209], v[24:27]
	v_mfma_f32_16x16x32_bf16 v[16:19], v[138:141], v[214:217], v[16:19]
	v_mfma_f32_16x16x32_bf16 v[8:11], v[154:157], v[214:217], v[8:11]
	v_mfma_f32_16x16x32_bf16 v[60:63], v[142:145], v[194:197], v[60:63]
	v_mfma_f32_16x16x32_bf16 v[56:59], v[158:161], v[194:197], v[56:59]
	v_mfma_f32_16x16x32_bf16 v[48:51], v[142:145], v[202:205], v[48:51]
	v_mfma_f32_16x16x32_bf16 v[40:43], v[158:161], v[202:205], v[40:43]
	v_mfma_f32_16x16x32_bf16 v[32:35], v[142:145], v[210:213], v[32:35]
	v_mfma_f32_16x16x32_bf16 v[24:27], v[158:161], v[210:213], v[24:27]
	v_mfma_f32_16x16x32_bf16 v[16:19], v[142:145], v[218:221], v[16:19]
	v_mfma_f32_16x16x32_bf16 v[8:11], v[158:161], v[218:221], v[8:11]
	s_setprio 0
	s_setprio 1
	v_mfma_f32_16x16x32_bf16 v[52:55], v[162:165], v[178:181], v[52:55]
	v_mfma_f32_16x16x32_bf16 v[44:47], v[170:173], v[178:181], v[44:47]
	v_mfma_f32_16x16x32_bf16 v[36:39], v[162:165], v[198:201], v[36:39]
	v_mfma_f32_16x16x32_bf16 v[28:31], v[170:173], v[198:201], v[28:31]
	v_mfma_f32_16x16x32_bf16 v[20:23], v[162:165], v[206:209], v[20:23]
	v_mfma_f32_16x16x32_bf16 v[12:15], v[170:173], v[206:209], v[12:15]
	v_mfma_f32_16x16x32_bf16 v[4:7], v[162:165], v[214:217], v[4:7]
	v_mfma_f32_16x16x32_bf16 v[0:3], v[170:173], v[214:217], v[0:3]
	v_mfma_f32_16x16x32_bf16 v[52:55], v[166:169], v[194:197], v[52:55]
	v_mfma_f32_16x16x32_bf16 v[44:47], v[174:177], v[194:197], v[44:47]
	v_mfma_f32_16x16x32_bf16 v[36:39], v[166:169], v[202:205], v[36:39]
	v_mfma_f32_16x16x32_bf16 v[28:31], v[174:177], v[202:205], v[28:31]
	v_mfma_f32_16x16x32_bf16 v[20:23], v[166:169], v[210:213], v[20:23]
	v_mfma_f32_16x16x32_bf16 v[12:15], v[174:177], v[210:213], v[12:15]
	v_mfma_f32_16x16x32_bf16 v[4:7], v[166:169], v[218:221], v[4:7]
	v_mfma_f32_16x16x32_bf16 v[0:3], v[174:177], v[218:221], v[0:3]
	s_setprio 0
	s_barrier
	s_add_i32 s85, s85, 2
	s_add_u32 s60, s60, 0x100
	s_addc_u32 s61, s61, 0
	s_add_u32 s16, s16, 0x100
	s_addc_u32 s17, s17, 0
	s_cmp_gt_u32 s85, 13
.LBB0_249:
	s_add_u32 s14, s60, 0xfffc0080
	s_addc_u32 s15, s61, -1
	s_add_i32 s18, 0, 0x10000
	s_cmp_eq_u32 s85, 12
	s_cselect_b32 s15, s22, s15
	s_cselect_b32 s14, s45, s14
	s_waitcnt lgkmcnt(0)
	v_add_u32_e32 v137, s18, v149
	s_cselect_b32 vcc_hi, s43, s17
	s_cselect_b32 vcc_lo, s84, s16
	s_add_i32 s21, 0, 0x14000
	ds_read_b128 v[138:141], v137
	ds_read_b128 v[142:145], v137 offset:1024
	ds_read_b128 v[154:157], v137 offset:2048
	ds_read_b128 v[158:161], v137 offset:3072
	v_add_u32_e32 v137, s21, v149
	ds_read_b128 v[162:165], v137
	ds_read_b128 v[166:169], v137 offset:1024
	ds_read_b128 v[170:173], v137 offset:2048
	ds_read_b128 v[174:177], v137 offset:3072
	v_lshl_add_u64 v[146:147], s[60:61], 0, v[134:135]
	s_add_i32 m0, s25, 0xc000
	ds_read_b128 v[178:181], v153
	ds_read_b128 v[194:197], v153 offset:1024
	ds_read_b128 v[198:201], v153 offset:2048
	ds_read_b128 v[202:205], v153 offset:3072
	ds_read_b128 v[206:209], v153 offset:4096
	ds_read_b128 v[210:213], v153 offset:5120
	ds_read_b128 v[214:217], v153 offset:6144
	ds_read_b128 v[218:221], v153 offset:7168
	global_load_lds_dwordx4 v[146:147], off
	v_lshl_add_u64 v[146:147], v[146:147], 0, s[34:35]
	s_add_i32 m0, s25, 0xe000
	s_nop 0
	global_load_lds_dwordx4 v[146:147], off
	s_waitcnt vmcnt(10)
	s_waitcnt lgkmcnt(0)
	s_barrier
	s_setprio 1
	s_waitcnt lgkmcnt(0)
	v_mfma_f32_16x16x32_bf16 v[124:127], v[138:141], v[178:181], v[124:127]
	v_mfma_f32_16x16x32_bf16 v[120:123], v[154:157], v[178:181], v[120:123]
	v_mfma_f32_16x16x32_bf16 v[108:111], v[138:141], v[198:201], v[108:111]
	v_mfma_f32_16x16x32_bf16 v[104:107], v[154:157], v[198:201], v[104:107]
	v_mfma_f32_16x16x32_bf16 v[96:99], v[138:141], v[206:209], v[96:99]
	v_mfma_f32_16x16x32_bf16 v[88:91], v[154:157], v[206:209], v[88:91]
	v_mfma_f32_16x16x32_bf16 v[80:83], v[138:141], v[214:217], v[80:83]
	v_mfma_f32_16x16x32_bf16 v[72:75], v[154:157], v[214:217], v[72:75]
	v_mfma_f32_16x16x32_bf16 v[124:127], v[142:145], v[194:197], v[124:127]
	v_mfma_f32_16x16x32_bf16 v[120:123], v[158:161], v[194:197], v[120:123]
	v_mfma_f32_16x16x32_bf16 v[108:111], v[142:145], v[202:205], v[108:111]
	v_mfma_f32_16x16x32_bf16 v[104:107], v[158:161], v[202:205], v[104:107]
	v_mfma_f32_16x16x32_bf16 v[96:99], v[142:145], v[210:213], v[96:99]
	v_mfma_f32_16x16x32_bf16 v[88:91], v[158:161], v[210:213], v[88:91]
	v_mfma_f32_16x16x32_bf16 v[80:83], v[142:145], v[218:221], v[80:83]
	v_mfma_f32_16x16x32_bf16 v[72:75], v[158:161], v[218:221], v[72:75]
	s_setprio 0
	s_setprio 1
	v_mfma_f32_16x16x32_bf16 v[116:119], v[162:165], v[178:181], v[116:119]
	v_mfma_f32_16x16x32_bf16 v[112:115], v[170:173], v[178:181], v[112:115]
	v_mfma_f32_16x16x32_bf16 v[100:103], v[162:165], v[198:201], v[100:103]
	v_mfma_f32_16x16x32_bf16 v[92:95], v[170:173], v[198:201], v[92:95]
	v_mfma_f32_16x16x32_bf16 v[84:87], v[162:165], v[206:209], v[84:87]
	v_mfma_f32_16x16x32_bf16 v[76:79], v[170:173], v[206:209], v[76:79]
	v_mfma_f32_16x16x32_bf16 v[68:71], v[162:165], v[214:217], v[68:71]
	v_mfma_f32_16x16x32_bf16 v[64:67], v[170:173], v[214:217], v[64:67]
	v_mfma_f32_16x16x32_bf16 v[116:119], v[166:169], v[194:197], v[116:119]
	v_mfma_f32_16x16x32_bf16 v[112:115], v[174:177], v[194:197], v[112:115]
	v_mfma_f32_16x16x32_bf16 v[100:103], v[166:169], v[202:205], v[100:103]
	v_mfma_f32_16x16x32_bf16 v[92:95], v[174:177], v[202:205], v[92:95]
	v_mfma_f32_16x16x32_bf16 v[84:87], v[166:169], v[210:213], v[84:87]
	v_mfma_f32_16x16x32_bf16 v[76:79], v[174:177], v[210:213], v[76:79]
	v_mfma_f32_16x16x32_bf16 v[68:71], v[166:169], v[218:221], v[68:71]
	v_mfma_f32_16x16x32_bf16 v[64:67], v[174:177], v[218:221], v[64:67]
	s_setprio 0
	s_barrier
	s_add_i32 s18, s18, s23
	v_lshl_add_u64 v[146:147], vcc, 0, v[128:129]
	s_mov_b32 m0, s18
	ds_read_b128 v[178:181], v153 offset:16384
	ds_read_b128 v[194:197], v153 offset:17408
	ds_read_b128 v[198:201], v153 offset:18432
	ds_read_b128 v[202:205], v153 offset:19456
	ds_read_b128 v[206:209], v153 offset:20480
	ds_read_b128 v[210:213], v153 offset:21504
	ds_read_b128 v[214:217], v153 offset:22528
	ds_read_b128 v[218:221], v153 offset:23552
	global_load_lds_dwordx4 v[146:147], off
	v_lshl_add_u64 v[182:183], v[146:147], 0, s[34:35]
	s_add_i32 m0, s18, 0x2000
	s_add_i32 s18, s21, s23
	global_load_lds_dwordx4 v[182:183], off
	v_lshl_add_u64 v[182:183], v[146:147], 0, s[92:93]
	s_mov_b32 m0, s18
	s_nop 0
	global_load_lds_dwordx4 v[182:183], off
	v_lshl_add_u64 v[182:183], v[146:147], 0, s[52:53]
	s_add_i32 m0, s18, 0x2000
	s_nop 0
	global_load_lds_dwordx4 v[182:183], off
	v_lshl_add_u64 v[182:183], s[14:15], 0, v[130:131]
	s_mov_b32 m0, s25
	v_lshl_add_u64 v[186:187], v[182:183], 0, s[34:35]
	global_load_lds_dwordx4 v[182:183], off
	s_mov_b32 m0, s26
	s_nop 0
	global_load_lds_dwordx4 v[186:187], off
	s_waitcnt vmcnt(14)
	s_waitcnt lgkmcnt(0)
	s_barrier
	s_setprio 1
	s_waitcnt lgkmcnt(0)
	v_mfma_f32_16x16x32_bf16 v[60:63], v[138:141], v[178:181], v[60:63]
	v_mfma_f32_16x16x32_bf16 v[56:59], v[154:157], v[178:181], v[56:59]
	v_mfma_f32_16x16x32_bf16 v[48:51], v[138:141], v[198:201], v[48:51]
	v_mfma_f32_16x16x32_bf16 v[40:43], v[154:157], v[198:201], v[40:43]
	v_mfma_f32_16x16x32_bf16 v[32:35], v[138:141], v[206:209], v[32:35]
	v_mfma_f32_16x16x32_bf16 v[24:27], v[154:157], v[206:209], v[24:27]
	v_mfma_f32_16x16x32_bf16 v[16:19], v[138:141], v[214:217], v[16:19]
	v_mfma_f32_16x16x32_bf16 v[8:11], v[154:157], v[214:217], v[8:11]
	v_mfma_f32_16x16x32_bf16 v[60:63], v[142:145], v[194:197], v[60:63]
	v_mfma_f32_16x16x32_bf16 v[56:59], v[158:161], v[194:197], v[56:59]
	v_mfma_f32_16x16x32_bf16 v[48:51], v[142:145], v[202:205], v[48:51]
	v_mfma_f32_16x16x32_bf16 v[40:43], v[158:161], v[202:205], v[40:43]
	v_mfma_f32_16x16x32_bf16 v[32:35], v[142:145], v[210:213], v[32:35]
	v_mfma_f32_16x16x32_bf16 v[24:27], v[158:161], v[210:213], v[24:27]
	v_mfma_f32_16x16x32_bf16 v[16:19], v[142:145], v[218:221], v[16:19]
	v_mfma_f32_16x16x32_bf16 v[8:11], v[158:161], v[218:221], v[8:11]
	s_setprio 0
	s_setprio 1
	v_mfma_f32_16x16x32_bf16 v[52:55], v[162:165], v[178:181], v[52:55]
	v_mfma_f32_16x16x32_bf16 v[44:47], v[170:173], v[178:181], v[44:47]
	v_mfma_f32_16x16x32_bf16 v[36:39], v[162:165], v[198:201], v[36:39]
	v_mfma_f32_16x16x32_bf16 v[28:31], v[170:173], v[198:201], v[28:31]
	v_mfma_f32_16x16x32_bf16 v[20:23], v[162:165], v[206:209], v[20:23]
	v_mfma_f32_16x16x32_bf16 v[12:15], v[170:173], v[206:209], v[12:15]
	v_mfma_f32_16x16x32_bf16 v[4:7], v[162:165], v[214:217], v[4:7]
	v_mfma_f32_16x16x32_bf16 v[0:3], v[170:173], v[214:217], v[0:3]
	v_mfma_f32_16x16x32_bf16 v[52:55], v[166:169], v[194:197], v[52:55]
	v_mfma_f32_16x16x32_bf16 v[44:47], v[174:177], v[194:197], v[44:47]
	v_mfma_f32_16x16x32_bf16 v[36:39], v[166:169], v[202:205], v[36:39]
	v_mfma_f32_16x16x32_bf16 v[28:31], v[174:177], v[202:205], v[28:31]
	v_mfma_f32_16x16x32_bf16 v[20:23], v[166:169], v[210:213], v[20:23]
	v_mfma_f32_16x16x32_bf16 v[12:15], v[174:177], v[210:213], v[12:15]
	v_mfma_f32_16x16x32_bf16 v[4:7], v[166:169], v[218:221], v[4:7]
	v_mfma_f32_16x16x32_bf16 v[0:3], v[174:177], v[218:221], v[0:3]
	s_setprio 0
	s_barrier
	s_add_i32 s14, 0, 0x18000
	v_add_u32_e32 v137, s14, v149
	s_add_i32 s15, 0, 0x1c000
	ds_read_b128 v[138:141], v137
	ds_read_b128 v[142:145], v137 offset:1024
	ds_read_b128 v[154:157], v137 offset:2048
	ds_read_b128 v[158:161], v137 offset:3072
	v_add_u32_e32 v137, s15, v149
	ds_read_b128 v[162:165], v137
	ds_read_b128 v[166:169], v137 offset:1024
	ds_read_b128 v[170:173], v137 offset:2048
	ds_read_b128 v[174:177], v137 offset:3072
	s_mov_b32 m0, s27
	v_lshl_add_u64 v[186:187], v[182:183], 0, s[92:93]
	ds_read_b128 v[178:181], v153 offset:32768
	ds_read_b128 v[194:197], v153 offset:33792
	ds_read_b128 v[198:201], v153 offset:34816
	ds_read_b128 v[202:205], v153 offset:35840
	ds_read_b128 v[206:209], v153 offset:36864
	ds_read_b128 v[210:213], v153 offset:37888
	ds_read_b128 v[214:217], v153 offset:38912
	ds_read_b128 v[218:221], v153 offset:39936
	global_load_lds_dwordx4 v[186:187], off
	v_lshl_add_u64 v[186:187], v[182:183], 0, s[52:53]
	s_mov_b32 m0, s28
	s_nop 0
	global_load_lds_dwordx4 v[186:187], off
	s_waitcnt vmcnt(10)
	s_waitcnt lgkmcnt(0)
	s_barrier
	s_setprio 1
	s_waitcnt lgkmcnt(0)
	v_mfma_f32_16x16x32_bf16 v[124:127], v[138:141], v[178:181], v[124:127]
	v_mfma_f32_16x16x32_bf16 v[120:123], v[154:157], v[178:181], v[120:123]
	v_mfma_f32_16x16x32_bf16 v[108:111], v[138:141], v[198:201], v[108:111]
	v_mfma_f32_16x16x32_bf16 v[104:107], v[154:157], v[198:201], v[104:107]
	v_mfma_f32_16x16x32_bf16 v[96:99], v[138:141], v[206:209], v[96:99]
	v_mfma_f32_16x16x32_bf16 v[88:91], v[154:157], v[206:209], v[88:91]
	v_mfma_f32_16x16x32_bf16 v[80:83], v[138:141], v[214:217], v[80:83]
	v_mfma_f32_16x16x32_bf16 v[72:75], v[154:157], v[214:217], v[72:75]
	v_mfma_f32_16x16x32_bf16 v[124:127], v[142:145], v[194:197], v[124:127]
	v_mfma_f32_16x16x32_bf16 v[120:123], v[158:161], v[194:197], v[120:123]
	v_mfma_f32_16x16x32_bf16 v[108:111], v[142:145], v[202:205], v[108:111]
	v_mfma_f32_16x16x32_bf16 v[104:107], v[158:161], v[202:205], v[104:107]
	v_mfma_f32_16x16x32_bf16 v[96:99], v[142:145], v[210:213], v[96:99]
	v_mfma_f32_16x16x32_bf16 v[88:91], v[158:161], v[210:213], v[88:91]
	v_mfma_f32_16x16x32_bf16 v[80:83], v[142:145], v[218:221], v[80:83]
	v_mfma_f32_16x16x32_bf16 v[72:75], v[158:161], v[218:221], v[72:75]
	s_setprio 0
	s_setprio 1
	v_mfma_f32_16x16x32_bf16 v[116:119], v[162:165], v[178:181], v[116:119]
	v_mfma_f32_16x16x32_bf16 v[112:115], v[170:173], v[178:181], v[112:115]
	v_mfma_f32_16x16x32_bf16 v[100:103], v[162:165], v[198:201], v[100:103]
	v_mfma_f32_16x16x32_bf16 v[92:95], v[170:173], v[198:201], v[92:95]
	v_mfma_f32_16x16x32_bf16 v[84:87], v[162:165], v[206:209], v[84:87]
	v_mfma_f32_16x16x32_bf16 v[76:79], v[170:173], v[206:209], v[76:79]
	v_mfma_f32_16x16x32_bf16 v[68:71], v[162:165], v[214:217], v[68:71]
	v_mfma_f32_16x16x32_bf16 v[64:67], v[170:173], v[214:217], v[64:67]
	v_mfma_f32_16x16x32_bf16 v[116:119], v[166:169], v[194:197], v[116:119]
	v_mfma_f32_16x16x32_bf16 v[112:115], v[174:177], v[194:197], v[112:115]
	v_mfma_f32_16x16x32_bf16 v[100:103], v[166:169], v[202:205], v[100:103]
	v_mfma_f32_16x16x32_bf16 v[92:95], v[174:177], v[202:205], v[92:95]
	v_mfma_f32_16x16x32_bf16 v[84:87], v[166:169], v[210:213], v[84:87]
	v_mfma_f32_16x16x32_bf16 v[76:79], v[174:177], v[210:213], v[76:79]
	v_mfma_f32_16x16x32_bf16 v[68:71], v[166:169], v[218:221], v[68:71]
	v_mfma_f32_16x16x32_bf16 v[64:67], v[174:177], v[218:221], v[64:67]
	s_setprio 0
	s_barrier
	s_add_i32 s14, s14, s23
	v_lshl_add_u64 v[186:187], v[146:147], 0, s[56:57]
	s_mov_b32 m0, s14
	ds_read_b128 v[178:181], v153 offset:49152
	ds_read_b128 v[194:197], v153 offset:50176
	ds_read_b128 v[198:201], v153 offset:51200
	ds_read_b128 v[202:205], v153 offset:52224
	ds_read_b128 v[206:209], v153 offset:53248
	ds_read_b128 v[210:213], v153 offset:54272
	ds_read_b128 v[214:217], v153 offset:55296
	ds_read_b128 v[218:221], v153 offset:56320
	global_load_lds_dwordx4 v[186:187], off
	v_lshl_add_u64 v[186:187], v[146:147], 0, s[96:97]
	s_add_i32 m0, s14, 0x2000
	s_add_i32 s14, s15, s23
	global_load_lds_dwordx4 v[186:187], off
	v_lshl_add_u64 v[186:187], v[146:147], 0, s[88:89]
	s_mov_b32 m0, s14
	v_lshl_add_u64 v[146:147], v[146:147], 0, s[68:69]
	global_load_lds_dwordx4 v[186:187], off
	s_add_i32 m0, s14, 0x2000
	s_nop 0
	global_load_lds_dwordx4 v[146:147], off
	v_lshl_add_u64 v[146:147], v[182:183], 0, s[56:57]
	s_mov_b32 m0, s29
	s_nop 0
	global_load_lds_dwordx4 v[146:147], off
	v_lshl_add_u64 v[146:147], v[182:183], 0, s[96:97]
	s_mov_b32 m0, s30
	s_nop 0
	global_load_lds_dwordx4 v[146:147], off
	s_waitcnt vmcnt(14)
	s_waitcnt lgkmcnt(0)
	s_barrier
	s_setprio 1
	s_waitcnt lgkmcnt(0)
	v_mfma_f32_16x16x32_bf16 v[60:63], v[138:141], v[178:181], v[60:63]
	v_mfma_f32_16x16x32_bf16 v[56:59], v[154:157], v[178:181], v[56:59]
	v_mfma_f32_16x16x32_bf16 v[48:51], v[138:141], v[198:201], v[48:51]
	v_mfma_f32_16x16x32_bf16 v[40:43], v[154:157], v[198:201], v[40:43]
	v_mfma_f32_16x16x32_bf16 v[32:35], v[138:141], v[206:209], v[32:35]
	v_mfma_f32_16x16x32_bf16 v[24:27], v[154:157], v[206:209], v[24:27]
	v_mfma_f32_16x16x32_bf16 v[16:19], v[138:141], v[214:217], v[16:19]
	v_mfma_f32_16x16x32_bf16 v[8:11], v[154:157], v[214:217], v[8:11]
	v_mfma_f32_16x16x32_bf16 v[60:63], v[142:145], v[194:197], v[60:63]
	v_mfma_f32_16x16x32_bf16 v[56:59], v[158:161], v[194:197], v[56:59]
	v_mfma_f32_16x16x32_bf16 v[48:51], v[142:145], v[202:205], v[48:51]
	v_mfma_f32_16x16x32_bf16 v[40:43], v[158:161], v[202:205], v[40:43]
	v_mfma_f32_16x16x32_bf16 v[32:35], v[142:145], v[210:213], v[32:35]
	v_mfma_f32_16x16x32_bf16 v[24:27], v[158:161], v[210:213], v[24:27]
	v_mfma_f32_16x16x32_bf16 v[16:19], v[142:145], v[218:221], v[16:19]
	v_mfma_f32_16x16x32_bf16 v[8:11], v[158:161], v[218:221], v[8:11]
	s_setprio 0
	s_setprio 1
	v_mfma_f32_16x16x32_bf16 v[52:55], v[162:165], v[178:181], v[52:55]
	v_mfma_f32_16x16x32_bf16 v[44:47], v[170:173], v[178:181], v[44:47]
	v_mfma_f32_16x16x32_bf16 v[36:39], v[162:165], v[198:201], v[36:39]
	v_mfma_f32_16x16x32_bf16 v[28:31], v[170:173], v[198:201], v[28:31]
	v_mfma_f32_16x16x32_bf16 v[20:23], v[162:165], v[206:209], v[20:23]
	v_mfma_f32_16x16x32_bf16 v[12:15], v[170:173], v[206:209], v[12:15]
	v_mfma_f32_16x16x32_bf16 v[4:7], v[162:165], v[214:217], v[4:7]
	v_mfma_f32_16x16x32_bf16 v[0:3], v[170:173], v[214:217], v[0:3]
	v_mfma_f32_16x16x32_bf16 v[52:55], v[166:169], v[194:197], v[52:55]
	v_mfma_f32_16x16x32_bf16 v[44:47], v[174:177], v[194:197], v[44:47]
	v_mfma_f32_16x16x32_bf16 v[36:39], v[166:169], v[202:205], v[36:39]
	v_mfma_f32_16x16x32_bf16 v[28:31], v[174:177], v[202:205], v[28:31]
	v_mfma_f32_16x16x32_bf16 v[20:23], v[166:169], v[210:213], v[20:23]
	v_mfma_f32_16x16x32_bf16 v[12:15], v[174:177], v[210:213], v[12:15]
	v_mfma_f32_16x16x32_bf16 v[4:7], v[166:169], v[218:221], v[4:7]
	v_mfma_f32_16x16x32_bf16 v[0:3], v[174:177], v[218:221], v[0:3]
	s_setprio 0
	s_barrier
	s_add_i32 s85, s85, 2
	s_add_u32 s60, s60, 0x100
	s_addc_u32 s61, s61, 0
	s_add_u32 s16, s16, 0x100
	s_addc_u32 s17, s17, 0
	s_cmp_gt_u32 s85, 13
	s_cbranch_scc0 .LBB0_249
	s_and_b64 vcc, exec, s[40:41]
	s_cbranch_vccz .LBB0_252
	s_barrier

.Lnostb3:
	s_add_u32 s14, s50, 0xfffa8080
	s_addc_u32 s15, s51, -1
	s_add_i32 s22, 0, 0x10000
	s_cmp_eq_u32 s85, 18
	s_cselect_b32 s15, s1, s15
	s_cselect_b32 s14, s0, s14
	s_cselect_b32 s17, s49, s84
	s_cselect_b32 s16, s48, s70
	s_add_i32 s23, 0, 0x14000
	v_add_u32_e32 v0, s22, v221
	v_add_u32_e32 v4, s23, v221
	ds_read_b128 v[24:27], v0
	ds_read_b128 v[28:31], v0 offset:1024
	ds_read_b128 v[16:19], v0 offset:2048
	ds_read_b128 v[20:23], v0 offset:3072
	ds_read_b128 v[8:11], v4
	ds_read_b128 v[12:15], v4 offset:1024
	ds_read_b128 v[0:3], v4 offset:2048
	ds_read_b128 v[4:7], v4 offset:3072
	v_lshl_add_u64 v[206:207], s[50:51], 0, v[196:197]
	s_add_i32 m0, s19, 0xc000
	ds_read_b128 v[160:163], v223
	ds_read_b128 v[164:167], v223 offset:1024
	ds_read_b128 v[168:171], v223 offset:2048
	ds_read_b128 v[172:175], v223 offset:3072
	ds_read_b128 v[176:179], v223 offset:4096
	ds_read_b128 v[180:183], v223 offset:5120
	ds_read_b128 v[198:201], v223 offset:6144
	ds_read_b128 v[202:205], v223 offset:7168
	global_load_lds_dwordx4 v[206:207], off
	v_lshl_add_u64 v[206:207], v[206:207], 0, vcc
	s_add_i32 m0, s19, 0xe000
	s_nop 0
	global_load_lds_dwordx4 v[206:207], off
	s_waitcnt vmcnt(10)
	s_waitcnt lgkmcnt(0)
	s_barrier
	s_setprio 1
	s_waitcnt lgkmcnt(0)
	v_mfma_scale_f32_16x16x128_f8f6f4 v[156:159], v[24:31], v[160:167], 0, v240, v240 op_sel_hi:[0,0,0]
	v_mfma_scale_f32_16x16x128_f8f6f4 v[152:155], v[16:23], v[160:167], 0, v240, v240 op_sel_hi:[0,0,0]
	v_mfma_scale_f32_16x16x128_f8f6f4 v[140:143], v[24:31], v[168:175], 0, v240, v240 op_sel_hi:[0,0,0]
	v_mfma_scale_f32_16x16x128_f8f6f4 v[136:139], v[16:23], v[168:175], 0, v240, v240 op_sel_hi:[0,0,0]
	v_mfma_scale_f32_16x16x128_f8f6f4 v[124:127], v[24:31], v[176:183], 0, v240, v240 op_sel_hi:[0,0,0]
	v_mfma_scale_f32_16x16x128_f8f6f4 v[120:123], v[16:23], v[176:183], 0, v240, v240 op_sel_hi:[0,0,0]
	v_mfma_scale_f32_16x16x128_f8f6f4 v[108:111], v[24:31], v[198:205], 0, v240, v240 op_sel_hi:[0,0,0]
	v_mfma_scale_f32_16x16x128_f8f6f4 v[104:107], v[16:23], v[198:205], 0, v240, v240 op_sel_hi:[0,0,0]
	s_setprio 0
	s_setprio 1
	v_mfma_scale_f32_16x16x128_f8f6f4 v[148:151], v[8:15], v[160:167], 0, v240, v240 op_sel_hi:[0,0,0]
	v_mfma_scale_f32_16x16x128_f8f6f4 v[144:147], v[0:7], v[160:167], 0, v240, v240 op_sel_hi:[0,0,0]
	v_mfma_scale_f32_16x16x128_f8f6f4 v[132:135], v[8:15], v[168:175], 0, v240, v240 op_sel_hi:[0,0,0]
	v_mfma_scale_f32_16x16x128_f8f6f4 v[128:131], v[0:7], v[168:175], 0, v240, v240 op_sel_hi:[0,0,0]
	v_mfma_scale_f32_16x16x128_f8f6f4 v[116:119], v[8:15], v[176:183], 0, v240, v240 op_sel_hi:[0,0,0]
	v_mfma_scale_f32_16x16x128_f8f6f4 v[112:115], v[0:7], v[176:183], 0, v240, v240 op_sel_hi:[0,0,0]
	v_mfma_scale_f32_16x16x128_f8f6f4 v[100:103], v[8:15], v[198:205], 0, v240, v240 op_sel_hi:[0,0,0]
	v_mfma_scale_f32_16x16x128_f8f6f4 v[96:99], v[0:7], v[198:205], 0, v240, v240 op_sel_hi:[0,0,0]
	s_setprio 0
	s_barrier
	v_lshl_add_u64 v[160:161], s[16:17], 0, v[184:185]
	s_add_i32 s16, s22, s6
	s_mov_b32 m0, s16
	ds_read_b128 v[164:167], v223 offset:16384
	ds_read_b128 v[168:171], v223 offset:17408
	ds_read_b128 v[172:175], v223 offset:18432
	ds_read_b128 v[176:179], v223 offset:19456
	ds_read_b128 v[198:201], v223 offset:20480
	ds_read_b128 v[202:205], v223 offset:21504
	ds_read_b128 v[206:209], v223 offset:22528
	ds_read_b128 v[210:213], v223 offset:23552
	global_load_lds_dwordx4 v[160:161], off
	v_lshl_add_u64 v[162:163], v[160:161], 0, vcc
	s_add_i32 m0, s16, 0x2000
	s_add_i32 s16, s23, s6
	global_load_lds_dwordx4 v[162:163], off
	v_lshl_add_u64 v[162:163], v[160:161], 0, s[2:3]
	s_mov_b32 m0, s16
	s_nop 0
	global_load_lds_dwordx4 v[162:163], off
	v_lshl_add_u64 v[162:163], v[160:161], 0, s[82:83]
	s_add_i32 m0, s16, 0x2000
	s_nop 0
	global_load_lds_dwordx4 v[162:163], off
	v_lshl_add_u64 v[162:163], s[14:15], 0, v[194:195]
	s_mov_b32 m0, s19
	v_lshl_add_u64 v[180:181], v[162:163], 0, vcc
	global_load_lds_dwordx4 v[162:163], off
	s_mov_b32 m0, s20
	s_nop 0
	global_load_lds_dwordx4 v[180:181], off
	s_waitcnt vmcnt(14)
	s_waitcnt lgkmcnt(0)
	s_barrier
	s_setprio 1
	s_waitcnt lgkmcnt(0)
	v_mfma_scale_f32_16x16x128_f8f6f4 v[92:95], v[24:31], v[164:171], 0, v240, v240 op_sel_hi:[0,0,0]
	v_mfma_scale_f32_16x16x128_f8f6f4 v[88:91], v[16:23], v[164:171], 0, v240, v240 op_sel_hi:[0,0,0]
	v_mfma_scale_f32_16x16x128_f8f6f4 v[76:79], v[24:31], v[172:179], 0, v240, v240 op_sel_hi:[0,0,0]
	v_mfma_scale_f32_16x16x128_f8f6f4 v[72:75], v[16:23], v[172:179], 0, v240, v240 op_sel_hi:[0,0,0]
	v_mfma_scale_f32_16x16x128_f8f6f4 v[60:63], v[24:31], v[198:205], 0, v240, v240 op_sel_hi:[0,0,0]
	v_mfma_scale_f32_16x16x128_f8f6f4 v[56:59], v[16:23], v[198:205], 0, v240, v240 op_sel_hi:[0,0,0]
	v_mfma_scale_f32_16x16x128_f8f6f4 v[44:47], v[24:31], v[206:213], 0, v240, v240 op_sel_hi:[0,0,0]
	v_mfma_scale_f32_16x16x128_f8f6f4 v[40:43], v[16:23], v[206:213], 0, v240, v240 op_sel_hi:[0,0,0]
	s_setprio 0
	s_setprio 1
	v_mfma_scale_f32_16x16x128_f8f6f4 v[84:87], v[8:15], v[164:171], 0, v240, v240 op_sel_hi:[0,0,0]
	v_mfma_scale_f32_16x16x128_f8f6f4 v[80:83], v[0:7], v[164:171], 0, v240, v240 op_sel_hi:[0,0,0]
	v_mfma_scale_f32_16x16x128_f8f6f4 v[68:71], v[8:15], v[172:179], 0, v240, v240 op_sel_hi:[0,0,0]
	v_mfma_scale_f32_16x16x128_f8f6f4 v[64:67], v[0:7], v[172:179], 0, v240, v240 op_sel_hi:[0,0,0]
	v_mfma_scale_f32_16x16x128_f8f6f4 v[52:55], v[8:15], v[198:205], 0, v240, v240 op_sel_hi:[0,0,0]
	v_mfma_scale_f32_16x16x128_f8f6f4 v[48:51], v[0:7], v[198:205], 0, v240, v240 op_sel_hi:[0,0,0]
	v_mfma_scale_f32_16x16x128_f8f6f4 v[36:39], v[8:15], v[206:213], 0, v240, v240 op_sel_hi:[0,0,0]
	v_mfma_scale_f32_16x16x128_f8f6f4 v[32:35], v[0:7], v[206:213], 0, v240, v240 op_sel_hi:[0,0,0]
	s_setprio 0
	s_barrier
	s_add_i32 s14, 0, 0x18000
	s_add_i32 s15, 0, 0x1c000
	v_add_u32_e32 v12, s14, v221
	v_add_u32_e32 v28, s15, v221
	ds_read_b128 v[0:3], v12
	ds_read_b128 v[4:7], v12 offset:1024
	ds_read_b128 v[8:11], v12 offset:2048
	ds_read_b128 v[12:15], v12 offset:3072
	ds_read_b128 v[16:19], v28
	ds_read_b128 v[20:23], v28 offset:1024
	ds_read_b128 v[24:27], v28 offset:2048
	ds_read_b128 v[28:31], v28 offset:3072
	s_mov_b32 m0, s25
	v_lshl_add_u64 v[180:181], v[162:163], 0, s[2:3]
	ds_read_b128 v[164:167], v223 offset:32768
	ds_read_b128 v[168:171], v223 offset:33792
	ds_read_b128 v[172:175], v223 offset:34816
	ds_read_b128 v[176:179], v223 offset:35840
	ds_read_b128 v[198:201], v223 offset:36864
	ds_read_b128 v[202:205], v223 offset:37888
	ds_read_b128 v[206:209], v223 offset:38912
	ds_read_b128 v[210:213], v223 offset:39936
	global_load_lds_dwordx4 v[180:181], off
	v_lshl_add_u64 v[180:181], v[162:163], 0, s[82:83]
	s_mov_b32 m0, s26
	s_nop 0
	global_load_lds_dwordx4 v[180:181], off
	s_waitcnt vmcnt(10)
	s_waitcnt lgkmcnt(0)
	s_barrier
	s_setprio 1
	s_waitcnt lgkmcnt(0)
	v_mfma_scale_f32_16x16x128_f8f6f4 v[156:159], v[0:7], v[164:171], v[156:159], v240, v240 op_sel_hi:[0,0,0]
	v_mfma_scale_f32_16x16x128_f8f6f4 v[152:155], v[8:15], v[164:171], v[152:155], v240, v240 op_sel_hi:[0,0,0]
	v_mfma_scale_f32_16x16x128_f8f6f4 v[140:143], v[0:7], v[172:179], v[140:143], v240, v240 op_sel_hi:[0,0,0]
	v_mfma_scale_f32_16x16x128_f8f6f4 v[136:139], v[8:15], v[172:179], v[136:139], v240, v240 op_sel_hi:[0,0,0]
	v_mfma_scale_f32_16x16x128_f8f6f4 v[124:127], v[0:7], v[198:205], v[124:127], v240, v240 op_sel_hi:[0,0,0]
	v_mfma_scale_f32_16x16x128_f8f6f4 v[120:123], v[8:15], v[198:205], v[120:123], v240, v240 op_sel_hi:[0,0,0]
	v_mfma_scale_f32_16x16x128_f8f6f4 v[108:111], v[0:7], v[206:213], v[108:111], v240, v240 op_sel_hi:[0,0,0]
	v_mfma_scale_f32_16x16x128_f8f6f4 v[104:107], v[8:15], v[206:213], v[104:107], v240, v240 op_sel_hi:[0,0,0]
	s_setprio 0
	s_setprio 1
	v_mfma_scale_f32_16x16x128_f8f6f4 v[148:151], v[16:23], v[164:171], v[148:151], v240, v240 op_sel_hi:[0,0,0]
	v_mfma_scale_f32_16x16x128_f8f6f4 v[144:147], v[24:31], v[164:171], v[144:147], v240, v240 op_sel_hi:[0,0,0]
	v_mfma_scale_f32_16x16x128_f8f6f4 v[132:135], v[16:23], v[172:179], v[132:135], v240, v240 op_sel_hi:[0,0,0]
	v_mfma_scale_f32_16x16x128_f8f6f4 v[128:131], v[24:31], v[172:179], v[128:131], v240, v240 op_sel_hi:[0,0,0]
	v_mfma_scale_f32_16x16x128_f8f6f4 v[116:119], v[16:23], v[198:205], v[116:119], v240, v240 op_sel_hi:[0,0,0]
	v_mfma_scale_f32_16x16x128_f8f6f4 v[112:115], v[24:31], v[198:205], v[112:115], v240, v240 op_sel_hi:[0,0,0]
	v_mfma_scale_f32_16x16x128_f8f6f4 v[100:103], v[16:23], v[206:213], v[100:103], v240, v240 op_sel_hi:[0,0,0]
	v_mfma_scale_f32_16x16x128_f8f6f4 v[96:99], v[24:31], v[206:213], v[96:99], v240, v240 op_sel_hi:[0,0,0]
	s_setprio 0
	s_barrier
	s_add_i32 s14, s14, s6
	v_lshl_add_u64 v[180:181], v[160:161], 0, s[56:57]
	s_mov_b32 m0, s14
	ds_read_b128 v[164:167], v223 offset:49152
	ds_read_b128 v[168:171], v223 offset:50176
	ds_read_b128 v[172:175], v223 offset:51200
	ds_read_b128 v[176:179], v223 offset:52224
	ds_read_b128 v[198:201], v223 offset:53248
	ds_read_b128 v[202:205], v223 offset:54272
	ds_read_b128 v[206:209], v223 offset:55296
	ds_read_b128 v[210:213], v223 offset:56320
	global_load_lds_dwordx4 v[180:181], off
	v_lshl_add_u64 v[180:181], v[160:161], 0, s[80:81]
	s_add_i32 m0, s14, 0x2000
	s_add_i32 s14, s15, s6
	global_load_lds_dwordx4 v[180:181], off
	v_lshl_add_u64 v[180:181], v[160:161], 0, s[74:75]
	s_mov_b32 m0, s14
	v_lshl_add_u64 v[160:161], v[160:161], 0, s[62:63]
	global_load_lds_dwordx4 v[180:181], off
	s_add_i32 m0, s14, 0x2000
	s_nop 0
	global_load_lds_dwordx4 v[160:161], off
	v_lshl_add_u64 v[160:161], v[162:163], 0, s[56:57]
	s_mov_b32 m0, s28
	s_nop 0
	global_load_lds_dwordx4 v[160:161], off
	v_lshl_add_u64 v[160:161], v[162:163], 0, s[80:81]
	s_mov_b32 m0, s29
	s_nop 0
	global_load_lds_dwordx4 v[160:161], off
	s_waitcnt vmcnt(14)
	s_waitcnt lgkmcnt(0)
	s_barrier
	s_setprio 1
	s_waitcnt lgkmcnt(0)
	v_mfma_scale_f32_16x16x128_f8f6f4 v[92:95], v[0:7], v[164:171], v[92:95], v240, v240 op_sel_hi:[0,0,0]
	v_mfma_scale_f32_16x16x128_f8f6f4 v[88:91], v[8:15], v[164:171], v[88:91], v240, v240 op_sel_hi:[0,0,0]
	v_mfma_scale_f32_16x16x128_f8f6f4 v[76:79], v[0:7], v[172:179], v[76:79], v240, v240 op_sel_hi:[0,0,0]
	v_mfma_scale_f32_16x16x128_f8f6f4 v[72:75], v[8:15], v[172:179], v[72:75], v240, v240 op_sel_hi:[0,0,0]
	v_mfma_scale_f32_16x16x128_f8f6f4 v[60:63], v[0:7], v[198:205], v[60:63], v240, v240 op_sel_hi:[0,0,0]
	v_mfma_scale_f32_16x16x128_f8f6f4 v[56:59], v[8:15], v[198:205], v[56:59], v240, v240 op_sel_hi:[0,0,0]
	v_mfma_scale_f32_16x16x128_f8f6f4 v[44:47], v[0:7], v[206:213], v[44:47], v240, v240 op_sel_hi:[0,0,0]
	v_mfma_scale_f32_16x16x128_f8f6f4 v[40:43], v[8:15], v[206:213], v[40:43], v240, v240 op_sel_hi:[0,0,0]
	s_setprio 0
	s_setprio 1
	v_mfma_scale_f32_16x16x128_f8f6f4 v[84:87], v[16:23], v[164:171], v[84:87], v240, v240 op_sel_hi:[0,0,0]
	v_mfma_scale_f32_16x16x128_f8f6f4 v[80:83], v[24:31], v[164:171], v[80:83], v240, v240 op_sel_hi:[0,0,0]
	v_mfma_scale_f32_16x16x128_f8f6f4 v[68:71], v[16:23], v[172:179], v[68:71], v240, v240 op_sel_hi:[0,0,0]
	v_mfma_scale_f32_16x16x128_f8f6f4 v[64:67], v[24:31], v[172:179], v[64:67], v240, v240 op_sel_hi:[0,0,0]
	v_mfma_scale_f32_16x16x128_f8f6f4 v[52:55], v[16:23], v[198:205], v[52:55], v240, v240 op_sel_hi:[0,0,0]
	v_mfma_scale_f32_16x16x128_f8f6f4 v[48:51], v[24:31], v[198:205], v[48:51], v240, v240 op_sel_hi:[0,0,0]
	v_mfma_scale_f32_16x16x128_f8f6f4 v[36:39], v[16:23], v[206:213], v[36:39], v240, v240 op_sel_hi:[0,0,0]
	v_mfma_scale_f32_16x16x128_f8f6f4 v[32:35], v[24:31], v[206:213], v[32:35], v240, v240 op_sel_hi:[0,0,0]
	s_setprio 0
	s_barrier
	s_add_i32 s85, s85, 2
	s_add_u32 s50, s50, 0x100
	s_addc_u32 s51, s51, 0
	s_add_u32 s70, s70, 0x100
	s_addc_u32 s84, s84, 0
	s_cmp_gt_u32 s85, 19
.LBB0_317:
	s_add_u32 s14, s50, 0xfffa8080
	s_addc_u32 s15, s51, -1
	s_add_i32 s22, 0, 0x10000
	s_cmp_eq_u32 s85, 18
	s_cselect_b32 s15, s1, s15
	s_cselect_b32 s14, s0, s14
	s_cselect_b32 s17, s49, s84
	s_cselect_b32 s16, s48, s70
	s_add_i32 s23, 0, 0x14000
	v_add_u32_e32 v0, s22, v221
	v_add_u32_e32 v4, s23, v221
	ds_read_b128 v[24:27], v0
	ds_read_b128 v[28:31], v0 offset:1024
	ds_read_b128 v[16:19], v0 offset:2048
	ds_read_b128 v[20:23], v0 offset:3072
	ds_read_b128 v[8:11], v4
	ds_read_b128 v[12:15], v4 offset:1024
	ds_read_b128 v[0:3], v4 offset:2048
	ds_read_b128 v[4:7], v4 offset:3072
	v_lshl_add_u64 v[206:207], s[50:51], 0, v[196:197]
	s_add_i32 m0, s19, 0xc000
	ds_read_b128 v[160:163], v223
	ds_read_b128 v[164:167], v223 offset:1024
	ds_read_b128 v[168:171], v223 offset:2048
	ds_read_b128 v[172:175], v223 offset:3072
	ds_read_b128 v[176:179], v223 offset:4096
	ds_read_b128 v[180:183], v223 offset:5120
	ds_read_b128 v[198:201], v223 offset:6144
	ds_read_b128 v[202:205], v223 offset:7168
	global_load_lds_dwordx4 v[206:207], off
	v_lshl_add_u64 v[206:207], v[206:207], 0, vcc
	s_add_i32 m0, s19, 0xe000
	s_nop 0
	global_load_lds_dwordx4 v[206:207], off
	s_waitcnt vmcnt(10)
	s_waitcnt lgkmcnt(0)
	s_barrier
	s_setprio 1
	s_waitcnt lgkmcnt(0)
	v_mfma_scale_f32_16x16x128_f8f6f4 v[156:159], v[24:31], v[160:167], v[156:159], v240, v240 op_sel_hi:[0,0,0]
	v_mfma_scale_f32_16x16x128_f8f6f4 v[152:155], v[16:23], v[160:167], v[152:155], v240, v240 op_sel_hi:[0,0,0]
	v_mfma_scale_f32_16x16x128_f8f6f4 v[140:143], v[24:31], v[168:175], v[140:143], v240, v240 op_sel_hi:[0,0,0]
	v_mfma_scale_f32_16x16x128_f8f6f4 v[136:139], v[16:23], v[168:175], v[136:139], v240, v240 op_sel_hi:[0,0,0]
	v_mfma_scale_f32_16x16x128_f8f6f4 v[124:127], v[24:31], v[176:183], v[124:127], v240, v240 op_sel_hi:[0,0,0]
	v_mfma_scale_f32_16x16x128_f8f6f4 v[120:123], v[16:23], v[176:183], v[120:123], v240, v240 op_sel_hi:[0,0,0]
	v_mfma_scale_f32_16x16x128_f8f6f4 v[108:111], v[24:31], v[198:205], v[108:111], v240, v240 op_sel_hi:[0,0,0]
	v_mfma_scale_f32_16x16x128_f8f6f4 v[104:107], v[16:23], v[198:205], v[104:107], v240, v240 op_sel_hi:[0,0,0]
	s_setprio 0
	s_setprio 1
	v_mfma_scale_f32_16x16x128_f8f6f4 v[148:151], v[8:15], v[160:167], v[148:151], v240, v240 op_sel_hi:[0,0,0]
	v_mfma_scale_f32_16x16x128_f8f6f4 v[144:147], v[0:7], v[160:167], v[144:147], v240, v240 op_sel_hi:[0,0,0]
	v_mfma_scale_f32_16x16x128_f8f6f4 v[132:135], v[8:15], v[168:175], v[132:135], v240, v240 op_sel_hi:[0,0,0]
	v_mfma_scale_f32_16x16x128_f8f6f4 v[128:131], v[0:7], v[168:175], v[128:131], v240, v240 op_sel_hi:[0,0,0]
	v_mfma_scale_f32_16x16x128_f8f6f4 v[116:119], v[8:15], v[176:183], v[116:119], v240, v240 op_sel_hi:[0,0,0]
	v_mfma_scale_f32_16x16x128_f8f6f4 v[112:115], v[0:7], v[176:183], v[112:115], v240, v240 op_sel_hi:[0,0,0]
	v_mfma_scale_f32_16x16x128_f8f6f4 v[100:103], v[8:15], v[198:205], v[100:103], v240, v240 op_sel_hi:[0,0,0]
	v_mfma_scale_f32_16x16x128_f8f6f4 v[96:99], v[0:7], v[198:205], v[96:99], v240, v240 op_sel_hi:[0,0,0]
	s_setprio 0
	s_barrier
	v_lshl_add_u64 v[160:161], s[16:17], 0, v[184:185]
	s_add_i32 s16, s22, s6
	s_mov_b32 m0, s16
	ds_read_b128 v[164:167], v223 offset:16384
	ds_read_b128 v[168:171], v223 offset:17408
	ds_read_b128 v[172:175], v223 offset:18432
	ds_read_b128 v[176:179], v223 offset:19456
	ds_read_b128 v[198:201], v223 offset:20480
	ds_read_b128 v[202:205], v223 offset:21504
	ds_read_b128 v[206:209], v223 offset:22528
	ds_read_b128 v[210:213], v223 offset:23552
	global_load_lds_dwordx4 v[160:161], off
	v_lshl_add_u64 v[162:163], v[160:161], 0, vcc
	s_add_i32 m0, s16, 0x2000
	s_add_i32 s16, s23, s6
	global_load_lds_dwordx4 v[162:163], off
	v_lshl_add_u64 v[162:163], v[160:161], 0, s[2:3]
	s_mov_b32 m0, s16
	s_nop 0
	global_load_lds_dwordx4 v[162:163], off
	v_lshl_add_u64 v[162:163], v[160:161], 0, s[82:83]
	s_add_i32 m0, s16, 0x2000
	s_nop 0
	global_load_lds_dwordx4 v[162:163], off
	v_lshl_add_u64 v[162:163], s[14:15], 0, v[194:195]
	s_mov_b32 m0, s19
	v_lshl_add_u64 v[180:181], v[162:163], 0, vcc
	global_load_lds_dwordx4 v[162:163], off
	s_mov_b32 m0, s20
	s_nop 0
	global_load_lds_dwordx4 v[180:181], off
	s_waitcnt vmcnt(14)
	s_waitcnt lgkmcnt(0)
	s_barrier
	s_setprio 1
	s_waitcnt lgkmcnt(0)
	v_mfma_scale_f32_16x16x128_f8f6f4 v[92:95], v[24:31], v[164:171], v[92:95], v240, v240 op_sel_hi:[0,0,0]
	v_mfma_scale_f32_16x16x128_f8f6f4 v[88:91], v[16:23], v[164:171], v[88:91], v240, v240 op_sel_hi:[0,0,0]
	v_mfma_scale_f32_16x16x128_f8f6f4 v[76:79], v[24:31], v[172:179], v[76:79], v240, v240 op_sel_hi:[0,0,0]
	v_mfma_scale_f32_16x16x128_f8f6f4 v[72:75], v[16:23], v[172:179], v[72:75], v240, v240 op_sel_hi:[0,0,0]
	v_mfma_scale_f32_16x16x128_f8f6f4 v[60:63], v[24:31], v[198:205], v[60:63], v240, v240 op_sel_hi:[0,0,0]
	v_mfma_scale_f32_16x16x128_f8f6f4 v[56:59], v[16:23], v[198:205], v[56:59], v240, v240 op_sel_hi:[0,0,0]
	v_mfma_scale_f32_16x16x128_f8f6f4 v[44:47], v[24:31], v[206:213], v[44:47], v240, v240 op_sel_hi:[0,0,0]
	v_mfma_scale_f32_16x16x128_f8f6f4 v[40:43], v[16:23], v[206:213], v[40:43], v240, v240 op_sel_hi:[0,0,0]
	s_setprio 0
	s_setprio 1
	v_mfma_scale_f32_16x16x128_f8f6f4 v[84:87], v[8:15], v[164:171], v[84:87], v240, v240 op_sel_hi:[0,0,0]
	v_mfma_scale_f32_16x16x128_f8f6f4 v[80:83], v[0:7], v[164:171], v[80:83], v240, v240 op_sel_hi:[0,0,0]
	v_mfma_scale_f32_16x16x128_f8f6f4 v[68:71], v[8:15], v[172:179], v[68:71], v240, v240 op_sel_hi:[0,0,0]
	v_mfma_scale_f32_16x16x128_f8f6f4 v[64:67], v[0:7], v[172:179], v[64:67], v240, v240 op_sel_hi:[0,0,0]
	v_mfma_scale_f32_16x16x128_f8f6f4 v[52:55], v[8:15], v[198:205], v[52:55], v240, v240 op_sel_hi:[0,0,0]
	v_mfma_scale_f32_16x16x128_f8f6f4 v[48:51], v[0:7], v[198:205], v[48:51], v240, v240 op_sel_hi:[0,0,0]
	v_mfma_scale_f32_16x16x128_f8f6f4 v[36:39], v[8:15], v[206:213], v[36:39], v240, v240 op_sel_hi:[0,0,0]
	v_mfma_scale_f32_16x16x128_f8f6f4 v[32:35], v[0:7], v[206:213], v[32:35], v240, v240 op_sel_hi:[0,0,0]
	s_setprio 0
	s_barrier
	s_add_i32 s14, 0, 0x18000
	s_add_i32 s15, 0, 0x1c000
	v_add_u32_e32 v12, s14, v221
	v_add_u32_e32 v28, s15, v221
	ds_read_b128 v[0:3], v12
	ds_read_b128 v[4:7], v12 offset:1024
	ds_read_b128 v[8:11], v12 offset:2048
	ds_read_b128 v[12:15], v12 offset:3072
	ds_read_b128 v[16:19], v28
	ds_read_b128 v[20:23], v28 offset:1024
	ds_read_b128 v[24:27], v28 offset:2048
	ds_read_b128 v[28:31], v28 offset:3072
	s_mov_b32 m0, s25
	v_lshl_add_u64 v[180:181], v[162:163], 0, s[2:3]
	ds_read_b128 v[164:167], v223 offset:32768
	ds_read_b128 v[168:171], v223 offset:33792
	ds_read_b128 v[172:175], v223 offset:34816
	ds_read_b128 v[176:179], v223 offset:35840
	ds_read_b128 v[198:201], v223 offset:36864
	ds_read_b128 v[202:205], v223 offset:37888
	ds_read_b128 v[206:209], v223 offset:38912
	ds_read_b128 v[210:213], v223 offset:39936
	global_load_lds_dwordx4 v[180:181], off
	v_lshl_add_u64 v[180:181], v[162:163], 0, s[82:83]
	s_mov_b32 m0, s26
	s_nop 0
	global_load_lds_dwordx4 v[180:181], off
	s_waitcnt vmcnt(10)
	s_waitcnt lgkmcnt(0)
	s_barrier
	s_setprio 1
	s_waitcnt lgkmcnt(0)
	v_mfma_scale_f32_16x16x128_f8f6f4 v[156:159], v[0:7], v[164:171], v[156:159], v240, v240 op_sel_hi:[0,0,0]
	v_mfma_scale_f32_16x16x128_f8f6f4 v[152:155], v[8:15], v[164:171], v[152:155], v240, v240 op_sel_hi:[0,0,0]
	v_mfma_scale_f32_16x16x128_f8f6f4 v[140:143], v[0:7], v[172:179], v[140:143], v240, v240 op_sel_hi:[0,0,0]
	v_mfma_scale_f32_16x16x128_f8f6f4 v[136:139], v[8:15], v[172:179], v[136:139], v240, v240 op_sel_hi:[0,0,0]
	v_mfma_scale_f32_16x16x128_f8f6f4 v[124:127], v[0:7], v[198:205], v[124:127], v240, v240 op_sel_hi:[0,0,0]
	v_mfma_scale_f32_16x16x128_f8f6f4 v[120:123], v[8:15], v[198:205], v[120:123], v240, v240 op_sel_hi:[0,0,0]
	v_mfma_scale_f32_16x16x128_f8f6f4 v[108:111], v[0:7], v[206:213], v[108:111], v240, v240 op_sel_hi:[0,0,0]
	v_mfma_scale_f32_16x16x128_f8f6f4 v[104:107], v[8:15], v[206:213], v[104:107], v240, v240 op_sel_hi:[0,0,0]
	s_setprio 0
	s_setprio 1
	v_mfma_scale_f32_16x16x128_f8f6f4 v[148:151], v[16:23], v[164:171], v[148:151], v240, v240 op_sel_hi:[0,0,0]
	v_mfma_scale_f32_16x16x128_f8f6f4 v[144:147], v[24:31], v[164:171], v[144:147], v240, v240 op_sel_hi:[0,0,0]
	v_mfma_scale_f32_16x16x128_f8f6f4 v[132:135], v[16:23], v[172:179], v[132:135], v240, v240 op_sel_hi:[0,0,0]
	v_mfma_scale_f32_16x16x128_f8f6f4 v[128:131], v[24:31], v[172:179], v[128:131], v240, v240 op_sel_hi:[0,0,0]
	v_mfma_scale_f32_16x16x128_f8f6f4 v[116:119], v[16:23], v[198:205], v[116:119], v240, v240 op_sel_hi:[0,0,0]
	v_mfma_scale_f32_16x16x128_f8f6f4 v[112:115], v[24:31], v[198:205], v[112:115], v240, v240 op_sel_hi:[0,0,0]
	v_mfma_scale_f32_16x16x128_f8f6f4 v[100:103], v[16:23], v[206:213], v[100:103], v240, v240 op_sel_hi:[0,0,0]
	v_mfma_scale_f32_16x16x128_f8f6f4 v[96:99], v[24:31], v[206:213], v[96:99], v240, v240 op_sel_hi:[0,0,0]
	s_setprio 0
	s_barrier
	s_add_i32 s14, s14, s6
	v_lshl_add_u64 v[180:181], v[160:161], 0, s[56:57]
	s_mov_b32 m0, s14
	ds_read_b128 v[164:167], v223 offset:49152
	ds_read_b128 v[168:171], v223 offset:50176
	ds_read_b128 v[172:175], v223 offset:51200
	ds_read_b128 v[176:179], v223 offset:52224
	ds_read_b128 v[198:201], v223 offset:53248
	ds_read_b128 v[202:205], v223 offset:54272
	ds_read_b128 v[206:209], v223 offset:55296
	ds_read_b128 v[210:213], v223 offset:56320
	global_load_lds_dwordx4 v[180:181], off
	v_lshl_add_u64 v[180:181], v[160:161], 0, s[80:81]
	s_add_i32 m0, s14, 0x2000
	s_add_i32 s14, s15, s6
	global_load_lds_dwordx4 v[180:181], off
	v_lshl_add_u64 v[180:181], v[160:161], 0, s[74:75]
	s_mov_b32 m0, s14
	v_lshl_add_u64 v[160:161], v[160:161], 0, s[62:63]
	global_load_lds_dwordx4 v[180:181], off
	s_add_i32 m0, s14, 0x2000
	s_nop 0
	global_load_lds_dwordx4 v[160:161], off
	v_lshl_add_u64 v[160:161], v[162:163], 0, s[56:57]
	s_mov_b32 m0, s28
	s_nop 0
	global_load_lds_dwordx4 v[160:161], off
	v_lshl_add_u64 v[160:161], v[162:163], 0, s[80:81]
	s_mov_b32 m0, s29
	s_nop 0
	global_load_lds_dwordx4 v[160:161], off
	s_waitcnt vmcnt(14)
	s_waitcnt lgkmcnt(0)
	s_barrier
	s_setprio 1
	s_waitcnt lgkmcnt(0)
	v_mfma_scale_f32_16x16x128_f8f6f4 v[92:95], v[0:7], v[164:171], v[92:95], v240, v240 op_sel_hi:[0,0,0]
	v_mfma_scale_f32_16x16x128_f8f6f4 v[88:91], v[8:15], v[164:171], v[88:91], v240, v240 op_sel_hi:[0,0,0]
	v_mfma_scale_f32_16x16x128_f8f6f4 v[76:79], v[0:7], v[172:179], v[76:79], v240, v240 op_sel_hi:[0,0,0]
	v_mfma_scale_f32_16x16x128_f8f6f4 v[72:75], v[8:15], v[172:179], v[72:75], v240, v240 op_sel_hi:[0,0,0]
	v_mfma_scale_f32_16x16x128_f8f6f4 v[60:63], v[0:7], v[198:205], v[60:63], v240, v240 op_sel_hi:[0,0,0]
	v_mfma_scale_f32_16x16x128_f8f6f4 v[56:59], v[8:15], v[198:205], v[56:59], v240, v240 op_sel_hi:[0,0,0]
	v_mfma_scale_f32_16x16x128_f8f6f4 v[44:47], v[0:7], v[206:213], v[44:47], v240, v240 op_sel_hi:[0,0,0]
	v_mfma_scale_f32_16x16x128_f8f6f4 v[40:43], v[8:15], v[206:213], v[40:43], v240, v240 op_sel_hi:[0,0,0]
	s_setprio 0
	s_setprio 1
	v_mfma_scale_f32_16x16x128_f8f6f4 v[84:87], v[16:23], v[164:171], v[84:87], v240, v240 op_sel_hi:[0,0,0]
	v_mfma_scale_f32_16x16x128_f8f6f4 v[80:83], v[24:31], v[164:171], v[80:83], v240, v240 op_sel_hi:[0,0,0]
	v_mfma_scale_f32_16x16x128_f8f6f4 v[68:71], v[16:23], v[172:179], v[68:71], v240, v240 op_sel_hi:[0,0,0]
	v_mfma_scale_f32_16x16x128_f8f6f4 v[64:67], v[24:31], v[172:179], v[64:67], v240, v240 op_sel_hi:[0,0,0]
	v_mfma_scale_f32_16x16x128_f8f6f4 v[52:55], v[16:23], v[198:205], v[52:55], v240, v240 op_sel_hi:[0,0,0]
	v_mfma_scale_f32_16x16x128_f8f6f4 v[48:51], v[24:31], v[198:205], v[48:51], v240, v240 op_sel_hi:[0,0,0]
	v_mfma_scale_f32_16x16x128_f8f6f4 v[36:39], v[16:23], v[206:213], v[36:39], v240, v240 op_sel_hi:[0,0,0]
	v_mfma_scale_f32_16x16x128_f8f6f4 v[32:35], v[24:31], v[206:213], v[32:35], v240, v240 op_sel_hi:[0,0,0]
	s_setprio 0
	s_barrier
	s_add_i32 s85, s85, 2
	s_add_u32 s50, s50, 0x100
	s_addc_u32 s51, s51, 0
	s_add_u32 s70, s70, 0x100
	s_addc_u32 s84, s84, 0
	s_cmp_gt_u32 s85, 19
	s_cbranch_scc0 .LBB0_317
	s_and_b64 vcc, exec, s[46:47]
	s_cbranch_vccz .LBB0_320
	s_barrier

.Lnostb4:
	s_add_i32 s24, s14, 2
	s_add_u32 s46, vcc_lo, 0x80
	s_addc_u32 s15, vcc_hi, 0
	s_add_i32 s18, 0, 0x10000
	s_cmp_eq_u32 s6, s14
	s_cselect_b32 s15, s1, s15
	s_cselect_b32 s14, s0, s46
	s_cselect_b32 s47, s13, s17
	s_cselect_b32 s46, s12, s16
	s_add_i32 s21, 0, 0x14000
	v_add_u32_e32 v140, s18, v223
	v_add_u32_e32 v156, s21, v223
	s_waitcnt lgkmcnt(0)
	ds_read_b128 v[128:131], v140
	ds_read_b128 v[132:135], v140 offset:1024
	ds_read_b128 v[136:139], v140 offset:2048
	ds_read_b128 v[140:143], v140 offset:3072
	ds_read_b128 v[144:147], v156
	ds_read_b128 v[148:151], v156 offset:1024
	ds_read_b128 v[152:155], v156 offset:2048
	ds_read_b128 v[156:159], v156 offset:3072
	v_lshl_add_u64 v[186:187], vcc, 0, v[196:197]
	s_add_i32 m0, s28, 0xc000
	ds_read_b128 v[160:163], v225
	ds_read_b128 v[164:167], v225 offset:1024
	ds_read_b128 v[168:171], v225 offset:2048
	ds_read_b128 v[172:175], v225 offset:3072
	ds_read_b128 v[176:179], v225 offset:4096
	ds_read_b128 v[180:183], v225 offset:5120
	ds_read_b128 v[200:203], v225 offset:6144
	ds_read_b128 v[204:207], v225 offset:7168
	global_load_lds_dwordx4 v[186:187], off
	v_lshl_add_u64 v[186:187], vcc, 0, v[198:199]
	s_add_i32 m0, s28, 0xe000
	s_nop 0
	global_load_lds_dwordx4 v[186:187], off
	s_waitcnt vmcnt(10)
	s_waitcnt lgkmcnt(0)
	s_barrier
	s_setprio 1
	s_waitcnt lgkmcnt(0)
	v_mfma_f32_16x16x32_bf16 v[124:127], v[128:131], v[160:163], 0
	v_mfma_f32_16x16x32_bf16 v[120:123], v[136:139], v[160:163], 0
	v_mfma_f32_16x16x32_bf16 v[108:111], v[128:131], v[168:171], 0
	v_mfma_f32_16x16x32_bf16 v[104:107], v[136:139], v[168:171], 0
	v_mfma_f32_16x16x32_bf16 v[92:95], v[128:131], v[176:179], 0
	v_mfma_f32_16x16x32_bf16 v[88:91], v[136:139], v[176:179], 0
	v_mfma_f32_16x16x32_bf16 v[76:79], v[128:131], v[200:203], 0
	v_mfma_f32_16x16x32_bf16 v[72:75], v[136:139], v[200:203], 0
	v_mfma_f32_16x16x32_bf16 v[124:127], v[132:135], v[164:167], v[124:127]
	v_mfma_f32_16x16x32_bf16 v[120:123], v[140:143], v[164:167], v[120:123]
	v_mfma_f32_16x16x32_bf16 v[108:111], v[132:135], v[172:175], v[108:111]
	v_mfma_f32_16x16x32_bf16 v[104:107], v[140:143], v[172:175], v[104:107]
	v_mfma_f32_16x16x32_bf16 v[92:95], v[132:135], v[180:183], v[92:95]
	v_mfma_f32_16x16x32_bf16 v[88:91], v[140:143], v[180:183], v[88:91]
	v_mfma_f32_16x16x32_bf16 v[76:79], v[132:135], v[204:207], v[76:79]
	v_mfma_f32_16x16x32_bf16 v[72:75], v[140:143], v[204:207], v[72:75]
	s_setprio 0
	s_setprio 1
	v_mfma_f32_16x16x32_bf16 v[116:119], v[144:147], v[160:163], 0
	v_mfma_f32_16x16x32_bf16 v[112:115], v[152:155], v[160:163], 0
	v_mfma_f32_16x16x32_bf16 v[100:103], v[144:147], v[168:171], 0
	v_mfma_f32_16x16x32_bf16 v[96:99], v[152:155], v[168:171], 0
	v_mfma_f32_16x16x32_bf16 v[84:87], v[144:147], v[176:179], 0
	v_mfma_f32_16x16x32_bf16 v[80:83], v[152:155], v[176:179], 0
	v_mfma_f32_16x16x32_bf16 v[68:71], v[144:147], v[200:203], 0
	v_mfma_f32_16x16x32_bf16 v[64:67], v[152:155], v[200:203], 0
	v_mfma_f32_16x16x32_bf16 v[116:119], v[148:151], v[164:167], v[116:119]
	v_mfma_f32_16x16x32_bf16 v[112:115], v[156:159], v[164:167], v[112:115]
	v_mfma_f32_16x16x32_bf16 v[100:103], v[148:151], v[172:175], v[100:103]
	v_mfma_f32_16x16x32_bf16 v[96:99], v[156:159], v[172:175], v[96:99]
	v_mfma_f32_16x16x32_bf16 v[84:87], v[148:151], v[180:183], v[84:87]
	v_mfma_f32_16x16x32_bf16 v[80:83], v[156:159], v[180:183], v[80:83]
	v_mfma_f32_16x16x32_bf16 v[68:71], v[148:151], v[204:207], v[68:71]
	v_mfma_f32_16x16x32_bf16 v[64:67], v[156:159], v[204:207], v[64:67]
	s_setprio 0
	s_barrier
	s_add_i32 s18, s18, s27
	v_lshl_add_u64 v[186:187], s[46:47], 0, v[184:185]
	s_mov_b32 m0, s18
	ds_read_b128 v[160:163], v225 offset:16384
	ds_read_b128 v[164:167], v225 offset:17408
	ds_read_b128 v[168:171], v225 offset:18432
	ds_read_b128 v[172:175], v225 offset:19456
	ds_read_b128 v[176:179], v225 offset:20480
	ds_read_b128 v[180:183], v225 offset:21504
	ds_read_b128 v[200:203], v225 offset:22528
	ds_read_b128 v[204:207], v225 offset:23552
	global_load_lds_dwordx4 v[186:187], off
	s_add_i32 m0, s18, 0x2000
	s_add_u32 s46, s46, s44
	v_lshl_add_u64 v[188:189], v[186:187], 0, s[70:71]
	s_addc_u32 s47, s47, 0
	s_add_i32 s18, s21, s27
	global_load_lds_dwordx4 v[188:189], off
	v_lshl_add_u64 v[208:209], s[46:47], 0, v[184:185]
	s_mov_b32 m0, s18
	v_lshl_add_u64 v[210:211], v[208:209], 0, s[70:71]
	global_load_lds_dwordx4 v[208:209], off
	s_add_i32 m0, s18, 0x2000
	v_lshl_add_u64 v[212:213], s[14:15], 0, v[194:195]
	global_load_lds_dwordx4 v[210:211], off
	s_mov_b32 m0, s28
	v_lshl_add_u64 v[214:215], v[212:213], 0, s[70:71]
	global_load_lds_dwordx4 v[212:213], off
	s_mov_b32 m0, s29
	s_nop 0
	global_load_lds_dwordx4 v[214:215], off
	s_waitcnt vmcnt(14)
	s_waitcnt lgkmcnt(0)
	s_barrier
	s_setprio 1
	s_waitcnt lgkmcnt(0)
	v_mfma_f32_16x16x32_bf16 v[60:63], v[128:131], v[160:163], 0
	v_mfma_f32_16x16x32_bf16 v[56:59], v[136:139], v[160:163], 0
	v_mfma_f32_16x16x32_bf16 v[44:47], v[128:131], v[168:171], 0
	v_mfma_f32_16x16x32_bf16 v[40:43], v[136:139], v[168:171], 0
	v_mfma_f32_16x16x32_bf16 v[28:31], v[128:131], v[176:179], 0
	v_mfma_f32_16x16x32_bf16 v[24:27], v[136:139], v[176:179], 0
	v_mfma_f32_16x16x32_bf16 v[12:15], v[128:131], v[200:203], 0
	v_mfma_f32_16x16x32_bf16 v[8:11], v[136:139], v[200:203], 0
	v_mfma_f32_16x16x32_bf16 v[60:63], v[132:135], v[164:167], v[60:63]
	v_mfma_f32_16x16x32_bf16 v[56:59], v[140:143], v[164:167], v[56:59]
	v_mfma_f32_16x16x32_bf16 v[44:47], v[132:135], v[172:175], v[44:47]
	v_mfma_f32_16x16x32_bf16 v[40:43], v[140:143], v[172:175], v[40:43]
	v_mfma_f32_16x16x32_bf16 v[28:31], v[132:135], v[180:183], v[28:31]
	v_mfma_f32_16x16x32_bf16 v[24:27], v[140:143], v[180:183], v[24:27]
	v_mfma_f32_16x16x32_bf16 v[12:15], v[132:135], v[204:207], v[12:15]
	v_mfma_f32_16x16x32_bf16 v[8:11], v[140:143], v[204:207], v[8:11]
	s_setprio 0
	s_setprio 1
	v_mfma_f32_16x16x32_bf16 v[52:55], v[144:147], v[160:163], 0
	v_mfma_f32_16x16x32_bf16 v[48:51], v[152:155], v[160:163], 0
	v_mfma_f32_16x16x32_bf16 v[36:39], v[144:147], v[168:171], 0
	v_mfma_f32_16x16x32_bf16 v[32:35], v[152:155], v[168:171], 0
	v_mfma_f32_16x16x32_bf16 v[20:23], v[144:147], v[176:179], 0
	v_mfma_f32_16x16x32_bf16 v[16:19], v[152:155], v[176:179], 0
	v_mfma_f32_16x16x32_bf16 v[4:7], v[144:147], v[200:203], 0
	v_mfma_f32_16x16x32_bf16 v[0:3], v[152:155], v[200:203], 0
	v_mfma_f32_16x16x32_bf16 v[52:55], v[148:151], v[164:167], v[52:55]
	v_mfma_f32_16x16x32_bf16 v[48:51], v[156:159], v[164:167], v[48:51]
	v_mfma_f32_16x16x32_bf16 v[36:39], v[148:151], v[172:175], v[36:39]
	v_mfma_f32_16x16x32_bf16 v[32:35], v[156:159], v[172:175], v[32:35]
	v_mfma_f32_16x16x32_bf16 v[20:23], v[148:151], v[180:183], v[20:23]
	v_mfma_f32_16x16x32_bf16 v[16:19], v[156:159], v[180:183], v[16:19]
	v_mfma_f32_16x16x32_bf16 v[4:7], v[148:151], v[204:207], v[4:7]
	v_mfma_f32_16x16x32_bf16 v[0:3], v[156:159], v[204:207], v[0:3]
	s_setprio 0
	s_barrier
	s_add_i32 s18, 0, 0x18000
	s_add_i32 s21, 0, 0x1c000
	v_add_u32_e32 v140, s18, v223
	v_add_u32_e32 v156, s21, v223
	ds_read_b128 v[128:131], v140
	ds_read_b128 v[132:135], v140 offset:1024
	ds_read_b128 v[136:139], v140 offset:2048
	ds_read_b128 v[140:143], v140 offset:3072
	ds_read_b128 v[144:147], v156
	ds_read_b128 v[148:151], v156 offset:1024
	ds_read_b128 v[152:155], v156 offset:2048
	ds_read_b128 v[156:159], v156 offset:3072
	s_add_u32 s14, s14, s44
	s_addc_u32 s15, s15, 0
	s_mov_b32 m0, s30
	v_lshl_add_u64 v[216:217], s[14:15], 0, v[194:195]
	ds_read_b128 v[160:163], v225 offset:32768
	ds_read_b128 v[164:167], v225 offset:33792
	ds_read_b128 v[168:171], v225 offset:34816
	ds_read_b128 v[172:175], v225 offset:35840
	ds_read_b128 v[176:179], v225 offset:36864
	ds_read_b128 v[180:183], v225 offset:37888
	ds_read_b128 v[200:203], v225 offset:38912
	ds_read_b128 v[204:207], v225 offset:39936
	global_load_lds_dwordx4 v[216:217], off
	v_lshl_add_u64 v[216:217], v[216:217], 0, s[70:71]
	s_mov_b32 m0, s31
	s_nop 0
	global_load_lds_dwordx4 v[216:217], off
	s_waitcnt vmcnt(10)
	s_waitcnt lgkmcnt(0)
	s_barrier
	s_setprio 1
	s_waitcnt lgkmcnt(0)
	v_mfma_f32_16x16x32_bf16 v[124:127], v[128:131], v[160:163], v[124:127]
	v_mfma_f32_16x16x32_bf16 v[120:123], v[136:139], v[160:163], v[120:123]
	v_mfma_f32_16x16x32_bf16 v[108:111], v[128:131], v[168:171], v[108:111]
	v_mfma_f32_16x16x32_bf16 v[104:107], v[136:139], v[168:171], v[104:107]
	v_mfma_f32_16x16x32_bf16 v[92:95], v[128:131], v[176:179], v[92:95]
	v_mfma_f32_16x16x32_bf16 v[88:91], v[136:139], v[176:179], v[88:91]
	v_mfma_f32_16x16x32_bf16 v[76:79], v[128:131], v[200:203], v[76:79]
	v_mfma_f32_16x16x32_bf16 v[72:75], v[136:139], v[200:203], v[72:75]
	v_mfma_f32_16x16x32_bf16 v[124:127], v[132:135], v[164:167], v[124:127]
	v_mfma_f32_16x16x32_bf16 v[120:123], v[140:143], v[164:167], v[120:123]
	v_mfma_f32_16x16x32_bf16 v[108:111], v[132:135], v[172:175], v[108:111]
	v_mfma_f32_16x16x32_bf16 v[104:107], v[140:143], v[172:175], v[104:107]
	v_mfma_f32_16x16x32_bf16 v[92:95], v[132:135], v[180:183], v[92:95]
	v_mfma_f32_16x16x32_bf16 v[88:91], v[140:143], v[180:183], v[88:91]
	v_mfma_f32_16x16x32_bf16 v[76:79], v[132:135], v[204:207], v[76:79]
	v_mfma_f32_16x16x32_bf16 v[72:75], v[140:143], v[204:207], v[72:75]
	s_setprio 0
	s_setprio 1
	v_mfma_f32_16x16x32_bf16 v[116:119], v[144:147], v[160:163], v[116:119]
	v_mfma_f32_16x16x32_bf16 v[112:115], v[152:155], v[160:163], v[112:115]
	v_mfma_f32_16x16x32_bf16 v[100:103], v[144:147], v[168:171], v[100:103]
	v_mfma_f32_16x16x32_bf16 v[96:99], v[152:155], v[168:171], v[96:99]
	v_mfma_f32_16x16x32_bf16 v[84:87], v[144:147], v[176:179], v[84:87]
	v_mfma_f32_16x16x32_bf16 v[80:83], v[152:155], v[176:179], v[80:83]
	v_mfma_f32_16x16x32_bf16 v[68:71], v[144:147], v[200:203], v[68:71]
	v_mfma_f32_16x16x32_bf16 v[64:67], v[152:155], v[200:203], v[64:67]
	v_mfma_f32_16x16x32_bf16 v[116:119], v[148:151], v[164:167], v[116:119]
	v_mfma_f32_16x16x32_bf16 v[112:115], v[156:159], v[164:167], v[112:115]
	v_mfma_f32_16x16x32_bf16 v[100:103], v[148:151], v[172:175], v[100:103]
	v_mfma_f32_16x16x32_bf16 v[96:99], v[156:159], v[172:175], v[96:99]
	v_mfma_f32_16x16x32_bf16 v[84:87], v[148:151], v[180:183], v[84:87]
	v_mfma_f32_16x16x32_bf16 v[80:83], v[156:159], v[180:183], v[80:83]
	v_mfma_f32_16x16x32_bf16 v[68:71], v[148:151], v[204:207], v[68:71]
	v_mfma_f32_16x16x32_bf16 v[64:67], v[156:159], v[204:207], v[64:67]
	s_setprio 0
	s_barrier
	s_add_i32 s14, s18, s27
	v_lshl_add_u64 v[186:187], v[186:187], 0, s[56:57]
	s_mov_b32 m0, s14
	ds_read_b128 v[160:163], v225 offset:49152
	ds_read_b128 v[164:167], v225 offset:50176
	ds_read_b128 v[168:171], v225 offset:51200
	ds_read_b128 v[172:175], v225 offset:52224
	ds_read_b128 v[176:179], v225 offset:53248
	ds_read_b128 v[180:183], v225 offset:54272
	ds_read_b128 v[200:203], v225 offset:55296
	ds_read_b128 v[204:207], v225 offset:56320
	global_load_lds_dwordx4 v[186:187], off
	v_lshl_add_u64 v[186:187], v[188:189], 0, s[56:57]
	s_add_i32 m0, s14, 0x2000
	s_add_i32 s14, s21, s27
	global_load_lds_dwordx4 v[186:187], off
	v_lshl_add_u64 v[186:187], v[208:209], 0, s[56:57]
	s_mov_b32 m0, s14
	s_nop 0
	global_load_lds_dwordx4 v[186:187], off
	v_lshl_add_u64 v[186:187], v[210:211], 0, s[56:57]
	s_add_i32 m0, s14, 0x2000
	s_nop 0
	global_load_lds_dwordx4 v[186:187], off
	v_lshl_add_u64 v[186:187], v[212:213], 0, s[56:57]
	s_mov_b32 m0, s19
	s_nop 0
	global_load_lds_dwordx4 v[186:187], off
	v_lshl_add_u64 v[186:187], v[214:215], 0, s[56:57]
	s_mov_b32 m0, s20
	s_nop 0
	global_load_lds_dwordx4 v[186:187], off
	s_waitcnt vmcnt(14)
	s_waitcnt lgkmcnt(0)
	s_barrier
	s_setprio 1
	s_waitcnt lgkmcnt(0)
	v_mfma_f32_16x16x32_bf16 v[60:63], v[128:131], v[160:163], v[60:63]
	v_mfma_f32_16x16x32_bf16 v[56:59], v[136:139], v[160:163], v[56:59]
	v_mfma_f32_16x16x32_bf16 v[44:47], v[128:131], v[168:171], v[44:47]
	v_mfma_f32_16x16x32_bf16 v[40:43], v[136:139], v[168:171], v[40:43]
	v_mfma_f32_16x16x32_bf16 v[28:31], v[128:131], v[176:179], v[28:31]
	v_mfma_f32_16x16x32_bf16 v[24:27], v[136:139], v[176:179], v[24:27]
	v_mfma_f32_16x16x32_bf16 v[12:15], v[128:131], v[200:203], v[12:15]
	v_mfma_f32_16x16x32_bf16 v[8:11], v[136:139], v[200:203], v[8:11]
	v_mfma_f32_16x16x32_bf16 v[60:63], v[132:135], v[164:167], v[60:63]
	v_mfma_f32_16x16x32_bf16 v[56:59], v[140:143], v[164:167], v[56:59]
	v_mfma_f32_16x16x32_bf16 v[44:47], v[132:135], v[172:175], v[44:47]
	v_mfma_f32_16x16x32_bf16 v[40:43], v[140:143], v[172:175], v[40:43]
	v_mfma_f32_16x16x32_bf16 v[28:31], v[132:135], v[180:183], v[28:31]
	v_mfma_f32_16x16x32_bf16 v[24:27], v[140:143], v[180:183], v[24:27]
	v_mfma_f32_16x16x32_bf16 v[12:15], v[132:135], v[204:207], v[12:15]
	v_mfma_f32_16x16x32_bf16 v[8:11], v[140:143], v[204:207], v[8:11]
	s_setprio 0
	s_setprio 1
	v_mfma_f32_16x16x32_bf16 v[52:55], v[144:147], v[160:163], v[52:55]
	v_mfma_f32_16x16x32_bf16 v[48:51], v[152:155], v[160:163], v[48:51]
	v_mfma_f32_16x16x32_bf16 v[36:39], v[144:147], v[168:171], v[36:39]
	v_mfma_f32_16x16x32_bf16 v[32:35], v[152:155], v[168:171], v[32:35]
	v_mfma_f32_16x16x32_bf16 v[20:23], v[144:147], v[176:179], v[20:23]
	v_mfma_f32_16x16x32_bf16 v[16:19], v[152:155], v[176:179], v[16:19]
	v_mfma_f32_16x16x32_bf16 v[4:7], v[144:147], v[200:203], v[4:7]
	v_mfma_f32_16x16x32_bf16 v[0:3], v[152:155], v[200:203], v[0:3]
	v_mfma_f32_16x16x32_bf16 v[52:55], v[148:151], v[164:167], v[52:55]
	v_mfma_f32_16x16x32_bf16 v[48:51], v[156:159], v[164:167], v[48:51]
	v_mfma_f32_16x16x32_bf16 v[36:39], v[148:151], v[172:175], v[36:39]
	v_mfma_f32_16x16x32_bf16 v[32:35], v[156:159], v[172:175], v[32:35]
	v_mfma_f32_16x16x32_bf16 v[20:23], v[148:151], v[180:183], v[20:23]
	v_mfma_f32_16x16x32_bf16 v[16:19], v[156:159], v[180:183], v[16:19]
	v_mfma_f32_16x16x32_bf16 v[4:7], v[148:151], v[204:207], v[4:7]
	v_mfma_f32_16x16x32_bf16 v[0:3], v[156:159], v[204:207], v[0:3]
	s_setprio 0
	s_barrier
	s_add_u32 vcc_lo, vcc_lo, 0x100
	s_addc_u32 vcc_hi, vcc_hi, 0
	s_add_u32 s16, s16, 0x100
	s_addc_u32 s17, s17, 0
	s_cmp_ge_u32 s24, s84
	s_mov_b32 s14, s24
.LBB0_362:
	s_add_i32 s24, s14, 2
	s_add_u32 s46, vcc_lo, 0x80
	s_addc_u32 s15, vcc_hi, 0
	s_add_i32 s18, 0, 0x10000
	s_cmp_eq_u32 s6, s14
	s_cselect_b32 s15, s1, s15
	s_cselect_b32 s14, s0, s46
	s_cselect_b32 s47, s13, s17
	s_cselect_b32 s46, s12, s16
	s_add_i32 s21, 0, 0x14000
	v_add_u32_e32 v140, s18, v223
	v_add_u32_e32 v156, s21, v223
	s_waitcnt lgkmcnt(0)
	ds_read_b128 v[128:131], v140
	ds_read_b128 v[132:135], v140 offset:1024
	ds_read_b128 v[136:139], v140 offset:2048
	ds_read_b128 v[140:143], v140 offset:3072
	ds_read_b128 v[144:147], v156
	ds_read_b128 v[148:151], v156 offset:1024
	ds_read_b128 v[152:155], v156 offset:2048
	ds_read_b128 v[156:159], v156 offset:3072
	v_lshl_add_u64 v[186:187], vcc, 0, v[196:197]
	s_add_i32 m0, s28, 0xc000
	ds_read_b128 v[160:163], v225
	ds_read_b128 v[164:167], v225 offset:1024
	ds_read_b128 v[168:171], v225 offset:2048
	ds_read_b128 v[172:175], v225 offset:3072
	ds_read_b128 v[176:179], v225 offset:4096
	ds_read_b128 v[180:183], v225 offset:5120
	ds_read_b128 v[200:203], v225 offset:6144
	ds_read_b128 v[204:207], v225 offset:7168
	global_load_lds_dwordx4 v[186:187], off
	v_lshl_add_u64 v[186:187], vcc, 0, v[198:199]
	s_add_i32 m0, s28, 0xe000
	s_nop 0
	global_load_lds_dwordx4 v[186:187], off
	s_waitcnt vmcnt(10)
	s_waitcnt lgkmcnt(0)
	s_barrier
	s_setprio 1
	s_waitcnt lgkmcnt(0)
	v_mfma_f32_16x16x32_bf16 v[124:127], v[128:131], v[160:163], v[124:127]
	v_mfma_f32_16x16x32_bf16 v[120:123], v[136:139], v[160:163], v[120:123]
	v_mfma_f32_16x16x32_bf16 v[108:111], v[128:131], v[168:171], v[108:111]
	v_mfma_f32_16x16x32_bf16 v[104:107], v[136:139], v[168:171], v[104:107]
	v_mfma_f32_16x16x32_bf16 v[92:95], v[128:131], v[176:179], v[92:95]
	v_mfma_f32_16x16x32_bf16 v[88:91], v[136:139], v[176:179], v[88:91]
	v_mfma_f32_16x16x32_bf16 v[76:79], v[128:131], v[200:203], v[76:79]
	v_mfma_f32_16x16x32_bf16 v[72:75], v[136:139], v[200:203], v[72:75]
	v_mfma_f32_16x16x32_bf16 v[124:127], v[132:135], v[164:167], v[124:127]
	v_mfma_f32_16x16x32_bf16 v[120:123], v[140:143], v[164:167], v[120:123]
	v_mfma_f32_16x16x32_bf16 v[108:111], v[132:135], v[172:175], v[108:111]
	v_mfma_f32_16x16x32_bf16 v[104:107], v[140:143], v[172:175], v[104:107]
	v_mfma_f32_16x16x32_bf16 v[92:95], v[132:135], v[180:183], v[92:95]
	v_mfma_f32_16x16x32_bf16 v[88:91], v[140:143], v[180:183], v[88:91]
	v_mfma_f32_16x16x32_bf16 v[76:79], v[132:135], v[204:207], v[76:79]
	v_mfma_f32_16x16x32_bf16 v[72:75], v[140:143], v[204:207], v[72:75]
	s_setprio 0
	s_setprio 1
	v_mfma_f32_16x16x32_bf16 v[116:119], v[144:147], v[160:163], v[116:119]
	v_mfma_f32_16x16x32_bf16 v[112:115], v[152:155], v[160:163], v[112:115]
	v_mfma_f32_16x16x32_bf16 v[100:103], v[144:147], v[168:171], v[100:103]
	v_mfma_f32_16x16x32_bf16 v[96:99], v[152:155], v[168:171], v[96:99]
	v_mfma_f32_16x16x32_bf16 v[84:87], v[144:147], v[176:179], v[84:87]
	v_mfma_f32_16x16x32_bf16 v[80:83], v[152:155], v[176:179], v[80:83]
	v_mfma_f32_16x16x32_bf16 v[68:71], v[144:147], v[200:203], v[68:71]
	v_mfma_f32_16x16x32_bf16 v[64:67], v[152:155], v[200:203], v[64:67]
	v_mfma_f32_16x16x32_bf16 v[116:119], v[148:151], v[164:167], v[116:119]
	v_mfma_f32_16x16x32_bf16 v[112:115], v[156:159], v[164:167], v[112:115]
	v_mfma_f32_16x16x32_bf16 v[100:103], v[148:151], v[172:175], v[100:103]
	v_mfma_f32_16x16x32_bf16 v[96:99], v[156:159], v[172:175], v[96:99]
	v_mfma_f32_16x16x32_bf16 v[84:87], v[148:151], v[180:183], v[84:87]
	v_mfma_f32_16x16x32_bf16 v[80:83], v[156:159], v[180:183], v[80:83]
	v_mfma_f32_16x16x32_bf16 v[68:71], v[148:151], v[204:207], v[68:71]
	v_mfma_f32_16x16x32_bf16 v[64:67], v[156:159], v[204:207], v[64:67]
	s_setprio 0
	s_barrier
	s_add_i32 s18, s18, s27
	v_lshl_add_u64 v[186:187], s[46:47], 0, v[184:185]
	s_mov_b32 m0, s18
	ds_read_b128 v[160:163], v225 offset:16384
	ds_read_b128 v[164:167], v225 offset:17408
	ds_read_b128 v[168:171], v225 offset:18432
	ds_read_b128 v[172:175], v225 offset:19456
	ds_read_b128 v[176:179], v225 offset:20480
	ds_read_b128 v[180:183], v225 offset:21504
	ds_read_b128 v[200:203], v225 offset:22528
	ds_read_b128 v[204:207], v225 offset:23552
	global_load_lds_dwordx4 v[186:187], off
	s_add_i32 m0, s18, 0x2000
	s_add_u32 s46, s46, s44
	v_lshl_add_u64 v[188:189], v[186:187], 0, s[70:71]
	s_addc_u32 s47, s47, 0
	s_add_i32 s18, s21, s27
	global_load_lds_dwordx4 v[188:189], off
	v_lshl_add_u64 v[208:209], s[46:47], 0, v[184:185]
	s_mov_b32 m0, s18
	v_lshl_add_u64 v[210:211], v[208:209], 0, s[70:71]
	global_load_lds_dwordx4 v[208:209], off
	s_add_i32 m0, s18, 0x2000
	v_lshl_add_u64 v[212:213], s[14:15], 0, v[194:195]
	global_load_lds_dwordx4 v[210:211], off
	s_mov_b32 m0, s28
	v_lshl_add_u64 v[214:215], v[212:213], 0, s[70:71]
	global_load_lds_dwordx4 v[212:213], off
	s_mov_b32 m0, s29
	s_nop 0
	global_load_lds_dwordx4 v[214:215], off
	s_waitcnt vmcnt(14)
	s_waitcnt lgkmcnt(0)
	s_barrier
	s_setprio 1
	s_waitcnt lgkmcnt(0)
	v_mfma_f32_16x16x32_bf16 v[60:63], v[128:131], v[160:163], v[60:63]
	v_mfma_f32_16x16x32_bf16 v[56:59], v[136:139], v[160:163], v[56:59]
	v_mfma_f32_16x16x32_bf16 v[44:47], v[128:131], v[168:171], v[44:47]
	v_mfma_f32_16x16x32_bf16 v[40:43], v[136:139], v[168:171], v[40:43]
	v_mfma_f32_16x16x32_bf16 v[28:31], v[128:131], v[176:179], v[28:31]
	v_mfma_f32_16x16x32_bf16 v[24:27], v[136:139], v[176:179], v[24:27]
	v_mfma_f32_16x16x32_bf16 v[12:15], v[128:131], v[200:203], v[12:15]
	v_mfma_f32_16x16x32_bf16 v[8:11], v[136:139], v[200:203], v[8:11]
	v_mfma_f32_16x16x32_bf16 v[60:63], v[132:135], v[164:167], v[60:63]
	v_mfma_f32_16x16x32_bf16 v[56:59], v[140:143], v[164:167], v[56:59]
	v_mfma_f32_16x16x32_bf16 v[44:47], v[132:135], v[172:175], v[44:47]
	v_mfma_f32_16x16x32_bf16 v[40:43], v[140:143], v[172:175], v[40:43]
	v_mfma_f32_16x16x32_bf16 v[28:31], v[132:135], v[180:183], v[28:31]
	v_mfma_f32_16x16x32_bf16 v[24:27], v[140:143], v[180:183], v[24:27]
	v_mfma_f32_16x16x32_bf16 v[12:15], v[132:135], v[204:207], v[12:15]
	v_mfma_f32_16x16x32_bf16 v[8:11], v[140:143], v[204:207], v[8:11]
	s_setprio 0
	s_setprio 1
	v_mfma_f32_16x16x32_bf16 v[52:55], v[144:147], v[160:163], v[52:55]
	v_mfma_f32_16x16x32_bf16 v[48:51], v[152:155], v[160:163], v[48:51]
	v_mfma_f32_16x16x32_bf16 v[36:39], v[144:147], v[168:171], v[36:39]
	v_mfma_f32_16x16x32_bf16 v[32:35], v[152:155], v[168:171], v[32:35]
	v_mfma_f32_16x16x32_bf16 v[20:23], v[144:147], v[176:179], v[20:23]
	v_mfma_f32_16x16x32_bf16 v[16:19], v[152:155], v[176:179], v[16:19]
	v_mfma_f32_16x16x32_bf16 v[4:7], v[144:147], v[200:203], v[4:7]
	v_mfma_f32_16x16x32_bf16 v[0:3], v[152:155], v[200:203], v[0:3]
	v_mfma_f32_16x16x32_bf16 v[52:55], v[148:151], v[164:167], v[52:55]
	v_mfma_f32_16x16x32_bf16 v[48:51], v[156:159], v[164:167], v[48:51]
	v_mfma_f32_16x16x32_bf16 v[36:39], v[148:151], v[172:175], v[36:39]
	v_mfma_f32_16x16x32_bf16 v[32:35], v[156:159], v[172:175], v[32:35]
	v_mfma_f32_16x16x32_bf16 v[20:23], v[148:151], v[180:183], v[20:23]
	v_mfma_f32_16x16x32_bf16 v[16:19], v[156:159], v[180:183], v[16:19]
	v_mfma_f32_16x16x32_bf16 v[4:7], v[148:151], v[204:207], v[4:7]
	v_mfma_f32_16x16x32_bf16 v[0:3], v[156:159], v[204:207], v[0:3]
	s_setprio 0
	s_barrier
	s_add_i32 s18, 0, 0x18000
	s_add_i32 s21, 0, 0x1c000
	v_add_u32_e32 v140, s18, v223
	v_add_u32_e32 v156, s21, v223
	ds_read_b128 v[128:131], v140
	ds_read_b128 v[132:135], v140 offset:1024
	ds_read_b128 v[136:139], v140 offset:2048
	ds_read_b128 v[140:143], v140 offset:3072
	ds_read_b128 v[144:147], v156
	ds_read_b128 v[148:151], v156 offset:1024
	ds_read_b128 v[152:155], v156 offset:2048
	ds_read_b128 v[156:159], v156 offset:3072
	s_add_u32 s14, s14, s44
	s_addc_u32 s15, s15, 0
	s_mov_b32 m0, s30
	v_lshl_add_u64 v[216:217], s[14:15], 0, v[194:195]
	ds_read_b128 v[160:163], v225 offset:32768
	ds_read_b128 v[164:167], v225 offset:33792
	ds_read_b128 v[168:171], v225 offset:34816
	ds_read_b128 v[172:175], v225 offset:35840
	ds_read_b128 v[176:179], v225 offset:36864
	ds_read_b128 v[180:183], v225 offset:37888
	ds_read_b128 v[200:203], v225 offset:38912
	ds_read_b128 v[204:207], v225 offset:39936
	global_load_lds_dwordx4 v[216:217], off
	v_lshl_add_u64 v[216:217], v[216:217], 0, s[70:71]
	s_mov_b32 m0, s31
	s_nop 0
	global_load_lds_dwordx4 v[216:217], off
	s_waitcnt vmcnt(10)
	s_waitcnt lgkmcnt(0)
	s_barrier
	s_setprio 1
	s_waitcnt lgkmcnt(0)
	v_mfma_f32_16x16x32_bf16 v[124:127], v[128:131], v[160:163], v[124:127]
	v_mfma_f32_16x16x32_bf16 v[120:123], v[136:139], v[160:163], v[120:123]
	v_mfma_f32_16x16x32_bf16 v[108:111], v[128:131], v[168:171], v[108:111]
	v_mfma_f32_16x16x32_bf16 v[104:107], v[136:139], v[168:171], v[104:107]
	v_mfma_f32_16x16x32_bf16 v[92:95], v[128:131], v[176:179], v[92:95]
	v_mfma_f32_16x16x32_bf16 v[88:91], v[136:139], v[176:179], v[88:91]
	v_mfma_f32_16x16x32_bf16 v[76:79], v[128:131], v[200:203], v[76:79]
	v_mfma_f32_16x16x32_bf16 v[72:75], v[136:139], v[200:203], v[72:75]
	v_mfma_f32_16x16x32_bf16 v[124:127], v[132:135], v[164:167], v[124:127]
	v_mfma_f32_16x16x32_bf16 v[120:123], v[140:143], v[164:167], v[120:123]
	v_mfma_f32_16x16x32_bf16 v[108:111], v[132:135], v[172:175], v[108:111]
	v_mfma_f32_16x16x32_bf16 v[104:107], v[140:143], v[172:175], v[104:107]
	v_mfma_f32_16x16x32_bf16 v[92:95], v[132:135], v[180:183], v[92:95]
	v_mfma_f32_16x16x32_bf16 v[88:91], v[140:143], v[180:183], v[88:91]
	v_mfma_f32_16x16x32_bf16 v[76:79], v[132:135], v[204:207], v[76:79]
	v_mfma_f32_16x16x32_bf16 v[72:75], v[140:143], v[204:207], v[72:75]
	s_setprio 0
	s_setprio 1
	v_mfma_f32_16x16x32_bf16 v[116:119], v[144:147], v[160:163], v[116:119]
	v_mfma_f32_16x16x32_bf16 v[112:115], v[152:155], v[160:163], v[112:115]
	v_mfma_f32_16x16x32_bf16 v[100:103], v[144:147], v[168:171], v[100:103]
	v_mfma_f32_16x16x32_bf16 v[96:99], v[152:155], v[168:171], v[96:99]
	v_mfma_f32_16x16x32_bf16 v[84:87], v[144:147], v[176:179], v[84:87]
	v_mfma_f32_16x16x32_bf16 v[80:83], v[152:155], v[176:179], v[80:83]
	v_mfma_f32_16x16x32_bf16 v[68:71], v[144:147], v[200:203], v[68:71]
	v_mfma_f32_16x16x32_bf16 v[64:67], v[152:155], v[200:203], v[64:67]
	v_mfma_f32_16x16x32_bf16 v[116:119], v[148:151], v[164:167], v[116:119]
	v_mfma_f32_16x16x32_bf16 v[112:115], v[156:159], v[164:167], v[112:115]
	v_mfma_f32_16x16x32_bf16 v[100:103], v[148:151], v[172:175], v[100:103]
	v_mfma_f32_16x16x32_bf16 v[96:99], v[156:159], v[172:175], v[96:99]
	v_mfma_f32_16x16x32_bf16 v[84:87], v[148:151], v[180:183], v[84:87]
	v_mfma_f32_16x16x32_bf16 v[80:83], v[156:159], v[180:183], v[80:83]
	v_mfma_f32_16x16x32_bf16 v[68:71], v[148:151], v[204:207], v[68:71]
	v_mfma_f32_16x16x32_bf16 v[64:67], v[156:159], v[204:207], v[64:67]
	s_setprio 0
	s_barrier
	s_add_i32 s14, s18, s27
	v_lshl_add_u64 v[186:187], v[186:187], 0, s[56:57]
	s_mov_b32 m0, s14
	ds_read_b128 v[160:163], v225 offset:49152
	ds_read_b128 v[164:167], v225 offset:50176
	ds_read_b128 v[168:171], v225 offset:51200
	ds_read_b128 v[172:175], v225 offset:52224
	ds_read_b128 v[176:179], v225 offset:53248
	ds_read_b128 v[180:183], v225 offset:54272
	ds_read_b128 v[200:203], v225 offset:55296
	ds_read_b128 v[204:207], v225 offset:56320
	global_load_lds_dwordx4 v[186:187], off
	v_lshl_add_u64 v[186:187], v[188:189], 0, s[56:57]
	s_add_i32 m0, s14, 0x2000
	s_add_i32 s14, s21, s27
	global_load_lds_dwordx4 v[186:187], off
	v_lshl_add_u64 v[186:187], v[208:209], 0, s[56:57]
	s_mov_b32 m0, s14
	s_nop 0
	global_load_lds_dwordx4 v[186:187], off
	v_lshl_add_u64 v[186:187], v[210:211], 0, s[56:57]
	s_add_i32 m0, s14, 0x2000
	s_nop 0
	global_load_lds_dwordx4 v[186:187], off
	v_lshl_add_u64 v[186:187], v[212:213], 0, s[56:57]
	s_mov_b32 m0, s19
	s_nop 0
	global_load_lds_dwordx4 v[186:187], off
	v_lshl_add_u64 v[186:187], v[214:215], 0, s[56:57]
	s_mov_b32 m0, s20
	s_nop 0
	global_load_lds_dwordx4 v[186:187], off
	s_waitcnt vmcnt(14)
	s_waitcnt lgkmcnt(0)
	s_barrier
	s_setprio 1
	s_waitcnt lgkmcnt(0)
	v_mfma_f32_16x16x32_bf16 v[60:63], v[128:131], v[160:163], v[60:63]
	v_mfma_f32_16x16x32_bf16 v[56:59], v[136:139], v[160:163], v[56:59]
	v_mfma_f32_16x16x32_bf16 v[44:47], v[128:131], v[168:171], v[44:47]
	v_mfma_f32_16x16x32_bf16 v[40:43], v[136:139], v[168:171], v[40:43]
	v_mfma_f32_16x16x32_bf16 v[28:31], v[128:131], v[176:179], v[28:31]
	v_mfma_f32_16x16x32_bf16 v[24:27], v[136:139], v[176:179], v[24:27]
	v_mfma_f32_16x16x32_bf16 v[12:15], v[128:131], v[200:203], v[12:15]
	v_mfma_f32_16x16x32_bf16 v[8:11], v[136:139], v[200:203], v[8:11]
	v_mfma_f32_16x16x32_bf16 v[60:63], v[132:135], v[164:167], v[60:63]
	v_mfma_f32_16x16x32_bf16 v[56:59], v[140:143], v[164:167], v[56:59]
	v_mfma_f32_16x16x32_bf16 v[44:47], v[132:135], v[172:175], v[44:47]
	v_mfma_f32_16x16x32_bf16 v[40:43], v[140:143], v[172:175], v[40:43]
	v_mfma_f32_16x16x32_bf16 v[28:31], v[132:135], v[180:183], v[28:31]
	v_mfma_f32_16x16x32_bf16 v[24:27], v[140:143], v[180:183], v[24:27]
	v_mfma_f32_16x16x32_bf16 v[12:15], v[132:135], v[204:207], v[12:15]
	v_mfma_f32_16x16x32_bf16 v[8:11], v[140:143], v[204:207], v[8:11]
	s_setprio 0
	s_setprio 1
	v_mfma_f32_16x16x32_bf16 v[52:55], v[144:147], v[160:163], v[52:55]
	v_mfma_f32_16x16x32_bf16 v[48:51], v[152:155], v[160:163], v[48:51]
	v_mfma_f32_16x16x32_bf16 v[36:39], v[144:147], v[168:171], v[36:39]
	v_mfma_f32_16x16x32_bf16 v[32:35], v[152:155], v[168:171], v[32:35]
	v_mfma_f32_16x16x32_bf16 v[20:23], v[144:147], v[176:179], v[20:23]
	v_mfma_f32_16x16x32_bf16 v[16:19], v[152:155], v[176:179], v[16:19]
	v_mfma_f32_16x16x32_bf16 v[4:7], v[144:147], v[200:203], v[4:7]
	v_mfma_f32_16x16x32_bf16 v[0:3], v[152:155], v[200:203], v[0:3]
	v_mfma_f32_16x16x32_bf16 v[52:55], v[148:151], v[164:167], v[52:55]
	v_mfma_f32_16x16x32_bf16 v[48:51], v[156:159], v[164:167], v[48:51]
	v_mfma_f32_16x16x32_bf16 v[36:39], v[148:151], v[172:175], v[36:39]
	v_mfma_f32_16x16x32_bf16 v[32:35], v[156:159], v[172:175], v[32:35]
	v_mfma_f32_16x16x32_bf16 v[20:23], v[148:151], v[180:183], v[20:23]
	v_mfma_f32_16x16x32_bf16 v[16:19], v[156:159], v[180:183], v[16:19]
	v_mfma_f32_16x16x32_bf16 v[4:7], v[148:151], v[204:207], v[4:7]
	v_mfma_f32_16x16x32_bf16 v[0:3], v[156:159], v[204:207], v[0:3]
	s_setprio 0
	s_barrier
	s_add_u32 vcc_lo, vcc_lo, 0x100
	s_addc_u32 vcc_hi, vcc_hi, 0
	s_add_u32 s16, s16, 0x100
	s_addc_u32 s17, s17, 0
	s_cmp_ge_u32 s24, s84
	s_mov_b32 s14, s24
	s_cbranch_scc0 .LBB0_362
	s_and_b64 vcc, exec, s[60:61]
	s_cbranch_vccz .LBB0_365
	s_barrier

.Lnostb5:
	s_add_i32 s23, s14, 2
	s_add_u32 s24, s44, 0x80
	s_addc_u32 s15, s45, 0
	s_add_i32 s49, 0, 0x10000
	s_cmp_eq_u32 s31, s14
	s_cselect_b32 s15, s1, s15
	s_cselect_b32 s14, s0, s24
	s_cselect_b32 s51, s43, s17
	s_cselect_b32 s50, s42, s16
	s_add_i32 s24, 0, 0x14000
	v_add_u32_e32 v108, s49, v249
	v_add_u32_e32 v140, s24, v249
	ds_read_b128 v[80:83], v108
	ds_read_b128 v[84:87], v108 offset:1024
	ds_read_b128 v[104:107], v108 offset:2048
	ds_read_b128 v[108:111], v108 offset:3072
	ds_read_b128 v[124:127], v140
	ds_read_b128 v[132:135], v140 offset:1024
	ds_read_b128 v[136:139], v140 offset:2048
	ds_read_b128 v[140:143], v140 offset:3072
	v_lshl_add_u64 v[208:209], s[44:45], 0, v[196:197]
	s_add_i32 m0, s20, 0xc000
	ds_read_b128 v[144:147], v251
	ds_read_b128 v[148:151], v251 offset:1024
	ds_read_b128 v[152:155], v251 offset:2048
	ds_read_b128 v[156:159], v251 offset:3072
	ds_read_b128 v[160:163], v251 offset:4096
	ds_read_b128 v[164:167], v251 offset:5120
	ds_read_b128 v[200:203], v251 offset:6144
	ds_read_b128 v[204:207], v251 offset:7168
	global_load_lds_dwordx4 v[208:209], off
	v_lshl_add_u64 v[208:209], s[44:45], 0, v[198:199]
	s_add_i32 m0, s20, 0xe000
	s_nop 0
	global_load_lds_dwordx4 v[208:209], off
	s_waitcnt vmcnt(10)
	s_waitcnt lgkmcnt(0)
	s_barrier
	s_setprio 1
	s_waitcnt lgkmcnt(0)
	v_mfma_f32_16x16x32_bf16 v[180:183], v[80:83], v[144:147], 0
	v_mfma_f32_16x16x32_bf16 v[176:179], v[104:107], v[144:147], 0
	v_mfma_f32_16x16x32_bf16 v[128:131], v[80:83], v[152:155], 0
	v_mfma_f32_16x16x32_bf16 v[120:123], v[104:107], v[152:155], 0
	v_mfma_f32_16x16x32_bf16 v[100:103], v[80:83], v[160:163], 0
	v_mfma_f32_16x16x32_bf16 v[96:99], v[104:107], v[160:163], 0
	v_mfma_f32_16x16x32_bf16 v[76:79], v[80:83], v[200:203], 0
	v_mfma_f32_16x16x32_bf16 v[72:75], v[104:107], v[200:203], 0
	v_mfma_f32_16x16x32_bf16 v[180:183], v[84:87], v[148:151], v[180:183]
	v_mfma_f32_16x16x32_bf16 v[176:179], v[108:111], v[148:151], v[176:179]
	v_mfma_f32_16x16x32_bf16 v[128:131], v[84:87], v[156:159], v[128:131]
	v_mfma_f32_16x16x32_bf16 v[120:123], v[108:111], v[156:159], v[120:123]
	v_mfma_f32_16x16x32_bf16 v[100:103], v[84:87], v[164:167], v[100:103]
	v_mfma_f32_16x16x32_bf16 v[96:99], v[108:111], v[164:167], v[96:99]
	v_mfma_f32_16x16x32_bf16 v[76:79], v[84:87], v[204:207], v[76:79]
	v_mfma_f32_16x16x32_bf16 v[72:75], v[108:111], v[204:207], v[72:75]
	s_setprio 0
	s_setprio 1
	v_mfma_f32_16x16x32_bf16 v[172:175], v[124:127], v[144:147], 0
	v_mfma_f32_16x16x32_bf16 v[116:119], v[124:127], v[152:155], 0
	v_mfma_f32_16x16x32_bf16 v[112:115], v[136:139], v[152:155], 0
	v_mfma_f32_16x16x32_bf16 v[92:95], v[124:127], v[160:163], 0
	v_mfma_f32_16x16x32_bf16 v[88:91], v[136:139], v[160:163], 0
	v_mfma_f32_16x16x32_bf16 v[68:71], v[124:127], v[200:203], 0
	v_mfma_f32_16x16x32_bf16 v[64:67], v[136:139], v[200:203], 0
	v_mfma_f32_16x16x32_bf16 v[172:175], v[132:135], v[148:151], v[172:175]
	v_mfma_f32_16x16x32_bf16 v[144:147], v[136:139], v[144:147], 0
	v_mfma_f32_16x16x32_bf16 v[116:119], v[132:135], v[156:159], v[116:119]
	v_mfma_f32_16x16x32_bf16 v[112:115], v[140:143], v[156:159], v[112:115]
	v_mfma_f32_16x16x32_bf16 v[92:95], v[132:135], v[164:167], v[92:95]
	v_mfma_f32_16x16x32_bf16 v[88:91], v[140:143], v[164:167], v[88:91]
	v_mfma_f32_16x16x32_bf16 v[68:71], v[132:135], v[204:207], v[68:71]
	v_mfma_f32_16x16x32_bf16 v[64:67], v[140:143], v[204:207], v[64:67]
	v_mfma_f32_16x16x32_bf16 v[144:147], v[140:143], v[148:151], v[144:147]
	s_setprio 0
	s_barrier
	s_add_i32 s49, s49, s19
	v_lshl_add_u64 v[212:213], s[50:51], 0, v[184:185]
	s_mov_b32 m0, s49
	ds_read_b128 v[148:151], v251 offset:16384
	ds_read_b128 v[152:155], v251 offset:17408
	ds_read_b128 v[156:159], v251 offset:18432
	ds_read_b128 v[160:163], v251 offset:19456
	ds_read_b128 v[164:167], v251 offset:20480
	ds_read_b128 v[168:171], v251 offset:21504
	ds_read_b128 v[200:203], v251 offset:22528
	ds_read_b128 v[204:207], v251 offset:23552
	global_load_lds_dwordx4 v[212:213], off
	s_add_i32 m0, s49, 0x2000
	s_add_u32 s50, s50, s8
	v_lshl_add_u64 v[214:215], v[212:213], 0, s[70:71]
	s_addc_u32 s51, s51, 0
	s_add_i32 s24, s24, s19
	global_load_lds_dwordx4 v[214:215], off
	v_lshl_add_u64 v[216:217], s[50:51], 0, v[184:185]
	s_mov_b32 m0, s24
	v_lshl_add_u64 v[218:219], v[216:217], 0, s[70:71]
	global_load_lds_dwordx4 v[216:217], off
	s_add_i32 m0, s24, 0x2000
	v_lshl_add_u64 v[220:221], s[14:15], 0, v[194:195]
	global_load_lds_dwordx4 v[218:219], off
	s_mov_b32 m0, s20
	v_lshl_add_u64 v[222:223], v[220:221], 0, s[70:71]
	global_load_lds_dwordx4 v[220:221], off
	s_mov_b32 m0, s25
	s_nop 0
	global_load_lds_dwordx4 v[222:223], off
	s_waitcnt vmcnt(14)
	s_waitcnt lgkmcnt(0)
	s_barrier
	s_setprio 1
	s_waitcnt lgkmcnt(0)
	v_mfma_f32_16x16x32_bf16 v[60:63], v[80:83], v[148:151], 0
	v_mfma_f32_16x16x32_bf16 v[56:59], v[104:107], v[148:151], 0
	v_mfma_f32_16x16x32_bf16 v[44:47], v[80:83], v[156:159], 0
	v_mfma_f32_16x16x32_bf16 v[40:43], v[104:107], v[156:159], 0
	v_mfma_f32_16x16x32_bf16 v[28:31], v[80:83], v[164:167], 0
	v_mfma_f32_16x16x32_bf16 v[24:27], v[104:107], v[164:167], 0
	v_mfma_f32_16x16x32_bf16 v[12:15], v[80:83], v[200:203], 0
	v_mfma_f32_16x16x32_bf16 v[8:11], v[104:107], v[200:203], 0
	v_mfma_f32_16x16x32_bf16 v[60:63], v[84:87], v[152:155], v[60:63]
	v_mfma_f32_16x16x32_bf16 v[56:59], v[108:111], v[152:155], v[56:59]
	v_mfma_f32_16x16x32_bf16 v[44:47], v[84:87], v[160:163], v[44:47]
	v_mfma_f32_16x16x32_bf16 v[40:43], v[108:111], v[160:163], v[40:43]
	v_mfma_f32_16x16x32_bf16 v[28:31], v[84:87], v[168:171], v[28:31]
	v_mfma_f32_16x16x32_bf16 v[24:27], v[108:111], v[168:171], v[24:27]
	v_mfma_f32_16x16x32_bf16 v[12:15], v[84:87], v[204:207], v[12:15]
	v_mfma_f32_16x16x32_bf16 v[8:11], v[108:111], v[204:207], v[8:11]
	s_setprio 0
	s_setprio 1
	v_mfma_f32_16x16x32_bf16 v[52:55], v[124:127], v[148:151], 0
	v_mfma_f32_16x16x32_bf16 v[48:51], v[136:139], v[148:151], 0
	v_mfma_f32_16x16x32_bf16 v[36:39], v[124:127], v[156:159], 0
	v_mfma_f32_16x16x32_bf16 v[32:35], v[136:139], v[156:159], 0
	v_mfma_f32_16x16x32_bf16 v[20:23], v[124:127], v[164:167], 0
	v_mfma_f32_16x16x32_bf16 v[16:19], v[136:139], v[164:167], 0
	v_mfma_f32_16x16x32_bf16 v[4:7], v[124:127], v[200:203], 0
	v_mfma_f32_16x16x32_bf16 v[0:3], v[136:139], v[200:203], 0
	v_mfma_f32_16x16x32_bf16 v[52:55], v[132:135], v[152:155], v[52:55]
	v_mfma_f32_16x16x32_bf16 v[48:51], v[140:143], v[152:155], v[48:51]
	v_mfma_f32_16x16x32_bf16 v[36:39], v[132:135], v[160:163], v[36:39]
	v_mfma_f32_16x16x32_bf16 v[32:35], v[140:143], v[160:163], v[32:35]
	v_mfma_f32_16x16x32_bf16 v[20:23], v[132:135], v[168:171], v[20:23]
	v_mfma_f32_16x16x32_bf16 v[16:19], v[140:143], v[168:171], v[16:19]
	v_mfma_f32_16x16x32_bf16 v[4:7], v[132:135], v[204:207], v[4:7]
	v_mfma_f32_16x16x32_bf16 v[0:3], v[140:143], v[204:207], v[0:3]
	s_setprio 0
	s_barrier
	s_add_i32 s24, 0, 0x18000
	s_add_i32 s49, 0, 0x1c000
	v_add_u32_e32 v108, s24, v249
	v_add_u32_e32 v140, s49, v249
	ds_read_b128 v[80:83], v108
	ds_read_b128 v[84:87], v108 offset:1024
	ds_read_b128 v[104:107], v108 offset:2048
	ds_read_b128 v[108:111], v108 offset:3072
	ds_read_b128 v[124:127], v140
	ds_read_b128 v[132:135], v140 offset:1024
	ds_read_b128 v[136:139], v140 offset:2048
	ds_read_b128 v[140:143], v140 offset:3072
	s_add_u32 s14, s14, s8
	s_addc_u32 s15, s15, 0
	s_mov_b32 m0, s26
	v_lshl_add_u64 v[168:169], s[14:15], 0, v[194:195]
	ds_read_b128 v[148:151], v251 offset:32768
	ds_read_b128 v[152:155], v251 offset:33792
	ds_read_b128 v[156:159], v251 offset:34816
	ds_read_b128 v[160:163], v251 offset:35840
	ds_read_b128 v[164:167], v251 offset:36864
	ds_read_b128 v[200:203], v251 offset:37888
	ds_read_b128 v[204:207], v251 offset:38912
	ds_read_b128 v[208:211], v251 offset:39936
	global_load_lds_dwordx4 v[168:169], off
	v_lshl_add_u64 v[168:169], v[168:169], 0, s[70:71]
	s_mov_b32 m0, s27
	s_nop 0
	global_load_lds_dwordx4 v[168:169], off
	s_waitcnt vmcnt(10)
	s_waitcnt lgkmcnt(0)
	s_barrier
	s_setprio 1
	s_waitcnt lgkmcnt(0)
	v_mfma_f32_16x16x32_bf16 v[168:171], v[80:83], v[148:151], v[180:183]
	v_mfma_f32_16x16x32_bf16 v[180:183], v[84:87], v[152:155], v[168:171]
	v_mfma_f32_16x16x32_bf16 v[168:171], v[104:107], v[148:151], v[176:179]
	v_mfma_f32_16x16x32_bf16 v[128:131], v[80:83], v[156:159], v[128:131]
	v_mfma_f32_16x16x32_bf16 v[120:123], v[104:107], v[156:159], v[120:123]
	v_mfma_f32_16x16x32_bf16 v[100:103], v[80:83], v[164:167], v[100:103]
	v_mfma_f32_16x16x32_bf16 v[96:99], v[104:107], v[164:167], v[96:99]
	v_mfma_f32_16x16x32_bf16 v[76:79], v[80:83], v[204:207], v[76:79]
	v_mfma_f32_16x16x32_bf16 v[72:75], v[104:107], v[204:207], v[72:75]
	v_mfma_f32_16x16x32_bf16 v[176:179], v[108:111], v[152:155], v[168:171]
	v_mfma_f32_16x16x32_bf16 v[128:131], v[84:87], v[160:163], v[128:131]
	v_mfma_f32_16x16x32_bf16 v[120:123], v[108:111], v[160:163], v[120:123]
	v_mfma_f32_16x16x32_bf16 v[100:103], v[84:87], v[200:203], v[100:103]
	v_mfma_f32_16x16x32_bf16 v[96:99], v[108:111], v[200:203], v[96:99]
	v_mfma_f32_16x16x32_bf16 v[76:79], v[84:87], v[208:211], v[76:79]
	v_mfma_f32_16x16x32_bf16 v[72:75], v[108:111], v[208:211], v[72:75]
	s_setprio 0
	s_setprio 1
	v_mfma_f32_16x16x32_bf16 v[168:171], v[124:127], v[148:151], v[172:175]
	v_mfma_f32_16x16x32_bf16 v[144:147], v[136:139], v[148:151], v[144:147]
	v_mfma_f32_16x16x32_bf16 v[116:119], v[124:127], v[156:159], v[116:119]
	v_mfma_f32_16x16x32_bf16 v[112:115], v[136:139], v[156:159], v[112:115]
	v_mfma_f32_16x16x32_bf16 v[92:95], v[124:127], v[164:167], v[92:95]
	v_mfma_f32_16x16x32_bf16 v[88:91], v[136:139], v[164:167], v[88:91]
	v_mfma_f32_16x16x32_bf16 v[68:71], v[124:127], v[204:207], v[68:71]
	v_mfma_f32_16x16x32_bf16 v[64:67], v[136:139], v[204:207], v[64:67]
	v_mfma_f32_16x16x32_bf16 v[172:175], v[132:135], v[152:155], v[168:171]
	v_mfma_f32_16x16x32_bf16 v[168:171], v[140:143], v[152:155], v[144:147]
	v_mfma_f32_16x16x32_bf16 v[116:119], v[132:135], v[160:163], v[116:119]
	v_mfma_f32_16x16x32_bf16 v[112:115], v[140:143], v[160:163], v[112:115]
	v_mfma_f32_16x16x32_bf16 v[92:95], v[132:135], v[200:203], v[92:95]
	v_mfma_f32_16x16x32_bf16 v[88:91], v[140:143], v[200:203], v[88:91]
	v_mfma_f32_16x16x32_bf16 v[68:71], v[132:135], v[208:211], v[68:71]
	v_mfma_f32_16x16x32_bf16 v[64:67], v[140:143], v[208:211], v[64:67]
	s_setprio 0
	s_barrier
	s_add_i32 s14, s24, s19
	v_lshl_add_u64 v[208:209], v[212:213], 0, s[56:57]
	s_mov_b32 m0, s14
	ds_read_b128 v[144:147], v251 offset:49152
	ds_read_b128 v[148:151], v251 offset:50176
	ds_read_b128 v[152:155], v251 offset:51200
	ds_read_b128 v[156:159], v251 offset:52224
	ds_read_b128 v[160:163], v251 offset:53248
	ds_read_b128 v[164:167], v251 offset:54272
	ds_read_b128 v[200:203], v251 offset:55296
	ds_read_b128 v[204:207], v251 offset:56320
	global_load_lds_dwordx4 v[208:209], off
	v_lshl_add_u64 v[208:209], v[214:215], 0, s[56:57]
	s_add_i32 m0, s14, 0x2000
	s_add_i32 s14, s49, s19
	global_load_lds_dwordx4 v[208:209], off
	v_lshl_add_u64 v[208:209], v[216:217], 0, s[56:57]
	s_mov_b32 m0, s14
	s_nop 0
	global_load_lds_dwordx4 v[208:209], off
	v_lshl_add_u64 v[208:209], v[218:219], 0, s[56:57]
	s_add_i32 m0, s14, 0x2000
	s_nop 0
	global_load_lds_dwordx4 v[208:209], off
	v_lshl_add_u64 v[208:209], v[220:221], 0, s[56:57]
	s_mov_b32 m0, s29
	s_nop 0
	global_load_lds_dwordx4 v[208:209], off
	v_lshl_add_u64 v[208:209], v[222:223], 0, s[56:57]
	s_mov_b32 m0, s30
	s_nop 0
	global_load_lds_dwordx4 v[208:209], off
	s_waitcnt vmcnt(14)
	s_waitcnt lgkmcnt(0)
	s_barrier
	s_setprio 1
	s_waitcnt lgkmcnt(0)
	v_mfma_f32_16x16x32_bf16 v[60:63], v[80:83], v[144:147], v[60:63]
	v_mfma_f32_16x16x32_bf16 v[56:59], v[104:107], v[144:147], v[56:59]
	v_mfma_f32_16x16x32_bf16 v[44:47], v[80:83], v[152:155], v[44:47]
	v_mfma_f32_16x16x32_bf16 v[40:43], v[104:107], v[152:155], v[40:43]
	v_mfma_f32_16x16x32_bf16 v[28:31], v[80:83], v[160:163], v[28:31]
	v_mfma_f32_16x16x32_bf16 v[24:27], v[104:107], v[160:163], v[24:27]
	v_mfma_f32_16x16x32_bf16 v[12:15], v[80:83], v[200:203], v[12:15]
	v_mfma_f32_16x16x32_bf16 v[8:11], v[104:107], v[200:203], v[8:11]
	v_mfma_f32_16x16x32_bf16 v[60:63], v[84:87], v[148:151], v[60:63]
	v_mfma_f32_16x16x32_bf16 v[56:59], v[108:111], v[148:151], v[56:59]
	v_mfma_f32_16x16x32_bf16 v[44:47], v[84:87], v[156:159], v[44:47]
	v_mfma_f32_16x16x32_bf16 v[40:43], v[108:111], v[156:159], v[40:43]
	v_mfma_f32_16x16x32_bf16 v[28:31], v[84:87], v[164:167], v[28:31]
	v_mfma_f32_16x16x32_bf16 v[24:27], v[108:111], v[164:167], v[24:27]
	v_mfma_f32_16x16x32_bf16 v[12:15], v[84:87], v[204:207], v[12:15]
	v_mfma_f32_16x16x32_bf16 v[8:11], v[108:111], v[204:207], v[8:11]
	s_setprio 0
	s_setprio 1
	v_mfma_f32_16x16x32_bf16 v[52:55], v[124:127], v[144:147], v[52:55]
	v_mfma_f32_16x16x32_bf16 v[48:51], v[136:139], v[144:147], v[48:51]
	v_mfma_f32_16x16x32_bf16 v[36:39], v[124:127], v[152:155], v[36:39]
	v_mfma_f32_16x16x32_bf16 v[32:35], v[136:139], v[152:155], v[32:35]
	v_mfma_f32_16x16x32_bf16 v[20:23], v[124:127], v[160:163], v[20:23]
	v_mfma_f32_16x16x32_bf16 v[16:19], v[136:139], v[160:163], v[16:19]
	v_mfma_f32_16x16x32_bf16 v[4:7], v[124:127], v[200:203], v[4:7]
	v_mfma_f32_16x16x32_bf16 v[0:3], v[136:139], v[200:203], v[0:3]
	v_mfma_f32_16x16x32_bf16 v[52:55], v[132:135], v[148:151], v[52:55]
	v_mfma_f32_16x16x32_bf16 v[48:51], v[140:143], v[148:151], v[48:51]
	v_mfma_f32_16x16x32_bf16 v[36:39], v[132:135], v[156:159], v[36:39]
	v_mfma_f32_16x16x32_bf16 v[32:35], v[140:143], v[156:159], v[32:35]
	v_mfma_f32_16x16x32_bf16 v[20:23], v[132:135], v[164:167], v[20:23]
	v_mfma_f32_16x16x32_bf16 v[16:19], v[140:143], v[164:167], v[16:19]
	v_mfma_f32_16x16x32_bf16 v[4:7], v[132:135], v[204:207], v[4:7]
	v_mfma_f32_16x16x32_bf16 v[0:3], v[140:143], v[204:207], v[0:3]
	s_setprio 0
	s_barrier
	s_add_u32 s44, s44, 0x100
	s_addc_u32 s45, s45, 0
	s_add_u32 s16, s16, 0x100
	s_addc_u32 s17, s17, 0
	s_cmp_ge_u32 s23, s28
	s_mov_b32 s14, s23
.LBB0_422:
	s_add_i32 s23, s14, 2
	s_add_u32 s24, s44, 0x80
	s_addc_u32 s15, s45, 0
	s_add_i32 s49, 0, 0x10000
	s_cmp_eq_u32 s31, s14
	s_cselect_b32 s15, s1, s15
	s_cselect_b32 s14, s0, s24
	s_cselect_b32 s51, s43, s17
	s_cselect_b32 s50, s42, s16
	s_add_i32 s24, 0, 0x14000
	v_add_u32_e32 v108, s49, v249
	v_add_u32_e32 v140, s24, v249
	ds_read_b128 v[80:83], v108
	ds_read_b128 v[84:87], v108 offset:1024
	ds_read_b128 v[104:107], v108 offset:2048
	ds_read_b128 v[108:111], v108 offset:3072
	ds_read_b128 v[124:127], v140
	ds_read_b128 v[132:135], v140 offset:1024
	ds_read_b128 v[136:139], v140 offset:2048
	ds_read_b128 v[140:143], v140 offset:3072
	v_lshl_add_u64 v[208:209], s[44:45], 0, v[196:197]
	s_add_i32 m0, s20, 0xc000
	ds_read_b128 v[144:147], v251
	ds_read_b128 v[148:151], v251 offset:1024
	ds_read_b128 v[152:155], v251 offset:2048
	ds_read_b128 v[156:159], v251 offset:3072
	ds_read_b128 v[160:163], v251 offset:4096
	ds_read_b128 v[164:167], v251 offset:5120
	ds_read_b128 v[200:203], v251 offset:6144
	ds_read_b128 v[204:207], v251 offset:7168
	global_load_lds_dwordx4 v[208:209], off
	v_lshl_add_u64 v[208:209], s[44:45], 0, v[198:199]
	s_add_i32 m0, s20, 0xe000
	s_nop 0
	global_load_lds_dwordx4 v[208:209], off
	s_waitcnt vmcnt(10)
	s_waitcnt lgkmcnt(0)
	s_barrier
	s_setprio 1
	s_waitcnt lgkmcnt(0)
	v_mfma_f32_16x16x32_bf16 v[180:183], v[80:83], v[144:147], v[180:183]
	v_mfma_f32_16x16x32_bf16 v[176:179], v[104:107], v[144:147], v[176:179]
	v_mfma_f32_16x16x32_bf16 v[128:131], v[80:83], v[152:155], v[128:131]
	v_mfma_f32_16x16x32_bf16 v[120:123], v[104:107], v[152:155], v[120:123]
	v_mfma_f32_16x16x32_bf16 v[100:103], v[80:83], v[160:163], v[100:103]
	v_mfma_f32_16x16x32_bf16 v[96:99], v[104:107], v[160:163], v[96:99]
	v_mfma_f32_16x16x32_bf16 v[76:79], v[80:83], v[200:203], v[76:79]
	v_mfma_f32_16x16x32_bf16 v[72:75], v[104:107], v[200:203], v[72:75]
	v_mfma_f32_16x16x32_bf16 v[180:183], v[84:87], v[148:151], v[180:183]
	v_mfma_f32_16x16x32_bf16 v[176:179], v[108:111], v[148:151], v[176:179]
	v_mfma_f32_16x16x32_bf16 v[128:131], v[84:87], v[156:159], v[128:131]
	v_mfma_f32_16x16x32_bf16 v[120:123], v[108:111], v[156:159], v[120:123]
	v_mfma_f32_16x16x32_bf16 v[100:103], v[84:87], v[164:167], v[100:103]
	v_mfma_f32_16x16x32_bf16 v[96:99], v[108:111], v[164:167], v[96:99]
	v_mfma_f32_16x16x32_bf16 v[76:79], v[84:87], v[204:207], v[76:79]
	v_mfma_f32_16x16x32_bf16 v[72:75], v[108:111], v[204:207], v[72:75]
	s_setprio 0
	s_setprio 1
	v_mfma_f32_16x16x32_bf16 v[172:175], v[124:127], v[144:147], v[172:175]
	v_mfma_f32_16x16x32_bf16 v[116:119], v[124:127], v[152:155], v[116:119]
	v_mfma_f32_16x16x32_bf16 v[112:115], v[136:139], v[152:155], v[112:115]
	v_mfma_f32_16x16x32_bf16 v[92:95], v[124:127], v[160:163], v[92:95]
	v_mfma_f32_16x16x32_bf16 v[88:91], v[136:139], v[160:163], v[88:91]
	v_mfma_f32_16x16x32_bf16 v[68:71], v[124:127], v[200:203], v[68:71]
	v_mfma_f32_16x16x32_bf16 v[64:67], v[136:139], v[200:203], v[64:67]
	v_mfma_f32_16x16x32_bf16 v[172:175], v[132:135], v[148:151], v[172:175]
	v_mfma_f32_16x16x32_bf16 v[144:147], v[136:139], v[144:147], v[168:171]
	v_mfma_f32_16x16x32_bf16 v[116:119], v[132:135], v[156:159], v[116:119]
	v_mfma_f32_16x16x32_bf16 v[112:115], v[140:143], v[156:159], v[112:115]
	v_mfma_f32_16x16x32_bf16 v[92:95], v[132:135], v[164:167], v[92:95]
	v_mfma_f32_16x16x32_bf16 v[88:91], v[140:143], v[164:167], v[88:91]
	v_mfma_f32_16x16x32_bf16 v[68:71], v[132:135], v[204:207], v[68:71]
	v_mfma_f32_16x16x32_bf16 v[64:67], v[140:143], v[204:207], v[64:67]
	v_mfma_f32_16x16x32_bf16 v[144:147], v[140:143], v[148:151], v[144:147]
	s_setprio 0
	s_barrier
	s_add_i32 s49, s49, s19
	v_lshl_add_u64 v[212:213], s[50:51], 0, v[184:185]
	s_mov_b32 m0, s49
	ds_read_b128 v[148:151], v251 offset:16384
	ds_read_b128 v[152:155], v251 offset:17408
	ds_read_b128 v[156:159], v251 offset:18432
	ds_read_b128 v[160:163], v251 offset:19456
	ds_read_b128 v[164:167], v251 offset:20480
	ds_read_b128 v[168:171], v251 offset:21504
	ds_read_b128 v[200:203], v251 offset:22528
	ds_read_b128 v[204:207], v251 offset:23552
	global_load_lds_dwordx4 v[212:213], off
	s_add_i32 m0, s49, 0x2000
	s_add_u32 s50, s50, s8
	v_lshl_add_u64 v[214:215], v[212:213], 0, s[70:71]
	s_addc_u32 s51, s51, 0
	s_add_i32 s24, s24, s19
	global_load_lds_dwordx4 v[214:215], off
	v_lshl_add_u64 v[216:217], s[50:51], 0, v[184:185]
	s_mov_b32 m0, s24
	v_lshl_add_u64 v[218:219], v[216:217], 0, s[70:71]
	global_load_lds_dwordx4 v[216:217], off
	s_add_i32 m0, s24, 0x2000
	v_lshl_add_u64 v[220:221], s[14:15], 0, v[194:195]
	global_load_lds_dwordx4 v[218:219], off
	s_mov_b32 m0, s20
	v_lshl_add_u64 v[222:223], v[220:221], 0, s[70:71]
	global_load_lds_dwordx4 v[220:221], off
	s_mov_b32 m0, s25
	s_nop 0
	global_load_lds_dwordx4 v[222:223], off
	s_waitcnt vmcnt(14)
	s_waitcnt lgkmcnt(0)
	s_barrier
	s_setprio 1
	s_waitcnt lgkmcnt(0)
	v_mfma_f32_16x16x32_bf16 v[60:63], v[80:83], v[148:151], v[60:63]
	v_mfma_f32_16x16x32_bf16 v[56:59], v[104:107], v[148:151], v[56:59]
	v_mfma_f32_16x16x32_bf16 v[44:47], v[80:83], v[156:159], v[44:47]
	v_mfma_f32_16x16x32_bf16 v[40:43], v[104:107], v[156:159], v[40:43]
	v_mfma_f32_16x16x32_bf16 v[28:31], v[80:83], v[164:167], v[28:31]
	v_mfma_f32_16x16x32_bf16 v[24:27], v[104:107], v[164:167], v[24:27]
	v_mfma_f32_16x16x32_bf16 v[12:15], v[80:83], v[200:203], v[12:15]
	v_mfma_f32_16x16x32_bf16 v[8:11], v[104:107], v[200:203], v[8:11]
	v_mfma_f32_16x16x32_bf16 v[60:63], v[84:87], v[152:155], v[60:63]
	v_mfma_f32_16x16x32_bf16 v[56:59], v[108:111], v[152:155], v[56:59]
	v_mfma_f32_16x16x32_bf16 v[44:47], v[84:87], v[160:163], v[44:47]
	v_mfma_f32_16x16x32_bf16 v[40:43], v[108:111], v[160:163], v[40:43]
	v_mfma_f32_16x16x32_bf16 v[28:31], v[84:87], v[168:171], v[28:31]
	v_mfma_f32_16x16x32_bf16 v[24:27], v[108:111], v[168:171], v[24:27]
	v_mfma_f32_16x16x32_bf16 v[12:15], v[84:87], v[204:207], v[12:15]
	v_mfma_f32_16x16x32_bf16 v[8:11], v[108:111], v[204:207], v[8:11]
	s_setprio 0
	s_setprio 1
	v_mfma_f32_16x16x32_bf16 v[52:55], v[124:127], v[148:151], v[52:55]
	v_mfma_f32_16x16x32_bf16 v[48:51], v[136:139], v[148:151], v[48:51]
	v_mfma_f32_16x16x32_bf16 v[36:39], v[124:127], v[156:159], v[36:39]
	v_mfma_f32_16x16x32_bf16 v[32:35], v[136:139], v[156:159], v[32:35]
	v_mfma_f32_16x16x32_bf16 v[20:23], v[124:127], v[164:167], v[20:23]
	v_mfma_f32_16x16x32_bf16 v[16:19], v[136:139], v[164:167], v[16:19]
	v_mfma_f32_16x16x32_bf16 v[4:7], v[124:127], v[200:203], v[4:7]
	v_mfma_f32_16x16x32_bf16 v[0:3], v[136:139], v[200:203], v[0:3]
	v_mfma_f32_16x16x32_bf16 v[52:55], v[132:135], v[152:155], v[52:55]
	v_mfma_f32_16x16x32_bf16 v[48:51], v[140:143], v[152:155], v[48:51]
	v_mfma_f32_16x16x32_bf16 v[36:39], v[132:135], v[160:163], v[36:39]
	v_mfma_f32_16x16x32_bf16 v[32:35], v[140:143], v[160:163], v[32:35]
	v_mfma_f32_16x16x32_bf16 v[20:23], v[132:135], v[168:171], v[20:23]
	v_mfma_f32_16x16x32_bf16 v[16:19], v[140:143], v[168:171], v[16:19]
	v_mfma_f32_16x16x32_bf16 v[4:7], v[132:135], v[204:207], v[4:7]
	v_mfma_f32_16x16x32_bf16 v[0:3], v[140:143], v[204:207], v[0:3]
	s_setprio 0
	s_barrier
	s_add_i32 s24, 0, 0x18000
	s_add_i32 s49, 0, 0x1c000
	v_add_u32_e32 v108, s24, v249
	v_add_u32_e32 v140, s49, v249
	ds_read_b128 v[80:83], v108
	ds_read_b128 v[84:87], v108 offset:1024
	ds_read_b128 v[104:107], v108 offset:2048
	ds_read_b128 v[108:111], v108 offset:3072
	ds_read_b128 v[124:127], v140
	ds_read_b128 v[132:135], v140 offset:1024
	ds_read_b128 v[136:139], v140 offset:2048
	ds_read_b128 v[140:143], v140 offset:3072
	s_add_u32 s14, s14, s8
	s_addc_u32 s15, s15, 0
	s_mov_b32 m0, s26
	v_lshl_add_u64 v[168:169], s[14:15], 0, v[194:195]
	ds_read_b128 v[148:151], v251 offset:32768
	ds_read_b128 v[152:155], v251 offset:33792
	ds_read_b128 v[156:159], v251 offset:34816
	ds_read_b128 v[160:163], v251 offset:35840
	ds_read_b128 v[164:167], v251 offset:36864
	ds_read_b128 v[200:203], v251 offset:37888
	ds_read_b128 v[204:207], v251 offset:38912
	ds_read_b128 v[208:211], v251 offset:39936
	global_load_lds_dwordx4 v[168:169], off
	v_lshl_add_u64 v[168:169], v[168:169], 0, s[70:71]
	s_mov_b32 m0, s27
	s_nop 0
	global_load_lds_dwordx4 v[168:169], off
	s_waitcnt vmcnt(10)
	s_waitcnt lgkmcnt(0)
	s_barrier
	s_setprio 1
	s_waitcnt lgkmcnt(0)
	v_mfma_f32_16x16x32_bf16 v[168:171], v[80:83], v[148:151], v[180:183]
	v_mfma_f32_16x16x32_bf16 v[180:183], v[84:87], v[152:155], v[168:171]
	v_mfma_f32_16x16x32_bf16 v[168:171], v[104:107], v[148:151], v[176:179]
	v_mfma_f32_16x16x32_bf16 v[128:131], v[80:83], v[156:159], v[128:131]
	v_mfma_f32_16x16x32_bf16 v[120:123], v[104:107], v[156:159], v[120:123]
	v_mfma_f32_16x16x32_bf16 v[100:103], v[80:83], v[164:167], v[100:103]
	v_mfma_f32_16x16x32_bf16 v[96:99], v[104:107], v[164:167], v[96:99]
	v_mfma_f32_16x16x32_bf16 v[76:79], v[80:83], v[204:207], v[76:79]
	v_mfma_f32_16x16x32_bf16 v[72:75], v[104:107], v[204:207], v[72:75]
	v_mfma_f32_16x16x32_bf16 v[176:179], v[108:111], v[152:155], v[168:171]
	v_mfma_f32_16x16x32_bf16 v[128:131], v[84:87], v[160:163], v[128:131]
	v_mfma_f32_16x16x32_bf16 v[120:123], v[108:111], v[160:163], v[120:123]
	v_mfma_f32_16x16x32_bf16 v[100:103], v[84:87], v[200:203], v[100:103]
	v_mfma_f32_16x16x32_bf16 v[96:99], v[108:111], v[200:203], v[96:99]
	v_mfma_f32_16x16x32_bf16 v[76:79], v[84:87], v[208:211], v[76:79]
	v_mfma_f32_16x16x32_bf16 v[72:75], v[108:111], v[208:211], v[72:75]
	s_setprio 0
	s_setprio 1
	v_mfma_f32_16x16x32_bf16 v[168:171], v[124:127], v[148:151], v[172:175]
	v_mfma_f32_16x16x32_bf16 v[144:147], v[136:139], v[148:151], v[144:147]
	v_mfma_f32_16x16x32_bf16 v[116:119], v[124:127], v[156:159], v[116:119]
	v_mfma_f32_16x16x32_bf16 v[112:115], v[136:139], v[156:159], v[112:115]
	v_mfma_f32_16x16x32_bf16 v[92:95], v[124:127], v[164:167], v[92:95]
	v_mfma_f32_16x16x32_bf16 v[88:91], v[136:139], v[164:167], v[88:91]
	v_mfma_f32_16x16x32_bf16 v[68:71], v[124:127], v[204:207], v[68:71]
	v_mfma_f32_16x16x32_bf16 v[64:67], v[136:139], v[204:207], v[64:67]
	v_mfma_f32_16x16x32_bf16 v[172:175], v[132:135], v[152:155], v[168:171]
	v_mfma_f32_16x16x32_bf16 v[168:171], v[140:143], v[152:155], v[144:147]
	v_mfma_f32_16x16x32_bf16 v[116:119], v[132:135], v[160:163], v[116:119]
	v_mfma_f32_16x16x32_bf16 v[112:115], v[140:143], v[160:163], v[112:115]
	v_mfma_f32_16x16x32_bf16 v[92:95], v[132:135], v[200:203], v[92:95]
	v_mfma_f32_16x16x32_bf16 v[88:91], v[140:143], v[200:203], v[88:91]
	v_mfma_f32_16x16x32_bf16 v[68:71], v[132:135], v[208:211], v[68:71]
	v_mfma_f32_16x16x32_bf16 v[64:67], v[140:143], v[208:211], v[64:67]
	s_setprio 0
	s_barrier
	s_add_i32 s14, s24, s19
	v_lshl_add_u64 v[208:209], v[212:213], 0, s[56:57]
	s_mov_b32 m0, s14
	ds_read_b128 v[144:147], v251 offset:49152
	ds_read_b128 v[148:151], v251 offset:50176
	ds_read_b128 v[152:155], v251 offset:51200
	ds_read_b128 v[156:159], v251 offset:52224
	ds_read_b128 v[160:163], v251 offset:53248
	ds_read_b128 v[164:167], v251 offset:54272
	ds_read_b128 v[200:203], v251 offset:55296
	ds_read_b128 v[204:207], v251 offset:56320
	global_load_lds_dwordx4 v[208:209], off
	v_lshl_add_u64 v[208:209], v[214:215], 0, s[56:57]
	s_add_i32 m0, s14, 0x2000
	s_add_i32 s14, s49, s19
	global_load_lds_dwordx4 v[208:209], off
	v_lshl_add_u64 v[208:209], v[216:217], 0, s[56:57]
	s_mov_b32 m0, s14
	s_nop 0
	global_load_lds_dwordx4 v[208:209], off
	v_lshl_add_u64 v[208:209], v[218:219], 0, s[56:57]
	s_add_i32 m0, s14, 0x2000
	s_nop 0
	global_load_lds_dwordx4 v[208:209], off
	v_lshl_add_u64 v[208:209], v[220:221], 0, s[56:57]
	s_mov_b32 m0, s29
	s_nop 0
	global_load_lds_dwordx4 v[208:209], off
	v_lshl_add_u64 v[208:209], v[222:223], 0, s[56:57]
	s_mov_b32 m0, s30
	s_nop 0
	global_load_lds_dwordx4 v[208:209], off
	s_waitcnt vmcnt(14)
	s_waitcnt lgkmcnt(0)
	s_barrier
	s_setprio 1
	s_waitcnt lgkmcnt(0)
	v_mfma_f32_16x16x32_bf16 v[60:63], v[80:83], v[144:147], v[60:63]
	v_mfma_f32_16x16x32_bf16 v[56:59], v[104:107], v[144:147], v[56:59]
	v_mfma_f32_16x16x32_bf16 v[44:47], v[80:83], v[152:155], v[44:47]
	v_mfma_f32_16x16x32_bf16 v[40:43], v[104:107], v[152:155], v[40:43]
	v_mfma_f32_16x16x32_bf16 v[28:31], v[80:83], v[160:163], v[28:31]
	v_mfma_f32_16x16x32_bf16 v[24:27], v[104:107], v[160:163], v[24:27]
	v_mfma_f32_16x16x32_bf16 v[12:15], v[80:83], v[200:203], v[12:15]
	v_mfma_f32_16x16x32_bf16 v[8:11], v[104:107], v[200:203], v[8:11]
	v_mfma_f32_16x16x32_bf16 v[60:63], v[84:87], v[148:151], v[60:63]
	v_mfma_f32_16x16x32_bf16 v[56:59], v[108:111], v[148:151], v[56:59]
	v_mfma_f32_16x16x32_bf16 v[44:47], v[84:87], v[156:159], v[44:47]
	v_mfma_f32_16x16x32_bf16 v[40:43], v[108:111], v[156:159], v[40:43]
	v_mfma_f32_16x16x32_bf16 v[28:31], v[84:87], v[164:167], v[28:31]
	v_mfma_f32_16x16x32_bf16 v[24:27], v[108:111], v[164:167], v[24:27]
	v_mfma_f32_16x16x32_bf16 v[12:15], v[84:87], v[204:207], v[12:15]
	v_mfma_f32_16x16x32_bf16 v[8:11], v[108:111], v[204:207], v[8:11]
	s_setprio 0
	s_setprio 1
	v_mfma_f32_16x16x32_bf16 v[52:55], v[124:127], v[144:147], v[52:55]
	v_mfma_f32_16x16x32_bf16 v[48:51], v[136:139], v[144:147], v[48:51]
	v_mfma_f32_16x16x32_bf16 v[36:39], v[124:127], v[152:155], v[36:39]
	v_mfma_f32_16x16x32_bf16 v[32:35], v[136:139], v[152:155], v[32:35]
	v_mfma_f32_16x16x32_bf16 v[20:23], v[124:127], v[160:163], v[20:23]
	v_mfma_f32_16x16x32_bf16 v[16:19], v[136:139], v[160:163], v[16:19]
	v_mfma_f32_16x16x32_bf16 v[4:7], v[124:127], v[200:203], v[4:7]
	v_mfma_f32_16x16x32_bf16 v[0:3], v[136:139], v[200:203], v[0:3]
	v_mfma_f32_16x16x32_bf16 v[52:55], v[132:135], v[148:151], v[52:55]
	v_mfma_f32_16x16x32_bf16 v[48:51], v[140:143], v[148:151], v[48:51]
	v_mfma_f32_16x16x32_bf16 v[36:39], v[132:135], v[156:159], v[36:39]
	v_mfma_f32_16x16x32_bf16 v[32:35], v[140:143], v[156:159], v[32:35]
	v_mfma_f32_16x16x32_bf16 v[20:23], v[132:135], v[164:167], v[20:23]
	v_mfma_f32_16x16x32_bf16 v[16:19], v[140:143], v[164:167], v[16:19]
	v_mfma_f32_16x16x32_bf16 v[4:7], v[132:135], v[204:207], v[4:7]
	v_mfma_f32_16x16x32_bf16 v[0:3], v[140:143], v[204:207], v[0:3]
	s_setprio 0
	s_barrier
	s_add_u32 s44, s44, 0x100
	s_addc_u32 s45, s45, 0
	s_add_u32 s16, s16, 0x100
	s_addc_u32 s17, s17, 0
	s_cmp_ge_u32 s23, s28
	s_mov_b32 s14, s23
	s_cbranch_scc0 .LBB0_422
	s_and_b64 vcc, exec, s[12:13]
	s_cbranch_vccz .LBB0_425
	s_barrier

.Lnostb6:
	s_add_u32 s14, s48, 0xfffc0080
	s_addc_u32 s15, s49, -1
	s_add_i32 s70, 0, 0x10000
	s_cmp_eq_u32 s51, 12
	s_cselect_b32 s15, s31, s15
	s_cselect_b32 s14, s43, s14
	v_add_u32_e32 v138, s70, v142
	s_cselect_b32 s61, s13, s17
	s_cselect_b32 s60, s50, s16
	s_add_i32 s84, 0, 0x14000
	ds_read_b128 v[134:137], v138
	ds_read_b128 v[148:151], v138 offset:1024
	ds_read_b128 v[152:155], v138 offset:2048
	ds_read_b128 v[156:159], v138 offset:3072
	v_add_u32_e32 v138, s84, v142
	ds_read_b128 v[160:163], v138
	ds_read_b128 v[164:167], v138 offset:1024
	ds_read_b128 v[168:171], v138 offset:2048
	ds_read_b128 v[172:175], v138 offset:3072
	v_lshl_add_u64 v[138:139], s[48:49], 0, v[132:133]
	s_add_i32 m0, s19, 0xc000
	ds_read_b128 v[176:179], v146
	ds_read_b128 v[180:183], v146 offset:1024
	ds_read_b128 v[194:197], v146 offset:2048
	ds_read_b128 v[198:201], v146 offset:3072
	ds_read_b128 v[202:205], v146 offset:4096
	ds_read_b128 v[206:209], v146 offset:5120
	ds_read_b128 v[210:213], v146 offset:6144
	ds_read_b128 v[214:217], v146 offset:7168
	global_load_lds_dwordx4 v[138:139], off
	v_lshl_add_u64 v[138:139], v[138:139], 0, s[34:35]
	s_add_i32 m0, s19, 0xe000
	s_nop 0
	global_load_lds_dwordx4 v[138:139], off
	s_waitcnt vmcnt(10)
	s_waitcnt lgkmcnt(0)
	s_barrier
	s_setprio 1
	s_waitcnt lgkmcnt(0)
	v_mfma_f32_16x16x32_bf16 v[124:127], v[134:137], v[176:179], 0
	v_mfma_f32_16x16x32_bf16 v[116:119], v[152:155], v[176:179], 0
	v_mfma_f32_16x16x32_bf16 v[108:111], v[134:137], v[194:197], 0
	v_mfma_f32_16x16x32_bf16 v[100:103], v[152:155], v[194:197], 0
	v_mfma_f32_16x16x32_bf16 v[92:95], v[134:137], v[202:205], 0
	v_mfma_f32_16x16x32_bf16 v[84:87], v[152:155], v[202:205], 0
	v_mfma_f32_16x16x32_bf16 v[76:79], v[134:137], v[210:213], 0
	v_mfma_f32_16x16x32_bf16 v[68:71], v[152:155], v[210:213], 0
	v_mfma_f32_16x16x32_bf16 v[124:127], v[148:151], v[180:183], v[124:127]
	v_mfma_f32_16x16x32_bf16 v[116:119], v[156:159], v[180:183], v[116:119]
	v_mfma_f32_16x16x32_bf16 v[108:111], v[148:151], v[198:201], v[108:111]
	v_mfma_f32_16x16x32_bf16 v[100:103], v[156:159], v[198:201], v[100:103]
	v_mfma_f32_16x16x32_bf16 v[92:95], v[148:151], v[206:209], v[92:95]
	v_mfma_f32_16x16x32_bf16 v[84:87], v[156:159], v[206:209], v[84:87]
	v_mfma_f32_16x16x32_bf16 v[76:79], v[148:151], v[214:217], v[76:79]
	v_mfma_f32_16x16x32_bf16 v[68:71], v[156:159], v[214:217], v[68:71]
	s_setprio 0
	s_setprio 1
	v_mfma_f32_16x16x32_bf16 v[120:123], v[160:163], v[176:179], 0
	v_mfma_f32_16x16x32_bf16 v[112:115], v[168:171], v[176:179], 0
	v_mfma_f32_16x16x32_bf16 v[104:107], v[160:163], v[194:197], 0
	v_mfma_f32_16x16x32_bf16 v[96:99], v[168:171], v[194:197], 0
	v_mfma_f32_16x16x32_bf16 v[88:91], v[160:163], v[202:205], 0
	v_mfma_f32_16x16x32_bf16 v[80:83], v[168:171], v[202:205], 0
	v_mfma_f32_16x16x32_bf16 v[72:75], v[160:163], v[210:213], 0
	v_mfma_f32_16x16x32_bf16 v[64:67], v[168:171], v[210:213], 0
	v_mfma_f32_16x16x32_bf16 v[120:123], v[164:167], v[180:183], v[120:123]
	v_mfma_f32_16x16x32_bf16 v[112:115], v[172:175], v[180:183], v[112:115]
	v_mfma_f32_16x16x32_bf16 v[104:107], v[164:167], v[198:201], v[104:107]
	v_mfma_f32_16x16x32_bf16 v[96:99], v[172:175], v[198:201], v[96:99]
	v_mfma_f32_16x16x32_bf16 v[88:91], v[164:167], v[206:209], v[88:91]
	v_mfma_f32_16x16x32_bf16 v[80:83], v[172:175], v[206:209], v[80:83]
	v_mfma_f32_16x16x32_bf16 v[72:75], v[164:167], v[214:217], v[72:75]
	v_mfma_f32_16x16x32_bf16 v[64:67], v[172:175], v[214:217], v[64:67]
	s_setprio 0
	s_barrier
	v_lshl_add_u64 v[138:139], s[60:61], 0, v[184:185]
	s_add_i32 s60, s70, s6
	s_mov_b32 m0, s60
	ds_read_b128 v[176:179], v146 offset:16384
	ds_read_b128 v[180:183], v146 offset:17408
	ds_read_b128 v[194:197], v146 offset:18432
	ds_read_b128 v[198:201], v146 offset:19456
	ds_read_b128 v[202:205], v146 offset:20480
	ds_read_b128 v[206:209], v146 offset:21504
	ds_read_b128 v[210:213], v146 offset:22528
	ds_read_b128 v[214:217], v146 offset:23552
	global_load_lds_dwordx4 v[138:139], off
	v_lshl_add_u64 v[218:219], v[138:139], 0, s[34:35]
	s_add_i32 m0, s60, 0x2000
	s_add_i32 s60, s84, s6
	global_load_lds_dwordx4 v[218:219], off
	v_lshl_add_u64 v[218:219], v[138:139], 0, s[92:93]
	s_mov_b32 m0, s60
	s_nop 0
	global_load_lds_dwordx4 v[218:219], off
	v_lshl_add_u64 v[218:219], v[138:139], 0, s[52:53]
	s_add_i32 m0, s60, 0x2000
	s_nop 0
	global_load_lds_dwordx4 v[218:219], off
	v_lshl_add_u64 v[218:219], s[14:15], 0, v[128:129]
	s_mov_b32 m0, s19
	v_lshl_add_u64 v[220:221], v[218:219], 0, s[34:35]
	global_load_lds_dwordx4 v[218:219], off
	s_mov_b32 m0, s20
	s_nop 0
	global_load_lds_dwordx4 v[220:221], off
	s_waitcnt vmcnt(14)
	s_waitcnt lgkmcnt(0)
	s_barrier
	s_setprio 1
	s_waitcnt lgkmcnt(0)
	v_mfma_f32_16x16x32_bf16 v[60:63], v[134:137], v[176:179], 0
	v_mfma_f32_16x16x32_bf16 v[52:55], v[152:155], v[176:179], 0
	v_mfma_f32_16x16x32_bf16 v[44:47], v[134:137], v[194:197], 0
	v_mfma_f32_16x16x32_bf16 v[36:39], v[152:155], v[194:197], 0
	v_mfma_f32_16x16x32_bf16 v[28:31], v[134:137], v[202:205], 0
	v_mfma_f32_16x16x32_bf16 v[20:23], v[152:155], v[202:205], 0
	v_mfma_f32_16x16x32_bf16 v[12:15], v[134:137], v[210:213], 0
	v_mfma_f32_16x16x32_bf16 v[4:7], v[152:155], v[210:213], 0
	v_mfma_f32_16x16x32_bf16 v[60:63], v[148:151], v[180:183], v[60:63]
	v_mfma_f32_16x16x32_bf16 v[52:55], v[156:159], v[180:183], v[52:55]
	v_mfma_f32_16x16x32_bf16 v[44:47], v[148:151], v[198:201], v[44:47]
	v_mfma_f32_16x16x32_bf16 v[36:39], v[156:159], v[198:201], v[36:39]
	v_mfma_f32_16x16x32_bf16 v[28:31], v[148:151], v[206:209], v[28:31]
	v_mfma_f32_16x16x32_bf16 v[20:23], v[156:159], v[206:209], v[20:23]
	v_mfma_f32_16x16x32_bf16 v[12:15], v[148:151], v[214:217], v[12:15]
	v_mfma_f32_16x16x32_bf16 v[4:7], v[156:159], v[214:217], v[4:7]
	s_setprio 0
	s_setprio 1
	v_mfma_f32_16x16x32_bf16 v[56:59], v[160:163], v[176:179], 0
	v_mfma_f32_16x16x32_bf16 v[48:51], v[168:171], v[176:179], 0
	v_mfma_f32_16x16x32_bf16 v[40:43], v[160:163], v[194:197], 0
	v_mfma_f32_16x16x32_bf16 v[32:35], v[168:171], v[194:197], 0
	v_mfma_f32_16x16x32_bf16 v[24:27], v[160:163], v[202:205], 0
	v_mfma_f32_16x16x32_bf16 v[16:19], v[168:171], v[202:205], 0
	v_mfma_f32_16x16x32_bf16 v[8:11], v[160:163], v[210:213], 0
	v_mfma_f32_16x16x32_bf16 v[0:3], v[168:171], v[210:213], 0
	v_mfma_f32_16x16x32_bf16 v[56:59], v[164:167], v[180:183], v[56:59]
	v_mfma_f32_16x16x32_bf16 v[48:51], v[172:175], v[180:183], v[48:51]
	v_mfma_f32_16x16x32_bf16 v[40:43], v[164:167], v[198:201], v[40:43]
	v_mfma_f32_16x16x32_bf16 v[32:35], v[172:175], v[198:201], v[32:35]
	v_mfma_f32_16x16x32_bf16 v[24:27], v[164:167], v[206:209], v[24:27]
	v_mfma_f32_16x16x32_bf16 v[16:19], v[172:175], v[206:209], v[16:19]
	v_mfma_f32_16x16x32_bf16 v[8:11], v[164:167], v[214:217], v[8:11]
	v_mfma_f32_16x16x32_bf16 v[0:3], v[172:175], v[214:217], v[0:3]
	s_setprio 0
	s_barrier
	s_add_i32 s14, 0, 0x18000
	v_add_u32_e32 v147, s14, v142
	s_add_i32 s15, 0, 0x1c000
	ds_read_b128 v[134:137], v147
	ds_read_b128 v[148:151], v147 offset:1024
	ds_read_b128 v[152:155], v147 offset:2048
	ds_read_b128 v[156:159], v147 offset:3072
	v_add_u32_e32 v147, s15, v142
	ds_read_b128 v[160:163], v147
	ds_read_b128 v[164:167], v147 offset:1024
	ds_read_b128 v[168:171], v147 offset:2048
	ds_read_b128 v[172:175], v147 offset:3072
	s_mov_b32 m0, s24
	v_lshl_add_u64 v[220:221], v[218:219], 0, s[92:93]
	ds_read_b128 v[176:179], v146 offset:32768
	ds_read_b128 v[180:183], v146 offset:33792
	ds_read_b128 v[194:197], v146 offset:34816
	ds_read_b128 v[198:201], v146 offset:35840
	ds_read_b128 v[202:205], v146 offset:36864
	ds_read_b128 v[206:209], v146 offset:37888
	ds_read_b128 v[210:213], v146 offset:38912
	ds_read_b128 v[214:217], v146 offset:39936
	global_load_lds_dwordx4 v[220:221], off
	v_lshl_add_u64 v[220:221], v[218:219], 0, s[52:53]
	s_mov_b32 m0, s25
	s_nop 0
	global_load_lds_dwordx4 v[220:221], off
	s_waitcnt vmcnt(10)
	s_waitcnt lgkmcnt(0)
	s_barrier
	s_setprio 1
	s_waitcnt lgkmcnt(0)
	v_mfma_f32_16x16x32_bf16 v[124:127], v[134:137], v[176:179], v[124:127]
	v_mfma_f32_16x16x32_bf16 v[116:119], v[152:155], v[176:179], v[116:119]
	v_mfma_f32_16x16x32_bf16 v[108:111], v[134:137], v[194:197], v[108:111]
	v_mfma_f32_16x16x32_bf16 v[100:103], v[152:155], v[194:197], v[100:103]
	v_mfma_f32_16x16x32_bf16 v[92:95], v[134:137], v[202:205], v[92:95]
	v_mfma_f32_16x16x32_bf16 v[84:87], v[152:155], v[202:205], v[84:87]
	v_mfma_f32_16x16x32_bf16 v[76:79], v[134:137], v[210:213], v[76:79]
	v_mfma_f32_16x16x32_bf16 v[68:71], v[152:155], v[210:213], v[68:71]
	v_mfma_f32_16x16x32_bf16 v[124:127], v[148:151], v[180:183], v[124:127]
	v_mfma_f32_16x16x32_bf16 v[116:119], v[156:159], v[180:183], v[116:119]
	v_mfma_f32_16x16x32_bf16 v[108:111], v[148:151], v[198:201], v[108:111]
	v_mfma_f32_16x16x32_bf16 v[100:103], v[156:159], v[198:201], v[100:103]
	v_mfma_f32_16x16x32_bf16 v[92:95], v[148:151], v[206:209], v[92:95]
	v_mfma_f32_16x16x32_bf16 v[84:87], v[156:159], v[206:209], v[84:87]
	v_mfma_f32_16x16x32_bf16 v[76:79], v[148:151], v[214:217], v[76:79]
	v_mfma_f32_16x16x32_bf16 v[68:71], v[156:159], v[214:217], v[68:71]
	s_setprio 0
	s_setprio 1
	v_mfma_f32_16x16x32_bf16 v[120:123], v[160:163], v[176:179], v[120:123]
	v_mfma_f32_16x16x32_bf16 v[112:115], v[168:171], v[176:179], v[112:115]
	v_mfma_f32_16x16x32_bf16 v[104:107], v[160:163], v[194:197], v[104:107]
	v_mfma_f32_16x16x32_bf16 v[96:99], v[168:171], v[194:197], v[96:99]
	v_mfma_f32_16x16x32_bf16 v[88:91], v[160:163], v[202:205], v[88:91]
	v_mfma_f32_16x16x32_bf16 v[80:83], v[168:171], v[202:205], v[80:83]
	v_mfma_f32_16x16x32_bf16 v[72:75], v[160:163], v[210:213], v[72:75]
	v_mfma_f32_16x16x32_bf16 v[64:67], v[168:171], v[210:213], v[64:67]
	v_mfma_f32_16x16x32_bf16 v[120:123], v[164:167], v[180:183], v[120:123]
	v_mfma_f32_16x16x32_bf16 v[112:115], v[172:175], v[180:183], v[112:115]
	v_mfma_f32_16x16x32_bf16 v[104:107], v[164:167], v[198:201], v[104:107]
	v_mfma_f32_16x16x32_bf16 v[96:99], v[172:175], v[198:201], v[96:99]
	v_mfma_f32_16x16x32_bf16 v[88:91], v[164:167], v[206:209], v[88:91]
	v_mfma_f32_16x16x32_bf16 v[80:83], v[172:175], v[206:209], v[80:83]
	v_mfma_f32_16x16x32_bf16 v[72:75], v[164:167], v[214:217], v[72:75]
	v_mfma_f32_16x16x32_bf16 v[64:67], v[172:175], v[214:217], v[64:67]
	s_setprio 0
	s_barrier
	s_add_i32 s14, s14, s6
	v_lshl_add_u64 v[220:221], v[138:139], 0, s[56:57]
	s_mov_b32 m0, s14
	ds_read_b128 v[176:179], v146 offset:49152
	ds_read_b128 v[180:183], v146 offset:50176
	ds_read_b128 v[194:197], v146 offset:51200
	ds_read_b128 v[198:201], v146 offset:52224
	ds_read_b128 v[202:205], v146 offset:53248
	ds_read_b128 v[206:209], v146 offset:54272
	ds_read_b128 v[210:213], v146 offset:55296
	ds_read_b128 v[214:217], v146 offset:56320
	global_load_lds_dwordx4 v[220:221], off
	v_lshl_add_u64 v[220:221], v[138:139], 0, s[96:97]
	s_add_i32 m0, s14, 0x2000
	s_add_i32 s14, s15, s6
	global_load_lds_dwordx4 v[220:221], off
	v_lshl_add_u64 v[220:221], v[138:139], 0, s[88:89]
	s_mov_b32 m0, s14
	v_lshl_add_u64 v[138:139], v[138:139], 0, s[68:69]
	global_load_lds_dwordx4 v[220:221], off
	s_add_i32 m0, s14, 0x2000
	s_nop 0
	global_load_lds_dwordx4 v[138:139], off
	v_lshl_add_u64 v[138:139], v[218:219], 0, s[56:57]
	s_mov_b32 m0, s26
	s_nop 0
	global_load_lds_dwordx4 v[138:139], off
	v_lshl_add_u64 v[138:139], v[218:219], 0, s[96:97]
	s_mov_b32 m0, s27
	s_nop 0
	global_load_lds_dwordx4 v[138:139], off
	s_waitcnt vmcnt(14)
	s_waitcnt lgkmcnt(0)
	s_barrier
	s_setprio 1
	s_waitcnt lgkmcnt(0)
	v_mfma_f32_16x16x32_bf16 v[60:63], v[134:137], v[176:179], v[60:63]
	v_mfma_f32_16x16x32_bf16 v[52:55], v[152:155], v[176:179], v[52:55]
	v_mfma_f32_16x16x32_bf16 v[44:47], v[134:137], v[194:197], v[44:47]
	v_mfma_f32_16x16x32_bf16 v[36:39], v[152:155], v[194:197], v[36:39]
	v_mfma_f32_16x16x32_bf16 v[28:31], v[134:137], v[202:205], v[28:31]
	v_mfma_f32_16x16x32_bf16 v[20:23], v[152:155], v[202:205], v[20:23]
	v_mfma_f32_16x16x32_bf16 v[12:15], v[134:137], v[210:213], v[12:15]
	v_mfma_f32_16x16x32_bf16 v[4:7], v[152:155], v[210:213], v[4:7]
	v_mfma_f32_16x16x32_bf16 v[60:63], v[148:151], v[180:183], v[60:63]
	v_mfma_f32_16x16x32_bf16 v[52:55], v[156:159], v[180:183], v[52:55]
	v_mfma_f32_16x16x32_bf16 v[44:47], v[148:151], v[198:201], v[44:47]
	v_mfma_f32_16x16x32_bf16 v[36:39], v[156:159], v[198:201], v[36:39]
	v_mfma_f32_16x16x32_bf16 v[28:31], v[148:151], v[206:209], v[28:31]
	v_mfma_f32_16x16x32_bf16 v[20:23], v[156:159], v[206:209], v[20:23]
	v_mfma_f32_16x16x32_bf16 v[12:15], v[148:151], v[214:217], v[12:15]
	v_mfma_f32_16x16x32_bf16 v[4:7], v[156:159], v[214:217], v[4:7]
	s_setprio 0
	s_setprio 1
	v_mfma_f32_16x16x32_bf16 v[56:59], v[160:163], v[176:179], v[56:59]
	v_mfma_f32_16x16x32_bf16 v[48:51], v[168:171], v[176:179], v[48:51]
	v_mfma_f32_16x16x32_bf16 v[40:43], v[160:163], v[194:197], v[40:43]
	v_mfma_f32_16x16x32_bf16 v[32:35], v[168:171], v[194:197], v[32:35]
	v_mfma_f32_16x16x32_bf16 v[24:27], v[160:163], v[202:205], v[24:27]
	v_mfma_f32_16x16x32_bf16 v[16:19], v[168:171], v[202:205], v[16:19]
	v_mfma_f32_16x16x32_bf16 v[8:11], v[160:163], v[210:213], v[8:11]
	v_mfma_f32_16x16x32_bf16 v[0:3], v[168:171], v[210:213], v[0:3]
	v_mfma_f32_16x16x32_bf16 v[56:59], v[164:167], v[180:183], v[56:59]
	v_mfma_f32_16x16x32_bf16 v[48:51], v[172:175], v[180:183], v[48:51]
	v_mfma_f32_16x16x32_bf16 v[40:43], v[164:167], v[198:201], v[40:43]
	v_mfma_f32_16x16x32_bf16 v[32:35], v[172:175], v[198:201], v[32:35]
	v_mfma_f32_16x16x32_bf16 v[24:27], v[164:167], v[206:209], v[24:27]
	v_mfma_f32_16x16x32_bf16 v[16:19], v[172:175], v[206:209], v[16:19]
	v_mfma_f32_16x16x32_bf16 v[8:11], v[164:167], v[214:217], v[8:11]
	v_mfma_f32_16x16x32_bf16 v[0:3], v[172:175], v[214:217], v[0:3]
	s_setprio 0
	s_barrier
	s_add_i32 s51, s51, 2
	s_add_u32 s48, s48, 0x100
	s_addc_u32 s49, s49, 0
	s_add_u32 s16, s16, 0x100
	s_addc_u32 s17, s17, 0
	s_cmp_gt_u32 s51, 13
.LBB0_459:
	s_add_u32 s14, s48, 0xfffc0080
	s_addc_u32 s15, s49, -1
	s_add_i32 s70, 0, 0x10000
	s_cmp_eq_u32 s51, 12
	s_cselect_b32 s15, s31, s15
	s_cselect_b32 s14, s43, s14
	v_add_u32_e32 v138, s70, v142
	s_cselect_b32 s61, s13, s17
	s_cselect_b32 s60, s50, s16
	s_add_i32 s84, 0, 0x14000
	ds_read_b128 v[134:137], v138
	ds_read_b128 v[148:151], v138 offset:1024
	ds_read_b128 v[152:155], v138 offset:2048
	ds_read_b128 v[156:159], v138 offset:3072
	v_add_u32_e32 v138, s84, v142
	ds_read_b128 v[160:163], v138
	ds_read_b128 v[164:167], v138 offset:1024
	ds_read_b128 v[168:171], v138 offset:2048
	ds_read_b128 v[172:175], v138 offset:3072
	v_lshl_add_u64 v[138:139], s[48:49], 0, v[132:133]
	s_add_i32 m0, s19, 0xc000
	ds_read_b128 v[176:179], v146
	ds_read_b128 v[180:183], v146 offset:1024
	ds_read_b128 v[194:197], v146 offset:2048
	ds_read_b128 v[198:201], v146 offset:3072
	ds_read_b128 v[202:205], v146 offset:4096
	ds_read_b128 v[206:209], v146 offset:5120
	ds_read_b128 v[210:213], v146 offset:6144
	ds_read_b128 v[214:217], v146 offset:7168
	global_load_lds_dwordx4 v[138:139], off
	v_lshl_add_u64 v[138:139], v[138:139], 0, s[34:35]
	s_add_i32 m0, s19, 0xe000
	s_nop 0
	global_load_lds_dwordx4 v[138:139], off
	s_waitcnt vmcnt(10)
	s_waitcnt lgkmcnt(0)
	s_barrier
	s_setprio 1
	s_waitcnt lgkmcnt(0)
	v_mfma_f32_16x16x32_bf16 v[124:127], v[134:137], v[176:179], v[124:127]
	v_mfma_f32_16x16x32_bf16 v[116:119], v[152:155], v[176:179], v[116:119]
	v_mfma_f32_16x16x32_bf16 v[108:111], v[134:137], v[194:197], v[108:111]
	v_mfma_f32_16x16x32_bf16 v[100:103], v[152:155], v[194:197], v[100:103]
	v_mfma_f32_16x16x32_bf16 v[92:95], v[134:137], v[202:205], v[92:95]
	v_mfma_f32_16x16x32_bf16 v[84:87], v[152:155], v[202:205], v[84:87]
	v_mfma_f32_16x16x32_bf16 v[76:79], v[134:137], v[210:213], v[76:79]
	v_mfma_f32_16x16x32_bf16 v[68:71], v[152:155], v[210:213], v[68:71]
	v_mfma_f32_16x16x32_bf16 v[124:127], v[148:151], v[180:183], v[124:127]
	v_mfma_f32_16x16x32_bf16 v[116:119], v[156:159], v[180:183], v[116:119]
	v_mfma_f32_16x16x32_bf16 v[108:111], v[148:151], v[198:201], v[108:111]
	v_mfma_f32_16x16x32_bf16 v[100:103], v[156:159], v[198:201], v[100:103]
	v_mfma_f32_16x16x32_bf16 v[92:95], v[148:151], v[206:209], v[92:95]
	v_mfma_f32_16x16x32_bf16 v[84:87], v[156:159], v[206:209], v[84:87]
	v_mfma_f32_16x16x32_bf16 v[76:79], v[148:151], v[214:217], v[76:79]
	v_mfma_f32_16x16x32_bf16 v[68:71], v[156:159], v[214:217], v[68:71]
	s_setprio 0
	s_setprio 1
	v_mfma_f32_16x16x32_bf16 v[120:123], v[160:163], v[176:179], v[120:123]
	v_mfma_f32_16x16x32_bf16 v[112:115], v[168:171], v[176:179], v[112:115]
	v_mfma_f32_16x16x32_bf16 v[104:107], v[160:163], v[194:197], v[104:107]
	v_mfma_f32_16x16x32_bf16 v[96:99], v[168:171], v[194:197], v[96:99]
	v_mfma_f32_16x16x32_bf16 v[88:91], v[160:163], v[202:205], v[88:91]
	v_mfma_f32_16x16x32_bf16 v[80:83], v[168:171], v[202:205], v[80:83]
	v_mfma_f32_16x16x32_bf16 v[72:75], v[160:163], v[210:213], v[72:75]
	v_mfma_f32_16x16x32_bf16 v[64:67], v[168:171], v[210:213], v[64:67]
	v_mfma_f32_16x16x32_bf16 v[120:123], v[164:167], v[180:183], v[120:123]
	v_mfma_f32_16x16x32_bf16 v[112:115], v[172:175], v[180:183], v[112:115]
	v_mfma_f32_16x16x32_bf16 v[104:107], v[164:167], v[198:201], v[104:107]
	v_mfma_f32_16x16x32_bf16 v[96:99], v[172:175], v[198:201], v[96:99]
	v_mfma_f32_16x16x32_bf16 v[88:91], v[164:167], v[206:209], v[88:91]
	v_mfma_f32_16x16x32_bf16 v[80:83], v[172:175], v[206:209], v[80:83]
	v_mfma_f32_16x16x32_bf16 v[72:75], v[164:167], v[214:217], v[72:75]
	v_mfma_f32_16x16x32_bf16 v[64:67], v[172:175], v[214:217], v[64:67]
	s_setprio 0
	s_barrier
	v_lshl_add_u64 v[138:139], s[60:61], 0, v[184:185]
	s_add_i32 s60, s70, s6
	s_mov_b32 m0, s60
	ds_read_b128 v[176:179], v146 offset:16384
	ds_read_b128 v[180:183], v146 offset:17408
	ds_read_b128 v[194:197], v146 offset:18432
	ds_read_b128 v[198:201], v146 offset:19456
	ds_read_b128 v[202:205], v146 offset:20480
	ds_read_b128 v[206:209], v146 offset:21504
	ds_read_b128 v[210:213], v146 offset:22528
	ds_read_b128 v[214:217], v146 offset:23552
	global_load_lds_dwordx4 v[138:139], off
	v_lshl_add_u64 v[218:219], v[138:139], 0, s[34:35]
	s_add_i32 m0, s60, 0x2000
	s_add_i32 s60, s84, s6
	global_load_lds_dwordx4 v[218:219], off
	v_lshl_add_u64 v[218:219], v[138:139], 0, s[92:93]
	s_mov_b32 m0, s60
	s_nop 0
	global_load_lds_dwordx4 v[218:219], off
	v_lshl_add_u64 v[218:219], v[138:139], 0, s[52:53]
	s_add_i32 m0, s60, 0x2000
	s_nop 0
	global_load_lds_dwordx4 v[218:219], off
	v_lshl_add_u64 v[218:219], s[14:15], 0, v[128:129]
	s_mov_b32 m0, s19
	v_lshl_add_u64 v[220:221], v[218:219], 0, s[34:35]
	global_load_lds_dwordx4 v[218:219], off
	s_mov_b32 m0, s20
	s_nop 0
	global_load_lds_dwordx4 v[220:221], off
	s_waitcnt vmcnt(14)
	s_waitcnt lgkmcnt(0)
	s_barrier
	s_setprio 1
	s_waitcnt lgkmcnt(0)
	v_mfma_f32_16x16x32_bf16 v[60:63], v[134:137], v[176:179], v[60:63]
	v_mfma_f32_16x16x32_bf16 v[52:55], v[152:155], v[176:179], v[52:55]
	v_mfma_f32_16x16x32_bf16 v[44:47], v[134:137], v[194:197], v[44:47]
	v_mfma_f32_16x16x32_bf16 v[36:39], v[152:155], v[194:197], v[36:39]
	v_mfma_f32_16x16x32_bf16 v[28:31], v[134:137], v[202:205], v[28:31]
	v_mfma_f32_16x16x32_bf16 v[20:23], v[152:155], v[202:205], v[20:23]
	v_mfma_f32_16x16x32_bf16 v[12:15], v[134:137], v[210:213], v[12:15]
	v_mfma_f32_16x16x32_bf16 v[4:7], v[152:155], v[210:213], v[4:7]
	v_mfma_f32_16x16x32_bf16 v[60:63], v[148:151], v[180:183], v[60:63]
	v_mfma_f32_16x16x32_bf16 v[52:55], v[156:159], v[180:183], v[52:55]
	v_mfma_f32_16x16x32_bf16 v[44:47], v[148:151], v[198:201], v[44:47]
	v_mfma_f32_16x16x32_bf16 v[36:39], v[156:159], v[198:201], v[36:39]
	v_mfma_f32_16x16x32_bf16 v[28:31], v[148:151], v[206:209], v[28:31]
	v_mfma_f32_16x16x32_bf16 v[20:23], v[156:159], v[206:209], v[20:23]
	v_mfma_f32_16x16x32_bf16 v[12:15], v[148:151], v[214:217], v[12:15]
	v_mfma_f32_16x16x32_bf16 v[4:7], v[156:159], v[214:217], v[4:7]
	s_setprio 0
	s_setprio 1
	v_mfma_f32_16x16x32_bf16 v[56:59], v[160:163], v[176:179], v[56:59]
	v_mfma_f32_16x16x32_bf16 v[48:51], v[168:171], v[176:179], v[48:51]
	v_mfma_f32_16x16x32_bf16 v[40:43], v[160:163], v[194:197], v[40:43]
	v_mfma_f32_16x16x32_bf16 v[32:35], v[168:171], v[194:197], v[32:35]
	v_mfma_f32_16x16x32_bf16 v[24:27], v[160:163], v[202:205], v[24:27]
	v_mfma_f32_16x16x32_bf16 v[16:19], v[168:171], v[202:205], v[16:19]
	v_mfma_f32_16x16x32_bf16 v[8:11], v[160:163], v[210:213], v[8:11]
	v_mfma_f32_16x16x32_bf16 v[0:3], v[168:171], v[210:213], v[0:3]
	v_mfma_f32_16x16x32_bf16 v[56:59], v[164:167], v[180:183], v[56:59]
	v_mfma_f32_16x16x32_bf16 v[48:51], v[172:175], v[180:183], v[48:51]
	v_mfma_f32_16x16x32_bf16 v[40:43], v[164:167], v[198:201], v[40:43]
	v_mfma_f32_16x16x32_bf16 v[32:35], v[172:175], v[198:201], v[32:35]
	v_mfma_f32_16x16x32_bf16 v[24:27], v[164:167], v[206:209], v[24:27]
	v_mfma_f32_16x16x32_bf16 v[16:19], v[172:175], v[206:209], v[16:19]
	v_mfma_f32_16x16x32_bf16 v[8:11], v[164:167], v[214:217], v[8:11]
	v_mfma_f32_16x16x32_bf16 v[0:3], v[172:175], v[214:217], v[0:3]
	s_setprio 0
	s_barrier
	s_add_i32 s14, 0, 0x18000
	v_add_u32_e32 v147, s14, v142
	s_add_i32 s15, 0, 0x1c000
	ds_read_b128 v[134:137], v147
	ds_read_b128 v[148:151], v147 offset:1024
	ds_read_b128 v[152:155], v147 offset:2048
	ds_read_b128 v[156:159], v147 offset:3072
	v_add_u32_e32 v147, s15, v142
	ds_read_b128 v[160:163], v147
	ds_read_b128 v[164:167], v147 offset:1024
	ds_read_b128 v[168:171], v147 offset:2048
	ds_read_b128 v[172:175], v147 offset:3072
	s_mov_b32 m0, s24
	v_lshl_add_u64 v[220:221], v[218:219], 0, s[92:93]
	ds_read_b128 v[176:179], v146 offset:32768
	ds_read_b128 v[180:183], v146 offset:33792
	ds_read_b128 v[194:197], v146 offset:34816
	ds_read_b128 v[198:201], v146 offset:35840
	ds_read_b128 v[202:205], v146 offset:36864
	ds_read_b128 v[206:209], v146 offset:37888
	ds_read_b128 v[210:213], v146 offset:38912
	ds_read_b128 v[214:217], v146 offset:39936
	global_load_lds_dwordx4 v[220:221], off
	v_lshl_add_u64 v[220:221], v[218:219], 0, s[52:53]
	s_mov_b32 m0, s25
	s_nop 0
	global_load_lds_dwordx4 v[220:221], off
	s_waitcnt vmcnt(10)
	s_waitcnt lgkmcnt(0)
	s_barrier
	s_setprio 1
	s_waitcnt lgkmcnt(0)
	v_mfma_f32_16x16x32_bf16 v[124:127], v[134:137], v[176:179], v[124:127]
	v_mfma_f32_16x16x32_bf16 v[116:119], v[152:155], v[176:179], v[116:119]
	v_mfma_f32_16x16x32_bf16 v[108:111], v[134:137], v[194:197], v[108:111]
	v_mfma_f32_16x16x32_bf16 v[100:103], v[152:155], v[194:197], v[100:103]
	v_mfma_f32_16x16x32_bf16 v[92:95], v[134:137], v[202:205], v[92:95]
	v_mfma_f32_16x16x32_bf16 v[84:87], v[152:155], v[202:205], v[84:87]
	v_mfma_f32_16x16x32_bf16 v[76:79], v[134:137], v[210:213], v[76:79]
	v_mfma_f32_16x16x32_bf16 v[68:71], v[152:155], v[210:213], v[68:71]
	v_mfma_f32_16x16x32_bf16 v[124:127], v[148:151], v[180:183], v[124:127]
	v_mfma_f32_16x16x32_bf16 v[116:119], v[156:159], v[180:183], v[116:119]
	v_mfma_f32_16x16x32_bf16 v[108:111], v[148:151], v[198:201], v[108:111]
	v_mfma_f32_16x16x32_bf16 v[100:103], v[156:159], v[198:201], v[100:103]
	v_mfma_f32_16x16x32_bf16 v[92:95], v[148:151], v[206:209], v[92:95]
	v_mfma_f32_16x16x32_bf16 v[84:87], v[156:159], v[206:209], v[84:87]
	v_mfma_f32_16x16x32_bf16 v[76:79], v[148:151], v[214:217], v[76:79]
	v_mfma_f32_16x16x32_bf16 v[68:71], v[156:159], v[214:217], v[68:71]
	s_setprio 0
	s_setprio 1
	v_mfma_f32_16x16x32_bf16 v[120:123], v[160:163], v[176:179], v[120:123]
	v_mfma_f32_16x16x32_bf16 v[112:115], v[168:171], v[176:179], v[112:115]
	v_mfma_f32_16x16x32_bf16 v[104:107], v[160:163], v[194:197], v[104:107]
	v_mfma_f32_16x16x32_bf16 v[96:99], v[168:171], v[194:197], v[96:99]
	v_mfma_f32_16x16x32_bf16 v[88:91], v[160:163], v[202:205], v[88:91]
	v_mfma_f32_16x16x32_bf16 v[80:83], v[168:171], v[202:205], v[80:83]
	v_mfma_f32_16x16x32_bf16 v[72:75], v[160:163], v[210:213], v[72:75]
	v_mfma_f32_16x16x32_bf16 v[64:67], v[168:171], v[210:213], v[64:67]
	v_mfma_f32_16x16x32_bf16 v[120:123], v[164:167], v[180:183], v[120:123]
	v_mfma_f32_16x16x32_bf16 v[112:115], v[172:175], v[180:183], v[112:115]
	v_mfma_f32_16x16x32_bf16 v[104:107], v[164:167], v[198:201], v[104:107]
	v_mfma_f32_16x16x32_bf16 v[96:99], v[172:175], v[198:201], v[96:99]
	v_mfma_f32_16x16x32_bf16 v[88:91], v[164:167], v[206:209], v[88:91]
	v_mfma_f32_16x16x32_bf16 v[80:83], v[172:175], v[206:209], v[80:83]
	v_mfma_f32_16x16x32_bf16 v[72:75], v[164:167], v[214:217], v[72:75]
	v_mfma_f32_16x16x32_bf16 v[64:67], v[172:175], v[214:217], v[64:67]
	s_setprio 0
	s_barrier
	s_add_i32 s14, s14, s6
	v_lshl_add_u64 v[220:221], v[138:139], 0, s[56:57]
	s_mov_b32 m0, s14
	ds_read_b128 v[176:179], v146 offset:49152
	ds_read_b128 v[180:183], v146 offset:50176
	ds_read_b128 v[194:197], v146 offset:51200
	ds_read_b128 v[198:201], v146 offset:52224
	ds_read_b128 v[202:205], v146 offset:53248
	ds_read_b128 v[206:209], v146 offset:54272
	ds_read_b128 v[210:213], v146 offset:55296
	ds_read_b128 v[214:217], v146 offset:56320
	global_load_lds_dwordx4 v[220:221], off
	v_lshl_add_u64 v[220:221], v[138:139], 0, s[96:97]
	s_add_i32 m0, s14, 0x2000
	s_add_i32 s14, s15, s6
	global_load_lds_dwordx4 v[220:221], off
	v_lshl_add_u64 v[220:221], v[138:139], 0, s[88:89]
	s_mov_b32 m0, s14
	v_lshl_add_u64 v[138:139], v[138:139], 0, s[68:69]
	global_load_lds_dwordx4 v[220:221], off
	s_add_i32 m0, s14, 0x2000
	s_nop 0
	global_load_lds_dwordx4 v[138:139], off
	v_lshl_add_u64 v[138:139], v[218:219], 0, s[56:57]
	s_mov_b32 m0, s26
	s_nop 0
	global_load_lds_dwordx4 v[138:139], off
	v_lshl_add_u64 v[138:139], v[218:219], 0, s[96:97]
	s_mov_b32 m0, s27
	s_nop 0
	global_load_lds_dwordx4 v[138:139], off
	s_waitcnt vmcnt(14)
	s_waitcnt lgkmcnt(0)
	s_barrier
	s_setprio 1
	s_waitcnt lgkmcnt(0)
	v_mfma_f32_16x16x32_bf16 v[60:63], v[134:137], v[176:179], v[60:63]
	v_mfma_f32_16x16x32_bf16 v[52:55], v[152:155], v[176:179], v[52:55]
	v_mfma_f32_16x16x32_bf16 v[44:47], v[134:137], v[194:197], v[44:47]
	v_mfma_f32_16x16x32_bf16 v[36:39], v[152:155], v[194:197], v[36:39]
	v_mfma_f32_16x16x32_bf16 v[28:31], v[134:137], v[202:205], v[28:31]
	v_mfma_f32_16x16x32_bf16 v[20:23], v[152:155], v[202:205], v[20:23]
	v_mfma_f32_16x16x32_bf16 v[12:15], v[134:137], v[210:213], v[12:15]
	v_mfma_f32_16x16x32_bf16 v[4:7], v[152:155], v[210:213], v[4:7]
	v_mfma_f32_16x16x32_bf16 v[60:63], v[148:151], v[180:183], v[60:63]
	v_mfma_f32_16x16x32_bf16 v[52:55], v[156:159], v[180:183], v[52:55]
	v_mfma_f32_16x16x32_bf16 v[44:47], v[148:151], v[198:201], v[44:47]
	v_mfma_f32_16x16x32_bf16 v[36:39], v[156:159], v[198:201], v[36:39]
	v_mfma_f32_16x16x32_bf16 v[28:31], v[148:151], v[206:209], v[28:31]
	v_mfma_f32_16x16x32_bf16 v[20:23], v[156:159], v[206:209], v[20:23]
	v_mfma_f32_16x16x32_bf16 v[12:15], v[148:151], v[214:217], v[12:15]
	v_mfma_f32_16x16x32_bf16 v[4:7], v[156:159], v[214:217], v[4:7]
	s_setprio 0
	s_setprio 1
	v_mfma_f32_16x16x32_bf16 v[56:59], v[160:163], v[176:179], v[56:59]
	v_mfma_f32_16x16x32_bf16 v[48:51], v[168:171], v[176:179], v[48:51]
	v_mfma_f32_16x16x32_bf16 v[40:43], v[160:163], v[194:197], v[40:43]
	v_mfma_f32_16x16x32_bf16 v[32:35], v[168:171], v[194:197], v[32:35]
	v_mfma_f32_16x16x32_bf16 v[24:27], v[160:163], v[202:205], v[24:27]
	v_mfma_f32_16x16x32_bf16 v[16:19], v[168:171], v[202:205], v[16:19]
	v_mfma_f32_16x16x32_bf16 v[8:11], v[160:163], v[210:213], v[8:11]
	v_mfma_f32_16x16x32_bf16 v[0:3], v[168:171], v[210:213], v[0:3]
	v_mfma_f32_16x16x32_bf16 v[56:59], v[164:167], v[180:183], v[56:59]
	v_mfma_f32_16x16x32_bf16 v[48:51], v[172:175], v[180:183], v[48:51]
	v_mfma_f32_16x16x32_bf16 v[40:43], v[164:167], v[198:201], v[40:43]
	v_mfma_f32_16x16x32_bf16 v[32:35], v[172:175], v[198:201], v[32:35]
	v_mfma_f32_16x16x32_bf16 v[24:27], v[164:167], v[206:209], v[24:27]
	v_mfma_f32_16x16x32_bf16 v[16:19], v[172:175], v[206:209], v[16:19]
	v_mfma_f32_16x16x32_bf16 v[8:11], v[164:167], v[214:217], v[8:11]
	v_mfma_f32_16x16x32_bf16 v[0:3], v[172:175], v[214:217], v[0:3]
	s_setprio 0
	s_barrier
	s_add_i32 s51, s51, 2
	s_add_u32 s48, s48, 0x100
	s_addc_u32 s49, s49, 0
	s_add_u32 s16, s16, 0x100
	s_addc_u32 s17, s17, 0
	s_cmp_gt_u32 s51, 13
	s_cbranch_scc0 .LBB0_459
	s_and_b64 vcc, exec, s[10:11]
	s_cbranch_vccz .LBB0_462
	s_barrier

.Lnostb7:
	s_add_u32 s14, s46, 0xfffc0080
	s_addc_u32 s15, s47, -1
	s_add_i32 s60, 0, 0x10000
	s_cmp_eq_u32 s49, 12
	s_cselect_b32 s15, s31, s15
	s_cselect_b32 s14, s41, s14
	v_add_u32_e32 v135, s60, v143
	s_cselect_b32 s51, s13, s17
	s_cselect_b32 s50, s48, s16
	s_add_i32 s61, 0, 0x14000
	ds_read_b128 v[136:139], v135
	ds_read_b128 v[148:151], v135 offset:1024
	ds_read_b128 v[152:155], v135 offset:2048
	ds_read_b128 v[156:159], v135 offset:3072
	v_add_u32_e32 v135, s61, v143
	ds_read_b128 v[160:163], v135
	ds_read_b128 v[164:167], v135 offset:1024
	ds_read_b128 v[168:171], v135 offset:2048
	ds_read_b128 v[172:175], v135 offset:3072
	v_lshl_add_u64 v[140:141], s[46:47], 0, v[184:185]
	s_add_i32 m0, s19, 0xc000
	ds_read_b128 v[176:179], v147
	ds_read_b128 v[180:183], v147 offset:1024
	ds_read_b128 v[194:197], v147 offset:2048
	ds_read_b128 v[198:201], v147 offset:3072
	ds_read_b128 v[202:205], v147 offset:4096
	ds_read_b128 v[206:209], v147 offset:5120
	ds_read_b128 v[210:213], v147 offset:6144
	ds_read_b128 v[214:217], v147 offset:7168
	global_load_lds_dwordx4 v[140:141], off
	v_lshl_add_u64 v[140:141], v[140:141], 0, s[34:35]
	s_add_i32 m0, s19, 0xe000
	s_nop 0
	global_load_lds_dwordx4 v[140:141], off
	s_waitcnt vmcnt(10)
	s_waitcnt lgkmcnt(0)
	s_barrier
	s_setprio 1
	s_waitcnt lgkmcnt(0)
	v_mfma_f32_16x16x32_bf16 v[124:127], v[136:139], v[176:179], 0
	v_mfma_f32_16x16x32_bf16 v[116:119], v[152:155], v[176:179], 0
	v_mfma_f32_16x16x32_bf16 v[108:111], v[136:139], v[194:197], 0
	v_mfma_f32_16x16x32_bf16 v[100:103], v[152:155], v[194:197], 0
	v_mfma_f32_16x16x32_bf16 v[92:95], v[136:139], v[202:205], 0
	v_mfma_f32_16x16x32_bf16 v[84:87], v[152:155], v[202:205], 0
	v_mfma_f32_16x16x32_bf16 v[76:79], v[136:139], v[210:213], 0
	v_mfma_f32_16x16x32_bf16 v[68:71], v[152:155], v[210:213], 0
	v_mfma_f32_16x16x32_bf16 v[124:127], v[148:151], v[180:183], v[124:127]
	v_mfma_f32_16x16x32_bf16 v[116:119], v[156:159], v[180:183], v[116:119]
	v_mfma_f32_16x16x32_bf16 v[108:111], v[148:151], v[198:201], v[108:111]
	v_mfma_f32_16x16x32_bf16 v[100:103], v[156:159], v[198:201], v[100:103]
	v_mfma_f32_16x16x32_bf16 v[92:95], v[148:151], v[206:209], v[92:95]
	v_mfma_f32_16x16x32_bf16 v[84:87], v[156:159], v[206:209], v[84:87]
	v_mfma_f32_16x16x32_bf16 v[76:79], v[148:151], v[214:217], v[76:79]
	v_mfma_f32_16x16x32_bf16 v[68:71], v[156:159], v[214:217], v[68:71]
	s_setprio 0
	s_setprio 1
	v_mfma_f32_16x16x32_bf16 v[120:123], v[160:163], v[176:179], 0
	v_mfma_f32_16x16x32_bf16 v[112:115], v[168:171], v[176:179], 0
	v_mfma_f32_16x16x32_bf16 v[104:107], v[160:163], v[194:197], 0
	v_mfma_f32_16x16x32_bf16 v[96:99], v[168:171], v[194:197], 0
	v_mfma_f32_16x16x32_bf16 v[88:91], v[160:163], v[202:205], 0
	v_mfma_f32_16x16x32_bf16 v[80:83], v[168:171], v[202:205], 0
	v_mfma_f32_16x16x32_bf16 v[72:75], v[160:163], v[210:213], 0
	v_mfma_f32_16x16x32_bf16 v[64:67], v[168:171], v[210:213], 0
	v_mfma_f32_16x16x32_bf16 v[120:123], v[164:167], v[180:183], v[120:123]
	v_mfma_f32_16x16x32_bf16 v[112:115], v[172:175], v[180:183], v[112:115]
	v_mfma_f32_16x16x32_bf16 v[104:107], v[164:167], v[198:201], v[104:107]
	v_mfma_f32_16x16x32_bf16 v[96:99], v[172:175], v[198:201], v[96:99]
	v_mfma_f32_16x16x32_bf16 v[88:91], v[164:167], v[206:209], v[88:91]
	v_mfma_f32_16x16x32_bf16 v[80:83], v[172:175], v[206:209], v[80:83]
	v_mfma_f32_16x16x32_bf16 v[72:75], v[164:167], v[214:217], v[72:75]
	v_mfma_f32_16x16x32_bf16 v[64:67], v[172:175], v[214:217], v[64:67]
	s_setprio 0
	s_barrier
	v_lshl_add_u64 v[140:141], s[50:51], 0, v[128:129]
	s_add_i32 s50, s60, s6
	s_mov_b32 m0, s50
	ds_read_b128 v[176:179], v147 offset:16384
	ds_read_b128 v[180:183], v147 offset:17408
	ds_read_b128 v[194:197], v147 offset:18432
	ds_read_b128 v[198:201], v147 offset:19456
	ds_read_b128 v[202:205], v147 offset:20480
	ds_read_b128 v[206:209], v147 offset:21504
	ds_read_b128 v[210:213], v147 offset:22528
	ds_read_b128 v[214:217], v147 offset:23552
	global_load_lds_dwordx4 v[140:141], off
	v_lshl_add_u64 v[218:219], v[140:141], 0, s[34:35]
	s_add_i32 m0, s50, 0x2000
	s_add_i32 s50, s61, s6
	global_load_lds_dwordx4 v[218:219], off
	v_lshl_add_u64 v[218:219], v[140:141], 0, s[92:93]
	s_mov_b32 m0, s50
	s_nop 0
	global_load_lds_dwordx4 v[218:219], off
	v_lshl_add_u64 v[218:219], v[140:141], 0, s[52:53]
	s_add_i32 m0, s50, 0x2000
	s_nop 0
	global_load_lds_dwordx4 v[218:219], off
	v_lshl_add_u64 v[218:219], s[14:15], 0, v[130:131]
	s_mov_b32 m0, s19
	v_lshl_add_u64 v[220:221], v[218:219], 0, s[34:35]
	global_load_lds_dwordx4 v[218:219], off
	s_mov_b32 m0, s20
	s_nop 0
	global_load_lds_dwordx4 v[220:221], off
	s_waitcnt vmcnt(14)
	s_waitcnt lgkmcnt(0)
	s_barrier
	s_setprio 1
	s_waitcnt lgkmcnt(0)
	v_mfma_f32_16x16x32_bf16 v[60:63], v[136:139], v[176:179], 0
	v_mfma_f32_16x16x32_bf16 v[52:55], v[152:155], v[176:179], 0
	v_mfma_f32_16x16x32_bf16 v[44:47], v[136:139], v[194:197], 0
	v_mfma_f32_16x16x32_bf16 v[36:39], v[152:155], v[194:197], 0
	v_mfma_f32_16x16x32_bf16 v[28:31], v[136:139], v[202:205], 0
	v_mfma_f32_16x16x32_bf16 v[20:23], v[152:155], v[202:205], 0
	v_mfma_f32_16x16x32_bf16 v[12:15], v[136:139], v[210:213], 0
	v_mfma_f32_16x16x32_bf16 v[4:7], v[152:155], v[210:213], 0
	v_mfma_f32_16x16x32_bf16 v[60:63], v[148:151], v[180:183], v[60:63]
	v_mfma_f32_16x16x32_bf16 v[52:55], v[156:159], v[180:183], v[52:55]
	v_mfma_f32_16x16x32_bf16 v[44:47], v[148:151], v[198:201], v[44:47]
	v_mfma_f32_16x16x32_bf16 v[36:39], v[156:159], v[198:201], v[36:39]
	v_mfma_f32_16x16x32_bf16 v[28:31], v[148:151], v[206:209], v[28:31]
	v_mfma_f32_16x16x32_bf16 v[20:23], v[156:159], v[206:209], v[20:23]
	v_mfma_f32_16x16x32_bf16 v[12:15], v[148:151], v[214:217], v[12:15]
	v_mfma_f32_16x16x32_bf16 v[4:7], v[156:159], v[214:217], v[4:7]
	s_setprio 0
	s_setprio 1
	v_mfma_f32_16x16x32_bf16 v[56:59], v[160:163], v[176:179], 0
	v_mfma_f32_16x16x32_bf16 v[48:51], v[168:171], v[176:179], 0
	v_mfma_f32_16x16x32_bf16 v[40:43], v[160:163], v[194:197], 0
	v_mfma_f32_16x16x32_bf16 v[32:35], v[168:171], v[194:197], 0
	v_mfma_f32_16x16x32_bf16 v[24:27], v[160:163], v[202:205], 0
	v_mfma_f32_16x16x32_bf16 v[16:19], v[168:171], v[202:205], 0
	v_mfma_f32_16x16x32_bf16 v[8:11], v[160:163], v[210:213], 0
	v_mfma_f32_16x16x32_bf16 v[0:3], v[168:171], v[210:213], 0
	v_mfma_f32_16x16x32_bf16 v[56:59], v[164:167], v[180:183], v[56:59]
	v_mfma_f32_16x16x32_bf16 v[48:51], v[172:175], v[180:183], v[48:51]
	v_mfma_f32_16x16x32_bf16 v[40:43], v[164:167], v[198:201], v[40:43]
	v_mfma_f32_16x16x32_bf16 v[32:35], v[172:175], v[198:201], v[32:35]
	v_mfma_f32_16x16x32_bf16 v[24:27], v[164:167], v[206:209], v[24:27]
	v_mfma_f32_16x16x32_bf16 v[16:19], v[172:175], v[206:209], v[16:19]
	v_mfma_f32_16x16x32_bf16 v[8:11], v[164:167], v[214:217], v[8:11]
	v_mfma_f32_16x16x32_bf16 v[0:3], v[172:175], v[214:217], v[0:3]
	s_setprio 0
	s_barrier
	s_add_i32 s14, 0, 0x18000
	v_add_u32_e32 v135, s14, v143
	s_add_i32 s15, 0, 0x1c000
	ds_read_b128 v[136:139], v135
	ds_read_b128 v[148:151], v135 offset:1024
	ds_read_b128 v[152:155], v135 offset:2048
	ds_read_b128 v[156:159], v135 offset:3072
	v_add_u32_e32 v135, s15, v143
	ds_read_b128 v[160:163], v135
	ds_read_b128 v[164:167], v135 offset:1024
	ds_read_b128 v[168:171], v135 offset:2048
	ds_read_b128 v[172:175], v135 offset:3072
	s_mov_b32 m0, s24
	v_lshl_add_u64 v[220:221], v[218:219], 0, s[92:93]
	ds_read_b128 v[176:179], v147 offset:32768
	ds_read_b128 v[180:183], v147 offset:33792
	ds_read_b128 v[194:197], v147 offset:34816
	ds_read_b128 v[198:201], v147 offset:35840
	ds_read_b128 v[202:205], v147 offset:36864
	ds_read_b128 v[206:209], v147 offset:37888
	ds_read_b128 v[210:213], v147 offset:38912
	ds_read_b128 v[214:217], v147 offset:39936
	global_load_lds_dwordx4 v[220:221], off
	v_lshl_add_u64 v[220:221], v[218:219], 0, s[52:53]
	s_mov_b32 m0, s25
	s_nop 0
	global_load_lds_dwordx4 v[220:221], off
	s_waitcnt vmcnt(10)
	s_waitcnt lgkmcnt(0)
	s_barrier
	s_setprio 1
	s_waitcnt lgkmcnt(0)
	v_mfma_f32_16x16x32_bf16 v[124:127], v[136:139], v[176:179], v[124:127]
	v_mfma_f32_16x16x32_bf16 v[116:119], v[152:155], v[176:179], v[116:119]
	v_mfma_f32_16x16x32_bf16 v[108:111], v[136:139], v[194:197], v[108:111]
	v_mfma_f32_16x16x32_bf16 v[100:103], v[152:155], v[194:197], v[100:103]
	v_mfma_f32_16x16x32_bf16 v[92:95], v[136:139], v[202:205], v[92:95]
	v_mfma_f32_16x16x32_bf16 v[84:87], v[152:155], v[202:205], v[84:87]
	v_mfma_f32_16x16x32_bf16 v[76:79], v[136:139], v[210:213], v[76:79]
	v_mfma_f32_16x16x32_bf16 v[68:71], v[152:155], v[210:213], v[68:71]
	v_mfma_f32_16x16x32_bf16 v[124:127], v[148:151], v[180:183], v[124:127]
	v_mfma_f32_16x16x32_bf16 v[116:119], v[156:159], v[180:183], v[116:119]
	v_mfma_f32_16x16x32_bf16 v[108:111], v[148:151], v[198:201], v[108:111]
	v_mfma_f32_16x16x32_bf16 v[100:103], v[156:159], v[198:201], v[100:103]
	v_mfma_f32_16x16x32_bf16 v[92:95], v[148:151], v[206:209], v[92:95]
	v_mfma_f32_16x16x32_bf16 v[84:87], v[156:159], v[206:209], v[84:87]
	v_mfma_f32_16x16x32_bf16 v[76:79], v[148:151], v[214:217], v[76:79]
	v_mfma_f32_16x16x32_bf16 v[68:71], v[156:159], v[214:217], v[68:71]
	s_setprio 0
	s_setprio 1
	v_mfma_f32_16x16x32_bf16 v[120:123], v[160:163], v[176:179], v[120:123]
	v_mfma_f32_16x16x32_bf16 v[112:115], v[168:171], v[176:179], v[112:115]
	v_mfma_f32_16x16x32_bf16 v[104:107], v[160:163], v[194:197], v[104:107]
	v_mfma_f32_16x16x32_bf16 v[96:99], v[168:171], v[194:197], v[96:99]
	v_mfma_f32_16x16x32_bf16 v[88:91], v[160:163], v[202:205], v[88:91]
	v_mfma_f32_16x16x32_bf16 v[80:83], v[168:171], v[202:205], v[80:83]
	v_mfma_f32_16x16x32_bf16 v[72:75], v[160:163], v[210:213], v[72:75]
	v_mfma_f32_16x16x32_bf16 v[64:67], v[168:171], v[210:213], v[64:67]
	v_mfma_f32_16x16x32_bf16 v[120:123], v[164:167], v[180:183], v[120:123]
	v_mfma_f32_16x16x32_bf16 v[112:115], v[172:175], v[180:183], v[112:115]
	v_mfma_f32_16x16x32_bf16 v[104:107], v[164:167], v[198:201], v[104:107]
	v_mfma_f32_16x16x32_bf16 v[96:99], v[172:175], v[198:201], v[96:99]
	v_mfma_f32_16x16x32_bf16 v[88:91], v[164:167], v[206:209], v[88:91]
	v_mfma_f32_16x16x32_bf16 v[80:83], v[172:175], v[206:209], v[80:83]
	v_mfma_f32_16x16x32_bf16 v[72:75], v[164:167], v[214:217], v[72:75]
	v_mfma_f32_16x16x32_bf16 v[64:67], v[172:175], v[214:217], v[64:67]
	s_setprio 0
	s_barrier
	s_add_i32 s14, s14, s6
	v_lshl_add_u64 v[220:221], v[140:141], 0, s[56:57]
	s_mov_b32 m0, s14
	ds_read_b128 v[176:179], v147 offset:49152
	ds_read_b128 v[180:183], v147 offset:50176
	ds_read_b128 v[194:197], v147 offset:51200
	ds_read_b128 v[198:201], v147 offset:52224
	ds_read_b128 v[202:205], v147 offset:53248
	ds_read_b128 v[206:209], v147 offset:54272
	ds_read_b128 v[210:213], v147 offset:55296
	ds_read_b128 v[214:217], v147 offset:56320
	global_load_lds_dwordx4 v[220:221], off
	v_lshl_add_u64 v[220:221], v[140:141], 0, s[96:97]
	s_add_i32 m0, s14, 0x2000
	s_add_i32 s14, s15, s6
	global_load_lds_dwordx4 v[220:221], off
	v_lshl_add_u64 v[220:221], v[140:141], 0, s[88:89]
	s_mov_b32 m0, s14
	v_lshl_add_u64 v[140:141], v[140:141], 0, s[68:69]
	global_load_lds_dwordx4 v[220:221], off
	s_add_i32 m0, s14, 0x2000
	s_nop 0
	global_load_lds_dwordx4 v[140:141], off
	v_lshl_add_u64 v[140:141], v[218:219], 0, s[56:57]
	s_mov_b32 m0, s26
	s_nop 0
	global_load_lds_dwordx4 v[140:141], off
	v_lshl_add_u64 v[140:141], v[218:219], 0, s[96:97]
	s_mov_b32 m0, s27
	s_nop 0
	global_load_lds_dwordx4 v[140:141], off
	s_waitcnt vmcnt(14)
	s_waitcnt lgkmcnt(0)
	s_barrier
	s_setprio 1
	s_waitcnt lgkmcnt(0)
	v_mfma_f32_16x16x32_bf16 v[60:63], v[136:139], v[176:179], v[60:63]
	v_mfma_f32_16x16x32_bf16 v[52:55], v[152:155], v[176:179], v[52:55]
	v_mfma_f32_16x16x32_bf16 v[44:47], v[136:139], v[194:197], v[44:47]
	v_mfma_f32_16x16x32_bf16 v[36:39], v[152:155], v[194:197], v[36:39]
	v_mfma_f32_16x16x32_bf16 v[28:31], v[136:139], v[202:205], v[28:31]
	v_mfma_f32_16x16x32_bf16 v[20:23], v[152:155], v[202:205], v[20:23]
	v_mfma_f32_16x16x32_bf16 v[12:15], v[136:139], v[210:213], v[12:15]
	v_mfma_f32_16x16x32_bf16 v[4:7], v[152:155], v[210:213], v[4:7]
	v_mfma_f32_16x16x32_bf16 v[60:63], v[148:151], v[180:183], v[60:63]
	v_mfma_f32_16x16x32_bf16 v[52:55], v[156:159], v[180:183], v[52:55]
	v_mfma_f32_16x16x32_bf16 v[44:47], v[148:151], v[198:201], v[44:47]
	v_mfma_f32_16x16x32_bf16 v[36:39], v[156:159], v[198:201], v[36:39]
	v_mfma_f32_16x16x32_bf16 v[28:31], v[148:151], v[206:209], v[28:31]
	v_mfma_f32_16x16x32_bf16 v[20:23], v[156:159], v[206:209], v[20:23]
	v_mfma_f32_16x16x32_bf16 v[12:15], v[148:151], v[214:217], v[12:15]
	v_mfma_f32_16x16x32_bf16 v[4:7], v[156:159], v[214:217], v[4:7]
	s_setprio 0
	s_setprio 1
	v_mfma_f32_16x16x32_bf16 v[56:59], v[160:163], v[176:179], v[56:59]
	v_mfma_f32_16x16x32_bf16 v[48:51], v[168:171], v[176:179], v[48:51]
	v_mfma_f32_16x16x32_bf16 v[40:43], v[160:163], v[194:197], v[40:43]
	v_mfma_f32_16x16x32_bf16 v[32:35], v[168:171], v[194:197], v[32:35]
	v_mfma_f32_16x16x32_bf16 v[24:27], v[160:163], v[202:205], v[24:27]
	v_mfma_f32_16x16x32_bf16 v[16:19], v[168:171], v[202:205], v[16:19]
	v_mfma_f32_16x16x32_bf16 v[8:11], v[160:163], v[210:213], v[8:11]
	v_mfma_f32_16x16x32_bf16 v[0:3], v[168:171], v[210:213], v[0:3]
	v_mfma_f32_16x16x32_bf16 v[56:59], v[164:167], v[180:183], v[56:59]
	v_mfma_f32_16x16x32_bf16 v[48:51], v[172:175], v[180:183], v[48:51]
	v_mfma_f32_16x16x32_bf16 v[40:43], v[164:167], v[198:201], v[40:43]
	v_mfma_f32_16x16x32_bf16 v[32:35], v[172:175], v[198:201], v[32:35]
	v_mfma_f32_16x16x32_bf16 v[24:27], v[164:167], v[206:209], v[24:27]
	v_mfma_f32_16x16x32_bf16 v[16:19], v[172:175], v[206:209], v[16:19]
	v_mfma_f32_16x16x32_bf16 v[8:11], v[164:167], v[214:217], v[8:11]
	v_mfma_f32_16x16x32_bf16 v[0:3], v[172:175], v[214:217], v[0:3]
	s_setprio 0
	s_barrier
	s_add_i32 s49, s49, 2
	s_add_u32 s46, s46, 0x100
	s_addc_u32 s47, s47, 0
	s_add_u32 s16, s16, 0x100
	s_addc_u32 s17, s17, 0
	s_cmp_gt_u32 s49, 13
.LBB0_481:
	s_add_u32 s14, s46, 0xfffc0080
	s_addc_u32 s15, s47, -1
	s_add_i32 s60, 0, 0x10000
	s_cmp_eq_u32 s49, 12
	s_cselect_b32 s15, s31, s15
	s_cselect_b32 s14, s41, s14
	v_add_u32_e32 v135, s60, v143
	s_cselect_b32 s51, s13, s17
	s_cselect_b32 s50, s48, s16
	s_add_i32 s61, 0, 0x14000
	ds_read_b128 v[136:139], v135
	ds_read_b128 v[148:151], v135 offset:1024
	ds_read_b128 v[152:155], v135 offset:2048
	ds_read_b128 v[156:159], v135 offset:3072
	v_add_u32_e32 v135, s61, v143
	ds_read_b128 v[160:163], v135
	ds_read_b128 v[164:167], v135 offset:1024
	ds_read_b128 v[168:171], v135 offset:2048
	ds_read_b128 v[172:175], v135 offset:3072
	v_lshl_add_u64 v[140:141], s[46:47], 0, v[184:185]
	s_add_i32 m0, s19, 0xc000
	ds_read_b128 v[176:179], v147
	ds_read_b128 v[180:183], v147 offset:1024
	ds_read_b128 v[194:197], v147 offset:2048
	ds_read_b128 v[198:201], v147 offset:3072
	ds_read_b128 v[202:205], v147 offset:4096
	ds_read_b128 v[206:209], v147 offset:5120
	ds_read_b128 v[210:213], v147 offset:6144
	ds_read_b128 v[214:217], v147 offset:7168
	global_load_lds_dwordx4 v[140:141], off
	v_lshl_add_u64 v[140:141], v[140:141], 0, s[34:35]
	s_add_i32 m0, s19, 0xe000
	s_nop 0
	global_load_lds_dwordx4 v[140:141], off
	s_waitcnt vmcnt(10)
	s_waitcnt lgkmcnt(0)
	s_barrier
	s_setprio 1
	s_waitcnt lgkmcnt(0)
	v_mfma_f32_16x16x32_bf16 v[124:127], v[136:139], v[176:179], v[124:127]
	v_mfma_f32_16x16x32_bf16 v[116:119], v[152:155], v[176:179], v[116:119]
	v_mfma_f32_16x16x32_bf16 v[108:111], v[136:139], v[194:197], v[108:111]
	v_mfma_f32_16x16x32_bf16 v[100:103], v[152:155], v[194:197], v[100:103]
	v_mfma_f32_16x16x32_bf16 v[92:95], v[136:139], v[202:205], v[92:95]
	v_mfma_f32_16x16x32_bf16 v[84:87], v[152:155], v[202:205], v[84:87]
	v_mfma_f32_16x16x32_bf16 v[76:79], v[136:139], v[210:213], v[76:79]
	v_mfma_f32_16x16x32_bf16 v[68:71], v[152:155], v[210:213], v[68:71]
	v_mfma_f32_16x16x32_bf16 v[124:127], v[148:151], v[180:183], v[124:127]
	v_mfma_f32_16x16x32_bf16 v[116:119], v[156:159], v[180:183], v[116:119]
	v_mfma_f32_16x16x32_bf16 v[108:111], v[148:151], v[198:201], v[108:111]
	v_mfma_f32_16x16x32_bf16 v[100:103], v[156:159], v[198:201], v[100:103]
	v_mfma_f32_16x16x32_bf16 v[92:95], v[148:151], v[206:209], v[92:95]
	v_mfma_f32_16x16x32_bf16 v[84:87], v[156:159], v[206:209], v[84:87]
	v_mfma_f32_16x16x32_bf16 v[76:79], v[148:151], v[214:217], v[76:79]
	v_mfma_f32_16x16x32_bf16 v[68:71], v[156:159], v[214:217], v[68:71]
	s_setprio 0
	s_setprio 1
	v_mfma_f32_16x16x32_bf16 v[120:123], v[160:163], v[176:179], v[120:123]
	v_mfma_f32_16x16x32_bf16 v[112:115], v[168:171], v[176:179], v[112:115]
	v_mfma_f32_16x16x32_bf16 v[104:107], v[160:163], v[194:197], v[104:107]
	v_mfma_f32_16x16x32_bf16 v[96:99], v[168:171], v[194:197], v[96:99]
	v_mfma_f32_16x16x32_bf16 v[88:91], v[160:163], v[202:205], v[88:91]
	v_mfma_f32_16x16x32_bf16 v[80:83], v[168:171], v[202:205], v[80:83]
	v_mfma_f32_16x16x32_bf16 v[72:75], v[160:163], v[210:213], v[72:75]
	v_mfma_f32_16x16x32_bf16 v[64:67], v[168:171], v[210:213], v[64:67]
	v_mfma_f32_16x16x32_bf16 v[120:123], v[164:167], v[180:183], v[120:123]
	v_mfma_f32_16x16x32_bf16 v[112:115], v[172:175], v[180:183], v[112:115]
	v_mfma_f32_16x16x32_bf16 v[104:107], v[164:167], v[198:201], v[104:107]
	v_mfma_f32_16x16x32_bf16 v[96:99], v[172:175], v[198:201], v[96:99]
	v_mfma_f32_16x16x32_bf16 v[88:91], v[164:167], v[206:209], v[88:91]
	v_mfma_f32_16x16x32_bf16 v[80:83], v[172:175], v[206:209], v[80:83]
	v_mfma_f32_16x16x32_bf16 v[72:75], v[164:167], v[214:217], v[72:75]
	v_mfma_f32_16x16x32_bf16 v[64:67], v[172:175], v[214:217], v[64:67]
	s_setprio 0
	s_barrier
	v_lshl_add_u64 v[140:141], s[50:51], 0, v[128:129]
	s_add_i32 s50, s60, s6
	s_mov_b32 m0, s50
	ds_read_b128 v[176:179], v147 offset:16384
	ds_read_b128 v[180:183], v147 offset:17408
	ds_read_b128 v[194:197], v147 offset:18432
	ds_read_b128 v[198:201], v147 offset:19456
	ds_read_b128 v[202:205], v147 offset:20480
	ds_read_b128 v[206:209], v147 offset:21504
	ds_read_b128 v[210:213], v147 offset:22528
	ds_read_b128 v[214:217], v147 offset:23552
	global_load_lds_dwordx4 v[140:141], off
	v_lshl_add_u64 v[218:219], v[140:141], 0, s[34:35]
	s_add_i32 m0, s50, 0x2000
	s_add_i32 s50, s61, s6
	global_load_lds_dwordx4 v[218:219], off
	v_lshl_add_u64 v[218:219], v[140:141], 0, s[92:93]
	s_mov_b32 m0, s50
	s_nop 0
	global_load_lds_dwordx4 v[218:219], off
	v_lshl_add_u64 v[218:219], v[140:141], 0, s[52:53]
	s_add_i32 m0, s50, 0x2000
	s_nop 0
	global_load_lds_dwordx4 v[218:219], off
	v_lshl_add_u64 v[218:219], s[14:15], 0, v[130:131]
	s_mov_b32 m0, s19
	v_lshl_add_u64 v[220:221], v[218:219], 0, s[34:35]
	global_load_lds_dwordx4 v[218:219], off
	s_mov_b32 m0, s20
	s_nop 0
	global_load_lds_dwordx4 v[220:221], off
	s_waitcnt vmcnt(14)
	s_waitcnt lgkmcnt(0)
	s_barrier
	s_setprio 1
	s_waitcnt lgkmcnt(0)
	v_mfma_f32_16x16x32_bf16 v[60:63], v[136:139], v[176:179], v[60:63]
	v_mfma_f32_16x16x32_bf16 v[52:55], v[152:155], v[176:179], v[52:55]
	v_mfma_f32_16x16x32_bf16 v[44:47], v[136:139], v[194:197], v[44:47]
	v_mfma_f32_16x16x32_bf16 v[36:39], v[152:155], v[194:197], v[36:39]
	v_mfma_f32_16x16x32_bf16 v[28:31], v[136:139], v[202:205], v[28:31]
	v_mfma_f32_16x16x32_bf16 v[20:23], v[152:155], v[202:205], v[20:23]
	v_mfma_f32_16x16x32_bf16 v[12:15], v[136:139], v[210:213], v[12:15]
	v_mfma_f32_16x16x32_bf16 v[4:7], v[152:155], v[210:213], v[4:7]
	v_mfma_f32_16x16x32_bf16 v[60:63], v[148:151], v[180:183], v[60:63]
	v_mfma_f32_16x16x32_bf16 v[52:55], v[156:159], v[180:183], v[52:55]
	v_mfma_f32_16x16x32_bf16 v[44:47], v[148:151], v[198:201], v[44:47]
	v_mfma_f32_16x16x32_bf16 v[36:39], v[156:159], v[198:201], v[36:39]
	v_mfma_f32_16x16x32_bf16 v[28:31], v[148:151], v[206:209], v[28:31]
	v_mfma_f32_16x16x32_bf16 v[20:23], v[156:159], v[206:209], v[20:23]
	v_mfma_f32_16x16x32_bf16 v[12:15], v[148:151], v[214:217], v[12:15]
	v_mfma_f32_16x16x32_bf16 v[4:7], v[156:159], v[214:217], v[4:7]
	s_setprio 0
	s_setprio 1
	v_mfma_f32_16x16x32_bf16 v[56:59], v[160:163], v[176:179], v[56:59]
	v_mfma_f32_16x16x32_bf16 v[48:51], v[168:171], v[176:179], v[48:51]
	v_mfma_f32_16x16x32_bf16 v[40:43], v[160:163], v[194:197], v[40:43]
	v_mfma_f32_16x16x32_bf16 v[32:35], v[168:171], v[194:197], v[32:35]
	v_mfma_f32_16x16x32_bf16 v[24:27], v[160:163], v[202:205], v[24:27]
	v_mfma_f32_16x16x32_bf16 v[16:19], v[168:171], v[202:205], v[16:19]
	v_mfma_f32_16x16x32_bf16 v[8:11], v[160:163], v[210:213], v[8:11]
	v_mfma_f32_16x16x32_bf16 v[0:3], v[168:171], v[210:213], v[0:3]
	v_mfma_f32_16x16x32_bf16 v[56:59], v[164:167], v[180:183], v[56:59]
	v_mfma_f32_16x16x32_bf16 v[48:51], v[172:175], v[180:183], v[48:51]
	v_mfma_f32_16x16x32_bf16 v[40:43], v[164:167], v[198:201], v[40:43]
	v_mfma_f32_16x16x32_bf16 v[32:35], v[172:175], v[198:201], v[32:35]
	v_mfma_f32_16x16x32_bf16 v[24:27], v[164:167], v[206:209], v[24:27]
	v_mfma_f32_16x16x32_bf16 v[16:19], v[172:175], v[206:209], v[16:19]
	v_mfma_f32_16x16x32_bf16 v[8:11], v[164:167], v[214:217], v[8:11]
	v_mfma_f32_16x16x32_bf16 v[0:3], v[172:175], v[214:217], v[0:3]
	s_setprio 0
	s_barrier
	s_add_i32 s14, 0, 0x18000
	v_add_u32_e32 v135, s14, v143
	s_add_i32 s15, 0, 0x1c000
	ds_read_b128 v[136:139], v135
	ds_read_b128 v[148:151], v135 offset:1024
	ds_read_b128 v[152:155], v135 offset:2048
	ds_read_b128 v[156:159], v135 offset:3072
	v_add_u32_e32 v135, s15, v143
	ds_read_b128 v[160:163], v135
	ds_read_b128 v[164:167], v135 offset:1024
	ds_read_b128 v[168:171], v135 offset:2048
	ds_read_b128 v[172:175], v135 offset:3072
	s_mov_b32 m0, s24
	v_lshl_add_u64 v[220:221], v[218:219], 0, s[92:93]
	ds_read_b128 v[176:179], v147 offset:32768
	ds_read_b128 v[180:183], v147 offset:33792
	ds_read_b128 v[194:197], v147 offset:34816
	ds_read_b128 v[198:201], v147 offset:35840
	ds_read_b128 v[202:205], v147 offset:36864
	ds_read_b128 v[206:209], v147 offset:37888
	ds_read_b128 v[210:213], v147 offset:38912
	ds_read_b128 v[214:217], v147 offset:39936
	global_load_lds_dwordx4 v[220:221], off
	v_lshl_add_u64 v[220:221], v[218:219], 0, s[52:53]
	s_mov_b32 m0, s25
	s_nop 0
	global_load_lds_dwordx4 v[220:221], off
	s_waitcnt vmcnt(10)
	s_waitcnt lgkmcnt(0)
	s_barrier
	s_setprio 1
	s_waitcnt lgkmcnt(0)
	v_mfma_f32_16x16x32_bf16 v[124:127], v[136:139], v[176:179], v[124:127]
	v_mfma_f32_16x16x32_bf16 v[116:119], v[152:155], v[176:179], v[116:119]
	v_mfma_f32_16x16x32_bf16 v[108:111], v[136:139], v[194:197], v[108:111]
	v_mfma_f32_16x16x32_bf16 v[100:103], v[152:155], v[194:197], v[100:103]
	v_mfma_f32_16x16x32_bf16 v[92:95], v[136:139], v[202:205], v[92:95]
	v_mfma_f32_16x16x32_bf16 v[84:87], v[152:155], v[202:205], v[84:87]
	v_mfma_f32_16x16x32_bf16 v[76:79], v[136:139], v[210:213], v[76:79]
	v_mfma_f32_16x16x32_bf16 v[68:71], v[152:155], v[210:213], v[68:71]
	v_mfma_f32_16x16x32_bf16 v[124:127], v[148:151], v[180:183], v[124:127]
	v_mfma_f32_16x16x32_bf16 v[116:119], v[156:159], v[180:183], v[116:119]
	v_mfma_f32_16x16x32_bf16 v[108:111], v[148:151], v[198:201], v[108:111]
	v_mfma_f32_16x16x32_bf16 v[100:103], v[156:159], v[198:201], v[100:103]
	v_mfma_f32_16x16x32_bf16 v[92:95], v[148:151], v[206:209], v[92:95]
	v_mfma_f32_16x16x32_bf16 v[84:87], v[156:159], v[206:209], v[84:87]
	v_mfma_f32_16x16x32_bf16 v[76:79], v[148:151], v[214:217], v[76:79]
	v_mfma_f32_16x16x32_bf16 v[68:71], v[156:159], v[214:217], v[68:71]
	s_setprio 0
	s_setprio 1
	v_mfma_f32_16x16x32_bf16 v[120:123], v[160:163], v[176:179], v[120:123]
	v_mfma_f32_16x16x32_bf16 v[112:115], v[168:171], v[176:179], v[112:115]
	v_mfma_f32_16x16x32_bf16 v[104:107], v[160:163], v[194:197], v[104:107]
	v_mfma_f32_16x16x32_bf16 v[96:99], v[168:171], v[194:197], v[96:99]
	v_mfma_f32_16x16x32_bf16 v[88:91], v[160:163], v[202:205], v[88:91]
	v_mfma_f32_16x16x32_bf16 v[80:83], v[168:171], v[202:205], v[80:83]
	v_mfma_f32_16x16x32_bf16 v[72:75], v[160:163], v[210:213], v[72:75]
	v_mfma_f32_16x16x32_bf16 v[64:67], v[168:171], v[210:213], v[64:67]
	v_mfma_f32_16x16x32_bf16 v[120:123], v[164:167], v[180:183], v[120:123]
	v_mfma_f32_16x16x32_bf16 v[112:115], v[172:175], v[180:183], v[112:115]
	v_mfma_f32_16x16x32_bf16 v[104:107], v[164:167], v[198:201], v[104:107]
	v_mfma_f32_16x16x32_bf16 v[96:99], v[172:175], v[198:201], v[96:99]
	v_mfma_f32_16x16x32_bf16 v[88:91], v[164:167], v[206:209], v[88:91]
	v_mfma_f32_16x16x32_bf16 v[80:83], v[172:175], v[206:209], v[80:83]
	v_mfma_f32_16x16x32_bf16 v[72:75], v[164:167], v[214:217], v[72:75]
	v_mfma_f32_16x16x32_bf16 v[64:67], v[172:175], v[214:217], v[64:67]
	s_setprio 0
	s_barrier
	s_add_i32 s14, s14, s6
	v_lshl_add_u64 v[220:221], v[140:141], 0, s[56:57]
	s_mov_b32 m0, s14
	ds_read_b128 v[176:179], v147 offset:49152
	ds_read_b128 v[180:183], v147 offset:50176
	ds_read_b128 v[194:197], v147 offset:51200
	ds_read_b128 v[198:201], v147 offset:52224
	ds_read_b128 v[202:205], v147 offset:53248
	ds_read_b128 v[206:209], v147 offset:54272
	ds_read_b128 v[210:213], v147 offset:55296
	ds_read_b128 v[214:217], v147 offset:56320
	global_load_lds_dwordx4 v[220:221], off
	v_lshl_add_u64 v[220:221], v[140:141], 0, s[96:97]
	s_add_i32 m0, s14, 0x2000
	s_add_i32 s14, s15, s6
	global_load_lds_dwordx4 v[220:221], off
	v_lshl_add_u64 v[220:221], v[140:141], 0, s[88:89]
	s_mov_b32 m0, s14
	v_lshl_add_u64 v[140:141], v[140:141], 0, s[68:69]
	global_load_lds_dwordx4 v[220:221], off
	s_add_i32 m0, s14, 0x2000
	s_nop 0
	global_load_lds_dwordx4 v[140:141], off
	v_lshl_add_u64 v[140:141], v[218:219], 0, s[56:57]
	s_mov_b32 m0, s26
	s_nop 0
	global_load_lds_dwordx4 v[140:141], off
	v_lshl_add_u64 v[140:141], v[218:219], 0, s[96:97]
	s_mov_b32 m0, s27
	s_nop 0
	global_load_lds_dwordx4 v[140:141], off
	s_waitcnt vmcnt(14)
	s_waitcnt lgkmcnt(0)
	s_barrier
	s_setprio 1
	s_waitcnt lgkmcnt(0)
	v_mfma_f32_16x16x32_bf16 v[60:63], v[136:139], v[176:179], v[60:63]
	v_mfma_f32_16x16x32_bf16 v[52:55], v[152:155], v[176:179], v[52:55]
	v_mfma_f32_16x16x32_bf16 v[44:47], v[136:139], v[194:197], v[44:47]
	v_mfma_f32_16x16x32_bf16 v[36:39], v[152:155], v[194:197], v[36:39]
	v_mfma_f32_16x16x32_bf16 v[28:31], v[136:139], v[202:205], v[28:31]
	v_mfma_f32_16x16x32_bf16 v[20:23], v[152:155], v[202:205], v[20:23]
	v_mfma_f32_16x16x32_bf16 v[12:15], v[136:139], v[210:213], v[12:15]
	v_mfma_f32_16x16x32_bf16 v[4:7], v[152:155], v[210:213], v[4:7]
	v_mfma_f32_16x16x32_bf16 v[60:63], v[148:151], v[180:183], v[60:63]
	v_mfma_f32_16x16x32_bf16 v[52:55], v[156:159], v[180:183], v[52:55]
	v_mfma_f32_16x16x32_bf16 v[44:47], v[148:151], v[198:201], v[44:47]
	v_mfma_f32_16x16x32_bf16 v[36:39], v[156:159], v[198:201], v[36:39]
	v_mfma_f32_16x16x32_bf16 v[28:31], v[148:151], v[206:209], v[28:31]
	v_mfma_f32_16x16x32_bf16 v[20:23], v[156:159], v[206:209], v[20:23]
	v_mfma_f32_16x16x32_bf16 v[12:15], v[148:151], v[214:217], v[12:15]
	v_mfma_f32_16x16x32_bf16 v[4:7], v[156:159], v[214:217], v[4:7]
	s_setprio 0
	s_setprio 1
	v_mfma_f32_16x16x32_bf16 v[56:59], v[160:163], v[176:179], v[56:59]
	v_mfma_f32_16x16x32_bf16 v[48:51], v[168:171], v[176:179], v[48:51]
	v_mfma_f32_16x16x32_bf16 v[40:43], v[160:163], v[194:197], v[40:43]
	v_mfma_f32_16x16x32_bf16 v[32:35], v[168:171], v[194:197], v[32:35]
	v_mfma_f32_16x16x32_bf16 v[24:27], v[160:163], v[202:205], v[24:27]
	v_mfma_f32_16x16x32_bf16 v[16:19], v[168:171], v[202:205], v[16:19]
	v_mfma_f32_16x16x32_bf16 v[8:11], v[160:163], v[210:213], v[8:11]
	v_mfma_f32_16x16x32_bf16 v[0:3], v[168:171], v[210:213], v[0:3]
	v_mfma_f32_16x16x32_bf16 v[56:59], v[164:167], v[180:183], v[56:59]
	v_mfma_f32_16x16x32_bf16 v[48:51], v[172:175], v[180:183], v[48:51]
	v_mfma_f32_16x16x32_bf16 v[40:43], v[164:167], v[198:201], v[40:43]
	v_mfma_f32_16x16x32_bf16 v[32:35], v[172:175], v[198:201], v[32:35]
	v_mfma_f32_16x16x32_bf16 v[24:27], v[164:167], v[206:209], v[24:27]
	v_mfma_f32_16x16x32_bf16 v[16:19], v[172:175], v[206:209], v[16:19]
	v_mfma_f32_16x16x32_bf16 v[8:11], v[164:167], v[214:217], v[8:11]
	v_mfma_f32_16x16x32_bf16 v[0:3], v[172:175], v[214:217], v[0:3]
	s_setprio 0
	s_barrier
	s_add_i32 s49, s49, 2
	s_add_u32 s46, s46, 0x100
	s_addc_u32 s47, s47, 0
	s_add_u32 s16, s16, 0x100
	s_addc_u32 s17, s17, 0
	s_cmp_gt_u32 s49, 13
	s_cbranch_scc0 .LBB0_481
	s_and_b64 vcc, exec, s[10:11]
	s_cbranch_vccz .LBB0_484
	s_barrier

.Lnostb8:
	s_add_u32 s14, s46, 0xfffe0080
	s_addc_u32 s15, s47, -1
	s_add_i32 s60, 0, 0x10000
	s_cmp_eq_u32 s51, 4
	s_cselect_b32 s15, s13, s15
	s_cselect_b32 s14, s31, s14
	s_cselect_b32 s17, s11, s50
	s_cselect_b32 s16, s48, s49
	s_add_i32 s61, 0, 0x14000
	v_add_u32_e32 v0, s60, v172
	v_add_u32_e32 v4, s61, v172
	ds_read_b128 v[24:27], v0
	ds_read_b128 v[28:31], v0 offset:1024
	ds_read_b128 v[16:19], v0 offset:2048
	ds_read_b128 v[20:23], v0 offset:3072
	ds_read_b128 v[8:11], v4
	ds_read_b128 v[12:15], v4 offset:1024
	ds_read_b128 v[0:3], v4 offset:2048
	ds_read_b128 v[4:7], v4 offset:3072
	v_lshl_add_u64 v[166:167], s[46:47], 0, v[164:165]
	s_add_i32 m0, s19, 0xc000
	ds_read_b128 v[194:197], v176
	ds_read_b128 v[198:201], v176 offset:1024
	ds_read_b128 v[202:205], v176 offset:2048
	ds_read_b128 v[206:209], v176 offset:3072
	ds_read_b128 v[210:213], v176 offset:4096
	ds_read_b128 v[214:217], v176 offset:5120
	ds_read_b128 v[218:221], v176 offset:6144
	ds_read_b128 v[222:225], v176 offset:7168
	global_load_lds_dwordx4 v[166:167], off
	v_lshl_add_u64 v[166:167], v[166:167], 0, s[94:95]
	s_add_i32 m0, s19, 0xe000
	s_nop 0
	global_load_lds_dwordx4 v[166:167], off
	s_waitcnt vmcnt(10)
	s_waitcnt lgkmcnt(0)
	s_barrier
	s_setprio 1
	s_waitcnt lgkmcnt(0)
	v_mfma_scale_f32_16x16x128_f8f6f4 v[156:159], v[24:31], v[194:201], 0, v240, v240 op_sel_hi:[0,0,0]
	v_mfma_scale_f32_16x16x128_f8f6f4 v[148:151], v[16:23], v[194:201], 0, v240, v240 op_sel_hi:[0,0,0]
	v_mfma_scale_f32_16x16x128_f8f6f4 v[140:143], v[24:31], v[202:209], 0, v240, v240 op_sel_hi:[0,0,0]
	v_mfma_scale_f32_16x16x128_f8f6f4 v[132:135], v[16:23], v[202:209], 0, v240, v240 op_sel_hi:[0,0,0]
	v_mfma_scale_f32_16x16x128_f8f6f4 v[124:127], v[24:31], v[210:217], 0, v240, v240 op_sel_hi:[0,0,0]
	v_mfma_scale_f32_16x16x128_f8f6f4 v[116:119], v[16:23], v[210:217], 0, v240, v240 op_sel_hi:[0,0,0]
	v_mfma_scale_f32_16x16x128_f8f6f4 v[108:111], v[24:31], v[218:225], 0, v240, v240 op_sel_hi:[0,0,0]
	v_mfma_scale_f32_16x16x128_f8f6f4 v[100:103], v[16:23], v[218:225], 0, v240, v240 op_sel_hi:[0,0,0]
	s_setprio 0
	s_setprio 1
	v_mfma_scale_f32_16x16x128_f8f6f4 v[152:155], v[8:15], v[194:201], 0, v240, v240 op_sel_hi:[0,0,0]
	v_mfma_scale_f32_16x16x128_f8f6f4 v[144:147], v[0:7], v[194:201], 0, v240, v240 op_sel_hi:[0,0,0]
	v_mfma_scale_f32_16x16x128_f8f6f4 v[136:139], v[8:15], v[202:209], 0, v240, v240 op_sel_hi:[0,0,0]
	v_mfma_scale_f32_16x16x128_f8f6f4 v[128:131], v[0:7], v[202:209], 0, v240, v240 op_sel_hi:[0,0,0]
	v_mfma_scale_f32_16x16x128_f8f6f4 v[120:123], v[8:15], v[210:217], 0, v240, v240 op_sel_hi:[0,0,0]
	v_mfma_scale_f32_16x16x128_f8f6f4 v[112:115], v[0:7], v[210:217], 0, v240, v240 op_sel_hi:[0,0,0]
	v_mfma_scale_f32_16x16x128_f8f6f4 v[104:107], v[8:15], v[218:225], 0, v240, v240 op_sel_hi:[0,0,0]
	v_mfma_scale_f32_16x16x128_f8f6f4 v[96:99], v[0:7], v[218:225], 0, v240, v240 op_sel_hi:[0,0,0]
	s_setprio 0
	s_barrier
	v_lshl_add_u64 v[166:167], s[16:17], 0, v[184:185]
	s_add_i32 s16, s60, s6
	s_mov_b32 m0, s16
	ds_read_b128 v[194:197], v176 offset:16384
	ds_read_b128 v[198:201], v176 offset:17408
	ds_read_b128 v[202:205], v176 offset:18432
	ds_read_b128 v[206:209], v176 offset:19456
	ds_read_b128 v[210:213], v176 offset:20480
	ds_read_b128 v[214:217], v176 offset:21504
	ds_read_b128 v[218:221], v176 offset:22528
	ds_read_b128 v[222:225], v176 offset:23552
	global_load_lds_dwordx4 v[166:167], off
	v_lshl_add_u64 v[168:169], v[166:167], 0, s[94:95]
	s_add_i32 m0, s16, 0x2000
	s_add_i32 s16, s61, s6
	global_load_lds_dwordx4 v[168:169], off
	v_lshl_add_u64 v[168:169], v[166:167], 0, s[34:35]
	s_mov_b32 m0, s16
	s_nop 0
	global_load_lds_dwordx4 v[168:169], off
	v_lshl_add_u64 v[168:169], v[166:167], 0, s[90:91]
	s_add_i32 m0, s16, 0x2000
	s_nop 0
	global_load_lds_dwordx4 v[168:169], off
	v_lshl_add_u64 v[168:169], s[14:15], 0, v[160:161]
	s_mov_b32 m0, s19
	v_lshl_add_u64 v[178:179], v[168:169], 0, s[94:95]
	global_load_lds_dwordx4 v[168:169], off
	s_mov_b32 m0, s20
	s_nop 0
	global_load_lds_dwordx4 v[178:179], off
	s_waitcnt vmcnt(14)
	s_waitcnt lgkmcnt(0)
	s_barrier
	s_setprio 1
	s_waitcnt lgkmcnt(0)
	v_mfma_scale_f32_16x16x128_f8f6f4 v[92:95], v[24:31], v[194:201], 0, v240, v240 op_sel_hi:[0,0,0]
	v_mfma_scale_f32_16x16x128_f8f6f4 v[84:87], v[16:23], v[194:201], 0, v240, v240 op_sel_hi:[0,0,0]
	v_mfma_scale_f32_16x16x128_f8f6f4 v[76:79], v[24:31], v[202:209], 0, v240, v240 op_sel_hi:[0,0,0]
	v_mfma_scale_f32_16x16x128_f8f6f4 v[68:71], v[16:23], v[202:209], 0, v240, v240 op_sel_hi:[0,0,0]
	v_mfma_scale_f32_16x16x128_f8f6f4 v[60:63], v[24:31], v[210:217], 0, v240, v240 op_sel_hi:[0,0,0]
	v_mfma_scale_f32_16x16x128_f8f6f4 v[52:55], v[16:23], v[210:217], 0, v240, v240 op_sel_hi:[0,0,0]
	v_mfma_scale_f32_16x16x128_f8f6f4 v[44:47], v[24:31], v[218:225], 0, v240, v240 op_sel_hi:[0,0,0]
	v_mfma_scale_f32_16x16x128_f8f6f4 v[36:39], v[16:23], v[218:225], 0, v240, v240 op_sel_hi:[0,0,0]
	s_setprio 0
	s_setprio 1
	v_mfma_scale_f32_16x16x128_f8f6f4 v[88:91], v[8:15], v[194:201], 0, v240, v240 op_sel_hi:[0,0,0]
	v_mfma_scale_f32_16x16x128_f8f6f4 v[80:83], v[0:7], v[194:201], 0, v240, v240 op_sel_hi:[0,0,0]
	v_mfma_scale_f32_16x16x128_f8f6f4 v[72:75], v[8:15], v[202:209], 0, v240, v240 op_sel_hi:[0,0,0]
	v_mfma_scale_f32_16x16x128_f8f6f4 v[64:67], v[0:7], v[202:209], 0, v240, v240 op_sel_hi:[0,0,0]
	v_mfma_scale_f32_16x16x128_f8f6f4 v[56:59], v[8:15], v[210:217], 0, v240, v240 op_sel_hi:[0,0,0]
	v_mfma_scale_f32_16x16x128_f8f6f4 v[48:51], v[0:7], v[210:217], 0, v240, v240 op_sel_hi:[0,0,0]
	v_mfma_scale_f32_16x16x128_f8f6f4 v[40:43], v[8:15], v[218:225], 0, v240, v240 op_sel_hi:[0,0,0]
	v_mfma_scale_f32_16x16x128_f8f6f4 v[32:35], v[0:7], v[218:225], 0, v240, v240 op_sel_hi:[0,0,0]
	s_setprio 0
	s_barrier
	s_add_i32 s14, 0, 0x18000
	s_add_i32 s15, 0, 0x1c000
	v_add_u32_e32 v12, s14, v172
	v_add_u32_e32 v28, s15, v172
	ds_read_b128 v[0:3], v12
	ds_read_b128 v[4:7], v12 offset:1024
	ds_read_b128 v[8:11], v12 offset:2048
	ds_read_b128 v[12:15], v12 offset:3072
	ds_read_b128 v[16:19], v28
	ds_read_b128 v[20:23], v28 offset:1024
	ds_read_b128 v[24:27], v28 offset:2048
	ds_read_b128 v[28:31], v28 offset:3072
	s_mov_b32 m0, s24
	v_lshl_add_u64 v[178:179], v[168:169], 0, s[34:35]
	ds_read_b128 v[194:197], v176 offset:32768
	ds_read_b128 v[198:201], v176 offset:33792
	ds_read_b128 v[202:205], v176 offset:34816
	ds_read_b128 v[206:209], v176 offset:35840
	ds_read_b128 v[210:213], v176 offset:36864
	ds_read_b128 v[214:217], v176 offset:37888
	ds_read_b128 v[218:221], v176 offset:38912
	ds_read_b128 v[222:225], v176 offset:39936
	global_load_lds_dwordx4 v[178:179], off
	v_lshl_add_u64 v[178:179], v[168:169], 0, s[90:91]
	s_mov_b32 m0, s25
	s_nop 0
	global_load_lds_dwordx4 v[178:179], off
	s_waitcnt vmcnt(10)
	s_waitcnt lgkmcnt(0)
	s_barrier
	s_setprio 1
	s_waitcnt lgkmcnt(0)
	v_mfma_scale_f32_16x16x128_f8f6f4 v[156:159], v[0:7], v[194:201], v[156:159], v240, v240 op_sel_hi:[0,0,0]
	v_mfma_scale_f32_16x16x128_f8f6f4 v[148:151], v[8:15], v[194:201], v[148:151], v240, v240 op_sel_hi:[0,0,0]
	v_mfma_scale_f32_16x16x128_f8f6f4 v[140:143], v[0:7], v[202:209], v[140:143], v240, v240 op_sel_hi:[0,0,0]
	v_mfma_scale_f32_16x16x128_f8f6f4 v[132:135], v[8:15], v[202:209], v[132:135], v240, v240 op_sel_hi:[0,0,0]
	v_mfma_scale_f32_16x16x128_f8f6f4 v[124:127], v[0:7], v[210:217], v[124:127], v240, v240 op_sel_hi:[0,0,0]
	v_mfma_scale_f32_16x16x128_f8f6f4 v[116:119], v[8:15], v[210:217], v[116:119], v240, v240 op_sel_hi:[0,0,0]
	v_mfma_scale_f32_16x16x128_f8f6f4 v[108:111], v[0:7], v[218:225], v[108:111], v240, v240 op_sel_hi:[0,0,0]
	v_mfma_scale_f32_16x16x128_f8f6f4 v[100:103], v[8:15], v[218:225], v[100:103], v240, v240 op_sel_hi:[0,0,0]
	s_setprio 0
	s_setprio 1
	v_mfma_scale_f32_16x16x128_f8f6f4 v[152:155], v[16:23], v[194:201], v[152:155], v240, v240 op_sel_hi:[0,0,0]
	v_mfma_scale_f32_16x16x128_f8f6f4 v[144:147], v[24:31], v[194:201], v[144:147], v240, v240 op_sel_hi:[0,0,0]
	v_mfma_scale_f32_16x16x128_f8f6f4 v[136:139], v[16:23], v[202:209], v[136:139], v240, v240 op_sel_hi:[0,0,0]
	v_mfma_scale_f32_16x16x128_f8f6f4 v[128:131], v[24:31], v[202:209], v[128:131], v240, v240 op_sel_hi:[0,0,0]
	v_mfma_scale_f32_16x16x128_f8f6f4 v[120:123], v[16:23], v[210:217], v[120:123], v240, v240 op_sel_hi:[0,0,0]
	v_mfma_scale_f32_16x16x128_f8f6f4 v[112:115], v[24:31], v[210:217], v[112:115], v240, v240 op_sel_hi:[0,0,0]
	v_mfma_scale_f32_16x16x128_f8f6f4 v[104:107], v[16:23], v[218:225], v[104:107], v240, v240 op_sel_hi:[0,0,0]
	v_mfma_scale_f32_16x16x128_f8f6f4 v[96:99], v[24:31], v[218:225], v[96:99], v240, v240 op_sel_hi:[0,0,0]
	s_setprio 0
	s_barrier
	s_add_i32 s14, s14, s6
	v_lshl_add_u64 v[178:179], v[166:167], 0, s[56:57]
	s_mov_b32 m0, s14
	ds_read_b128 v[194:197], v176 offset:49152
	ds_read_b128 v[198:201], v176 offset:50176
	ds_read_b128 v[202:205], v176 offset:51200
	ds_read_b128 v[206:209], v176 offset:52224
	ds_read_b128 v[210:213], v176 offset:53248
	ds_read_b128 v[214:217], v176 offset:54272
	ds_read_b128 v[218:221], v176 offset:55296
	ds_read_b128 v[222:225], v176 offset:56320
	global_load_lds_dwordx4 v[178:179], off
	v_lshl_add_u64 v[178:179], v[166:167], 0, s[58:59]
	s_add_i32 m0, s14, 0x2000
	s_add_i32 s14, s15, s6
	global_load_lds_dwordx4 v[178:179], off
	v_lshl_add_u64 v[178:179], v[166:167], 0, s[96:97]
	s_mov_b32 m0, s14
	v_lshl_add_u64 v[166:167], v[166:167], 0, s[4:5]
	global_load_lds_dwordx4 v[178:179], off
	s_add_i32 m0, s14, 0x2000
	s_nop 0
	global_load_lds_dwordx4 v[166:167], off
	v_lshl_add_u64 v[166:167], v[168:169], 0, s[56:57]
	s_mov_b32 m0, s26
	s_nop 0
	global_load_lds_dwordx4 v[166:167], off
	v_lshl_add_u64 v[166:167], v[168:169], 0, s[58:59]
	s_mov_b32 m0, s27
	s_nop 0
	global_load_lds_dwordx4 v[166:167], off
	s_waitcnt vmcnt(14)
	s_waitcnt lgkmcnt(0)
	s_barrier
	s_setprio 1
	s_waitcnt lgkmcnt(0)
	v_mfma_scale_f32_16x16x128_f8f6f4 v[92:95], v[0:7], v[194:201], v[92:95], v240, v240 op_sel_hi:[0,0,0]
	v_mfma_scale_f32_16x16x128_f8f6f4 v[84:87], v[8:15], v[194:201], v[84:87], v240, v240 op_sel_hi:[0,0,0]
	v_mfma_scale_f32_16x16x128_f8f6f4 v[76:79], v[0:7], v[202:209], v[76:79], v240, v240 op_sel_hi:[0,0,0]
	v_mfma_scale_f32_16x16x128_f8f6f4 v[68:71], v[8:15], v[202:209], v[68:71], v240, v240 op_sel_hi:[0,0,0]
	v_mfma_scale_f32_16x16x128_f8f6f4 v[60:63], v[0:7], v[210:217], v[60:63], v240, v240 op_sel_hi:[0,0,0]
	v_mfma_scale_f32_16x16x128_f8f6f4 v[52:55], v[8:15], v[210:217], v[52:55], v240, v240 op_sel_hi:[0,0,0]
	v_mfma_scale_f32_16x16x128_f8f6f4 v[44:47], v[0:7], v[218:225], v[44:47], v240, v240 op_sel_hi:[0,0,0]
	v_mfma_scale_f32_16x16x128_f8f6f4 v[36:39], v[8:15], v[218:225], v[36:39], v240, v240 op_sel_hi:[0,0,0]
	s_setprio 0
	s_setprio 1
	v_mfma_scale_f32_16x16x128_f8f6f4 v[88:91], v[16:23], v[194:201], v[88:91], v240, v240 op_sel_hi:[0,0,0]
	v_mfma_scale_f32_16x16x128_f8f6f4 v[80:83], v[24:31], v[194:201], v[80:83], v240, v240 op_sel_hi:[0,0,0]
	v_mfma_scale_f32_16x16x128_f8f6f4 v[72:75], v[16:23], v[202:209], v[72:75], v240, v240 op_sel_hi:[0,0,0]
	v_mfma_scale_f32_16x16x128_f8f6f4 v[64:67], v[24:31], v[202:209], v[64:67], v240, v240 op_sel_hi:[0,0,0]
	v_mfma_scale_f32_16x16x128_f8f6f4 v[56:59], v[16:23], v[210:217], v[56:59], v240, v240 op_sel_hi:[0,0,0]
	v_mfma_scale_f32_16x16x128_f8f6f4 v[48:51], v[24:31], v[210:217], v[48:51], v240, v240 op_sel_hi:[0,0,0]
	v_mfma_scale_f32_16x16x128_f8f6f4 v[40:43], v[16:23], v[218:225], v[40:43], v240, v240 op_sel_hi:[0,0,0]
	v_mfma_scale_f32_16x16x128_f8f6f4 v[32:35], v[24:31], v[218:225], v[32:35], v240, v240 op_sel_hi:[0,0,0]
	s_setprio 0
	s_barrier
	s_add_i32 s51, s51, 2
	s_add_u32 s46, s46, 0x100
	s_addc_u32 s47, s47, 0
	s_add_u32 s49, s49, 0x100
	s_addc_u32 s50, s50, 0
	s_cmp_gt_u32 s51, 5
.LBB0_503:
	s_add_u32 s14, s46, 0xfffe0080
	s_addc_u32 s15, s47, -1
	s_add_i32 s60, 0, 0x10000
	s_cmp_eq_u32 s51, 4
	s_cselect_b32 s15, s13, s15
	s_cselect_b32 s14, s31, s14
	s_cselect_b32 s17, s11, s50
	s_cselect_b32 s16, s48, s49
	s_add_i32 s61, 0, 0x14000
	v_add_u32_e32 v0, s60, v172
	v_add_u32_e32 v4, s61, v172
	ds_read_b128 v[24:27], v0
	ds_read_b128 v[28:31], v0 offset:1024
	ds_read_b128 v[16:19], v0 offset:2048
	ds_read_b128 v[20:23], v0 offset:3072
	ds_read_b128 v[8:11], v4
	ds_read_b128 v[12:15], v4 offset:1024
	ds_read_b128 v[0:3], v4 offset:2048
	ds_read_b128 v[4:7], v4 offset:3072
	v_lshl_add_u64 v[166:167], s[46:47], 0, v[164:165]
	s_add_i32 m0, s19, 0xc000
	ds_read_b128 v[194:197], v176
	ds_read_b128 v[198:201], v176 offset:1024
	ds_read_b128 v[202:205], v176 offset:2048
	ds_read_b128 v[206:209], v176 offset:3072
	ds_read_b128 v[210:213], v176 offset:4096
	ds_read_b128 v[214:217], v176 offset:5120
	ds_read_b128 v[218:221], v176 offset:6144
	ds_read_b128 v[222:225], v176 offset:7168
	global_load_lds_dwordx4 v[166:167], off
	v_lshl_add_u64 v[166:167], v[166:167], 0, s[94:95]
	s_add_i32 m0, s19, 0xe000
	s_nop 0
	global_load_lds_dwordx4 v[166:167], off
	s_waitcnt vmcnt(10)
	s_waitcnt lgkmcnt(0)
	s_barrier
	s_setprio 1
	s_waitcnt lgkmcnt(0)
	v_mfma_scale_f32_16x16x128_f8f6f4 v[156:159], v[24:31], v[194:201], v[156:159], v240, v240 op_sel_hi:[0,0,0]
	v_mfma_scale_f32_16x16x128_f8f6f4 v[148:151], v[16:23], v[194:201], v[148:151], v240, v240 op_sel_hi:[0,0,0]
	v_mfma_scale_f32_16x16x128_f8f6f4 v[140:143], v[24:31], v[202:209], v[140:143], v240, v240 op_sel_hi:[0,0,0]
	v_mfma_scale_f32_16x16x128_f8f6f4 v[132:135], v[16:23], v[202:209], v[132:135], v240, v240 op_sel_hi:[0,0,0]
	v_mfma_scale_f32_16x16x128_f8f6f4 v[124:127], v[24:31], v[210:217], v[124:127], v240, v240 op_sel_hi:[0,0,0]
	v_mfma_scale_f32_16x16x128_f8f6f4 v[116:119], v[16:23], v[210:217], v[116:119], v240, v240 op_sel_hi:[0,0,0]
	v_mfma_scale_f32_16x16x128_f8f6f4 v[108:111], v[24:31], v[218:225], v[108:111], v240, v240 op_sel_hi:[0,0,0]
	v_mfma_scale_f32_16x16x128_f8f6f4 v[100:103], v[16:23], v[218:225], v[100:103], v240, v240 op_sel_hi:[0,0,0]
	s_setprio 0
	s_setprio 1
	v_mfma_scale_f32_16x16x128_f8f6f4 v[152:155], v[8:15], v[194:201], v[152:155], v240, v240 op_sel_hi:[0,0,0]
	v_mfma_scale_f32_16x16x128_f8f6f4 v[144:147], v[0:7], v[194:201], v[144:147], v240, v240 op_sel_hi:[0,0,0]
	v_mfma_scale_f32_16x16x128_f8f6f4 v[136:139], v[8:15], v[202:209], v[136:139], v240, v240 op_sel_hi:[0,0,0]
	v_mfma_scale_f32_16x16x128_f8f6f4 v[128:131], v[0:7], v[202:209], v[128:131], v240, v240 op_sel_hi:[0,0,0]
	v_mfma_scale_f32_16x16x128_f8f6f4 v[120:123], v[8:15], v[210:217], v[120:123], v240, v240 op_sel_hi:[0,0,0]
	v_mfma_scale_f32_16x16x128_f8f6f4 v[112:115], v[0:7], v[210:217], v[112:115], v240, v240 op_sel_hi:[0,0,0]
	v_mfma_scale_f32_16x16x128_f8f6f4 v[104:107], v[8:15], v[218:225], v[104:107], v240, v240 op_sel_hi:[0,0,0]
	v_mfma_scale_f32_16x16x128_f8f6f4 v[96:99], v[0:7], v[218:225], v[96:99], v240, v240 op_sel_hi:[0,0,0]
	s_setprio 0
	s_barrier
	v_lshl_add_u64 v[166:167], s[16:17], 0, v[184:185]
	s_add_i32 s16, s60, s6
	s_mov_b32 m0, s16
	ds_read_b128 v[194:197], v176 offset:16384
	ds_read_b128 v[198:201], v176 offset:17408
	ds_read_b128 v[202:205], v176 offset:18432
	ds_read_b128 v[206:209], v176 offset:19456
	ds_read_b128 v[210:213], v176 offset:20480
	ds_read_b128 v[214:217], v176 offset:21504
	ds_read_b128 v[218:221], v176 offset:22528
	ds_read_b128 v[222:225], v176 offset:23552
	global_load_lds_dwordx4 v[166:167], off
	v_lshl_add_u64 v[168:169], v[166:167], 0, s[94:95]
	s_add_i32 m0, s16, 0x2000
	s_add_i32 s16, s61, s6
	global_load_lds_dwordx4 v[168:169], off
	v_lshl_add_u64 v[168:169], v[166:167], 0, s[34:35]
	s_mov_b32 m0, s16
	s_nop 0
	global_load_lds_dwordx4 v[168:169], off
	v_lshl_add_u64 v[168:169], v[166:167], 0, s[90:91]
	s_add_i32 m0, s16, 0x2000
	s_nop 0
	global_load_lds_dwordx4 v[168:169], off
	v_lshl_add_u64 v[168:169], s[14:15], 0, v[160:161]
	s_mov_b32 m0, s19
	v_lshl_add_u64 v[178:179], v[168:169], 0, s[94:95]
	global_load_lds_dwordx4 v[168:169], off
	s_mov_b32 m0, s20
	s_nop 0
	global_load_lds_dwordx4 v[178:179], off
	s_waitcnt vmcnt(14)
	s_waitcnt lgkmcnt(0)
	s_barrier
	s_setprio 1
	s_waitcnt lgkmcnt(0)
	v_mfma_scale_f32_16x16x128_f8f6f4 v[92:95], v[24:31], v[194:201], v[92:95], v240, v240 op_sel_hi:[0,0,0]
	v_mfma_scale_f32_16x16x128_f8f6f4 v[84:87], v[16:23], v[194:201], v[84:87], v240, v240 op_sel_hi:[0,0,0]
	v_mfma_scale_f32_16x16x128_f8f6f4 v[76:79], v[24:31], v[202:209], v[76:79], v240, v240 op_sel_hi:[0,0,0]
	v_mfma_scale_f32_16x16x128_f8f6f4 v[68:71], v[16:23], v[202:209], v[68:71], v240, v240 op_sel_hi:[0,0,0]
	v_mfma_scale_f32_16x16x128_f8f6f4 v[60:63], v[24:31], v[210:217], v[60:63], v240, v240 op_sel_hi:[0,0,0]
	v_mfma_scale_f32_16x16x128_f8f6f4 v[52:55], v[16:23], v[210:217], v[52:55], v240, v240 op_sel_hi:[0,0,0]
	v_mfma_scale_f32_16x16x128_f8f6f4 v[44:47], v[24:31], v[218:225], v[44:47], v240, v240 op_sel_hi:[0,0,0]
	v_mfma_scale_f32_16x16x128_f8f6f4 v[36:39], v[16:23], v[218:225], v[36:39], v240, v240 op_sel_hi:[0,0,0]
	s_setprio 0
	s_setprio 1
	v_mfma_scale_f32_16x16x128_f8f6f4 v[88:91], v[8:15], v[194:201], v[88:91], v240, v240 op_sel_hi:[0,0,0]
	v_mfma_scale_f32_16x16x128_f8f6f4 v[80:83], v[0:7], v[194:201], v[80:83], v240, v240 op_sel_hi:[0,0,0]
	v_mfma_scale_f32_16x16x128_f8f6f4 v[72:75], v[8:15], v[202:209], v[72:75], v240, v240 op_sel_hi:[0,0,0]
	v_mfma_scale_f32_16x16x128_f8f6f4 v[64:67], v[0:7], v[202:209], v[64:67], v240, v240 op_sel_hi:[0,0,0]
	v_mfma_scale_f32_16x16x128_f8f6f4 v[56:59], v[8:15], v[210:217], v[56:59], v240, v240 op_sel_hi:[0,0,0]
	v_mfma_scale_f32_16x16x128_f8f6f4 v[48:51], v[0:7], v[210:217], v[48:51], v240, v240 op_sel_hi:[0,0,0]
	v_mfma_scale_f32_16x16x128_f8f6f4 v[40:43], v[8:15], v[218:225], v[40:43], v240, v240 op_sel_hi:[0,0,0]
	v_mfma_scale_f32_16x16x128_f8f6f4 v[32:35], v[0:7], v[218:225], v[32:35], v240, v240 op_sel_hi:[0,0,0]
	s_setprio 0
	s_barrier
	s_add_i32 s14, 0, 0x18000
	s_add_i32 s15, 0, 0x1c000
	v_add_u32_e32 v12, s14, v172
	v_add_u32_e32 v28, s15, v172
	ds_read_b128 v[0:3], v12
	ds_read_b128 v[4:7], v12 offset:1024
	ds_read_b128 v[8:11], v12 offset:2048
	ds_read_b128 v[12:15], v12 offset:3072
	ds_read_b128 v[16:19], v28
	ds_read_b128 v[20:23], v28 offset:1024
	ds_read_b128 v[24:27], v28 offset:2048
	ds_read_b128 v[28:31], v28 offset:3072
	s_mov_b32 m0, s24
	v_lshl_add_u64 v[178:179], v[168:169], 0, s[34:35]
	ds_read_b128 v[194:197], v176 offset:32768
	ds_read_b128 v[198:201], v176 offset:33792
	ds_read_b128 v[202:205], v176 offset:34816
	ds_read_b128 v[206:209], v176 offset:35840
	ds_read_b128 v[210:213], v176 offset:36864
	ds_read_b128 v[214:217], v176 offset:37888
	ds_read_b128 v[218:221], v176 offset:38912
	ds_read_b128 v[222:225], v176 offset:39936
	global_load_lds_dwordx4 v[178:179], off
	v_lshl_add_u64 v[178:179], v[168:169], 0, s[90:91]
	s_mov_b32 m0, s25
	s_nop 0
	global_load_lds_dwordx4 v[178:179], off
	s_waitcnt vmcnt(10)
	s_waitcnt lgkmcnt(0)
	s_barrier
	s_setprio 1
	s_waitcnt lgkmcnt(0)
	v_mfma_scale_f32_16x16x128_f8f6f4 v[156:159], v[0:7], v[194:201], v[156:159], v240, v240 op_sel_hi:[0,0,0]
	v_mfma_scale_f32_16x16x128_f8f6f4 v[148:151], v[8:15], v[194:201], v[148:151], v240, v240 op_sel_hi:[0,0,0]
	v_mfma_scale_f32_16x16x128_f8f6f4 v[140:143], v[0:7], v[202:209], v[140:143], v240, v240 op_sel_hi:[0,0,0]
	v_mfma_scale_f32_16x16x128_f8f6f4 v[132:135], v[8:15], v[202:209], v[132:135], v240, v240 op_sel_hi:[0,0,0]
	v_mfma_scale_f32_16x16x128_f8f6f4 v[124:127], v[0:7], v[210:217], v[124:127], v240, v240 op_sel_hi:[0,0,0]
	v_mfma_scale_f32_16x16x128_f8f6f4 v[116:119], v[8:15], v[210:217], v[116:119], v240, v240 op_sel_hi:[0,0,0]
	v_mfma_scale_f32_16x16x128_f8f6f4 v[108:111], v[0:7], v[218:225], v[108:111], v240, v240 op_sel_hi:[0,0,0]
	v_mfma_scale_f32_16x16x128_f8f6f4 v[100:103], v[8:15], v[218:225], v[100:103], v240, v240 op_sel_hi:[0,0,0]
	s_setprio 0
	s_setprio 1
	v_mfma_scale_f32_16x16x128_f8f6f4 v[152:155], v[16:23], v[194:201], v[152:155], v240, v240 op_sel_hi:[0,0,0]
	v_mfma_scale_f32_16x16x128_f8f6f4 v[144:147], v[24:31], v[194:201], v[144:147], v240, v240 op_sel_hi:[0,0,0]
	v_mfma_scale_f32_16x16x128_f8f6f4 v[136:139], v[16:23], v[202:209], v[136:139], v240, v240 op_sel_hi:[0,0,0]
	v_mfma_scale_f32_16x16x128_f8f6f4 v[128:131], v[24:31], v[202:209], v[128:131], v240, v240 op_sel_hi:[0,0,0]
	v_mfma_scale_f32_16x16x128_f8f6f4 v[120:123], v[16:23], v[210:217], v[120:123], v240, v240 op_sel_hi:[0,0,0]
	v_mfma_scale_f32_16x16x128_f8f6f4 v[112:115], v[24:31], v[210:217], v[112:115], v240, v240 op_sel_hi:[0,0,0]
	v_mfma_scale_f32_16x16x128_f8f6f4 v[104:107], v[16:23], v[218:225], v[104:107], v240, v240 op_sel_hi:[0,0,0]
	v_mfma_scale_f32_16x16x128_f8f6f4 v[96:99], v[24:31], v[218:225], v[96:99], v240, v240 op_sel_hi:[0,0,0]
	s_setprio 0
	s_barrier
	s_add_i32 s14, s14, s6
	v_lshl_add_u64 v[178:179], v[166:167], 0, s[56:57]
	s_mov_b32 m0, s14
	ds_read_b128 v[194:197], v176 offset:49152
	ds_read_b128 v[198:201], v176 offset:50176
	ds_read_b128 v[202:205], v176 offset:51200
	ds_read_b128 v[206:209], v176 offset:52224
	ds_read_b128 v[210:213], v176 offset:53248
	ds_read_b128 v[214:217], v176 offset:54272
	ds_read_b128 v[218:221], v176 offset:55296
	ds_read_b128 v[222:225], v176 offset:56320
	global_load_lds_dwordx4 v[178:179], off
	v_lshl_add_u64 v[178:179], v[166:167], 0, s[58:59]
	s_add_i32 m0, s14, 0x2000
	s_add_i32 s14, s15, s6
	global_load_lds_dwordx4 v[178:179], off
	v_lshl_add_u64 v[178:179], v[166:167], 0, s[96:97]
	s_mov_b32 m0, s14
	v_lshl_add_u64 v[166:167], v[166:167], 0, s[4:5]
	global_load_lds_dwordx4 v[178:179], off
	s_add_i32 m0, s14, 0x2000
	s_nop 0
	global_load_lds_dwordx4 v[166:167], off
	v_lshl_add_u64 v[166:167], v[168:169], 0, s[56:57]
	s_mov_b32 m0, s26
	s_nop 0
	global_load_lds_dwordx4 v[166:167], off
	v_lshl_add_u64 v[166:167], v[168:169], 0, s[58:59]
	s_mov_b32 m0, s27
	s_nop 0
	global_load_lds_dwordx4 v[166:167], off
	s_waitcnt vmcnt(14)
	s_waitcnt lgkmcnt(0)
	s_barrier
	s_setprio 1
	s_waitcnt lgkmcnt(0)
	v_mfma_scale_f32_16x16x128_f8f6f4 v[92:95], v[0:7], v[194:201], v[92:95], v240, v240 op_sel_hi:[0,0,0]
	v_mfma_scale_f32_16x16x128_f8f6f4 v[84:87], v[8:15], v[194:201], v[84:87], v240, v240 op_sel_hi:[0,0,0]
	v_mfma_scale_f32_16x16x128_f8f6f4 v[76:79], v[0:7], v[202:209], v[76:79], v240, v240 op_sel_hi:[0,0,0]
	v_mfma_scale_f32_16x16x128_f8f6f4 v[68:71], v[8:15], v[202:209], v[68:71], v240, v240 op_sel_hi:[0,0,0]
	v_mfma_scale_f32_16x16x128_f8f6f4 v[60:63], v[0:7], v[210:217], v[60:63], v240, v240 op_sel_hi:[0,0,0]
	v_mfma_scale_f32_16x16x128_f8f6f4 v[52:55], v[8:15], v[210:217], v[52:55], v240, v240 op_sel_hi:[0,0,0]
	v_mfma_scale_f32_16x16x128_f8f6f4 v[44:47], v[0:7], v[218:225], v[44:47], v240, v240 op_sel_hi:[0,0,0]
	v_mfma_scale_f32_16x16x128_f8f6f4 v[36:39], v[8:15], v[218:225], v[36:39], v240, v240 op_sel_hi:[0,0,0]
	s_setprio 0
	s_setprio 1
	v_mfma_scale_f32_16x16x128_f8f6f4 v[88:91], v[16:23], v[194:201], v[88:91], v240, v240 op_sel_hi:[0,0,0]
	v_mfma_scale_f32_16x16x128_f8f6f4 v[80:83], v[24:31], v[194:201], v[80:83], v240, v240 op_sel_hi:[0,0,0]
	v_mfma_scale_f32_16x16x128_f8f6f4 v[72:75], v[16:23], v[202:209], v[72:75], v240, v240 op_sel_hi:[0,0,0]
	v_mfma_scale_f32_16x16x128_f8f6f4 v[64:67], v[24:31], v[202:209], v[64:67], v240, v240 op_sel_hi:[0,0,0]
	v_mfma_scale_f32_16x16x128_f8f6f4 v[56:59], v[16:23], v[210:217], v[56:59], v240, v240 op_sel_hi:[0,0,0]
	v_mfma_scale_f32_16x16x128_f8f6f4 v[48:51], v[24:31], v[210:217], v[48:51], v240, v240 op_sel_hi:[0,0,0]
	v_mfma_scale_f32_16x16x128_f8f6f4 v[40:43], v[16:23], v[218:225], v[40:43], v240, v240 op_sel_hi:[0,0,0]
	v_mfma_scale_f32_16x16x128_f8f6f4 v[32:35], v[24:31], v[218:225], v[32:35], v240, v240 op_sel_hi:[0,0,0]
	s_setprio 0
	s_barrier
	s_add_i32 s51, s51, 2
	s_add_u32 s46, s46, 0x100
	s_addc_u32 s47, s47, 0
	s_add_u32 s49, s49, 0x100
	s_addc_u32 s50, s50, 0
	s_cmp_gt_u32 s51, 5
	s_cbranch_scc0 .LBB0_503
	s_and_b64 vcc, exec, s[8:9]
	s_cbranch_vccz .LBB0_506
	s_barrier
